# speedup vs baseline: 1.0017x; 1.0014x over previous
; #define PG8_STAGE(bufoff, gbase, voff) do { _Pragma("unroll") for (int _i = 0; _i < 2; ++_i) \
;         __builtin_amdgcn_global_load_lds((const unsigned*)((const char*)(gbase) + (voff)[_i]), (LAS unsigned*)(lds + (bufoff) + ldsw + _i * 8192), 16, 0, 0); } while (0)
; #define PG8_LDA(dst, b, h) do { _Pragma("unroll") for (int m = 0; m < 4; ++m) _Pragma("unroll") for (int k = 0; k < 2; ++k) dst[m][k] = *(const LAS bf16x8*)(lds + PG8_SA(b, h) + aoff + m * 2048 + k * 1024); } while (0)
; #define PG8_LDB(dst, b, h) do { _Pragma("unroll") for (int n = 0; n < 2; ++n) _Pragma("unroll") for (int k = 0; k < 2; ++k) dst[n][k] = *(const LAS bf16x8*)(lds + PG8_SB(b, h) + boff + n * 2048 + k * 1024); } while (0)
; #define PG8_MMA(ai, bj, At, Bt) do { __builtin_amdgcn_s_setprio(1); _Pragma("unroll") for (int m = 0; m < 4; ++m) _Pragma("unroll") for (int n = 0; n < 2; ++n) _Pragma("unroll") for (int k = 0; k < 2; ++k) \
;         acc[ai][bj][m][n] = __builtin_amdgcn_mfma_f32_16x16x32_bf16(Bt[n][k], At[m][k], acc[ai][bj][m][n], 0, 0, 0); __builtin_amdgcn_s_setprio(0); } while (0)
; #define PG8_WAIT_L(n) asm volatile("s_waitcnt lgkmcnt(" #n ")" ::: "memory")
; #define PG8_BAR __builtin_amdgcn_s_barrier()
; #define PG8_SCHED __builtin_amdgcn_sched_barrier(0)
;     ...
;             const char* a1 = cA + (size_t)(t + 1) * kstep;
;             const char* a2 = last ? nA : cA + (size_t)(t + 2) * kstep; const char* b2 = last ? nB : cB + (size_t)(t + 2) * kstep;
;             const char* a3 = a2 + kstep; const char* b3 = b2 + kstep;
;             PG8_LDB(B0, 0, 0); PG8_SCHED; PG8_LDA(At, 0, 0); PG8_STAGE(PG8_SA(1, 1), a1 + hstep, voffA);
;             PG8_WAIT_L(8); PG8_BAR; PG8_WAIT_L(0); PG8_MMA(0, 0, At, B0); PG8_BAR; PG8_SCHED;
;             PG8_LDB(B1, 0, 1); PG8_STAGE(PG8_SB(0, 0), b2, voffB);
;             PG8_BAR; PG8_WAIT_L(0); PG8_MMA(0, 1, At, B1); PG8_BAR;
;             PG8_LDA(At, 0, 1); PG8_STAGE(PG8_SA(0, 0), a2, voffA);
;             PG8_BAR; PG8_WAIT_L(0); PG8_MMA(1, 0, At, B0); PG8_BAR; PG8_SCHED;
.LBB0_120:
	s_add_i32 s44, s2, 2
	s_add_u32 s10, s8, 0x100
	s_addc_u32 s11, s9, 0
	s_add_i32 s35, 0, 0x10000
	v_add_u32_e32 v156, s35, v145
	ds_read_b128 v[140:143], v156
	ds_read_b128 v[148:151], v156 offset:1024
	ds_read_b128 v[152:155], v156 offset:2048
	ds_read_b128 v[156:159], v156 offset:3072
	s_cmp_eq_u32 s41, s2
	s_cselect_b32 s2, s6, s10
	s_cselect_b32 s3, s7, s11
	s_cselect_b32 s13, s19, s43
	s_cselect_b32 s12, s18, s42
	v_lshl_add_u64 v[192:193], s[8:9], 0, v[136:137]
	s_add_i32 m0, s21, 0xc000
	ds_read_b128 v[160:163], v147
	ds_read_b128 v[164:167], v147 offset:1024
	ds_read_b128 v[168:171], v147 offset:2048
	ds_read_b128 v[172:175], v147 offset:3072
	ds_read_b128 v[176:179], v147 offset:4096
	ds_read_b128 v[180:183], v147 offset:5120
	ds_read_b128 v[184:187], v147 offset:6144
	ds_read_b128 v[188:191], v147 offset:7168
	global_load_lds_dwordx4 v[192:193], off
	v_lshl_add_u64 v[192:193], s[8:9], 0, v[138:139]
	s_add_i32 m0, s21, 0xe000
	s_nop 0
	global_load_lds_dwordx4 v[192:193], off
	s_waitcnt lgkmcnt(0)
	s_barrier
	v_mfma_f32_16x16x32_bf16 v[126:129], v[140:143], v[160:163], v[126:129]
	v_mfma_f32_16x16x32_bf16 v[122:125], v[152:155], v[160:163], v[122:125]
	v_mfma_f32_16x16x32_bf16 v[110:113], v[140:143], v[168:171], v[110:113]
	v_mfma_f32_16x16x32_bf16 v[106:109], v[152:155], v[168:171], v[106:109]
	v_mfma_f32_16x16x32_bf16 v[94:97], v[140:143], v[176:179], v[94:97]
	v_mfma_f32_16x16x32_bf16 v[90:93], v[152:155], v[176:179], v[90:93]
	v_mfma_f32_16x16x32_bf16 v[78:81], v[140:143], v[184:187], v[78:81]
	v_mfma_f32_16x16x32_bf16 v[74:77], v[152:155], v[184:187], v[74:77]
	v_mfma_f32_16x16x32_bf16 v[126:129], v[148:151], v[164:167], v[126:129]
	v_mfma_f32_16x16x32_bf16 v[122:125], v[156:159], v[164:167], v[122:125]
	v_mfma_f32_16x16x32_bf16 v[110:113], v[148:151], v[172:175], v[110:113]
	v_mfma_f32_16x16x32_bf16 v[106:109], v[156:159], v[172:175], v[106:109]
	v_mfma_f32_16x16x32_bf16 v[94:97], v[148:151], v[180:183], v[94:97]
	v_mfma_f32_16x16x32_bf16 v[90:93], v[156:159], v[180:183], v[90:93]
	v_mfma_f32_16x16x32_bf16 v[78:81], v[148:151], v[188:191], v[78:81]
	v_mfma_f32_16x16x32_bf16 v[74:77], v[156:159], v[188:191], v[74:77]
	s_barrier
	s_add_i32 s45, 0, 0x14000
	v_add_u32_e32 v208, s45, v145
	s_add_i32 s8, s35, s20
	ds_read_b128 v[192:195], v208
	ds_read_b128 v[196:199], v208 offset:1024
	ds_read_b128 v[220:223], v208 offset:2048
	ds_read_b128 v[224:227], v208 offset:3072
	v_lshl_add_u64 v[208:209], s[12:13], 0, v[64:65]
	s_mov_b32 m0, s8
	v_lshl_add_u64 v[210:211], s[12:13], 0, v[134:135]
	global_load_lds_dwordx4 v[208:209], off
	s_add_i32 m0, s8, 0x2000
	s_nop 0
	global_load_lds_dwordx4 v[210:211], off
	s_waitcnt lgkmcnt(0)
	s_barrier
	v_mfma_f32_16x16x32_bf16 v[118:121], v[192:195], v[160:163], v[118:121]
	v_mfma_f32_16x16x32_bf16 v[114:117], v[220:223], v[160:163], v[114:117]
	v_mfma_f32_16x16x32_bf16 v[102:105], v[192:195], v[168:171], v[102:105]
	v_mfma_f32_16x16x32_bf16 v[98:101], v[220:223], v[168:171], v[98:101]
	v_mfma_f32_16x16x32_bf16 v[86:89], v[192:195], v[176:179], v[86:89]
	v_mfma_f32_16x16x32_bf16 v[82:85], v[220:223], v[176:179], v[82:85]
	v_mfma_f32_16x16x32_bf16 v[70:73], v[192:195], v[184:187], v[70:73]
	v_mfma_f32_16x16x32_bf16 v[66:69], v[220:223], v[184:187], v[66:69]
	v_mfma_f32_16x16x32_bf16 v[118:121], v[196:199], v[164:167], v[118:121]
	v_mfma_f32_16x16x32_bf16 v[114:117], v[224:227], v[164:167], v[114:117]
	v_mfma_f32_16x16x32_bf16 v[102:105], v[196:199], v[172:175], v[102:105]
	v_mfma_f32_16x16x32_bf16 v[98:101], v[224:227], v[172:175], v[98:101]
	v_mfma_f32_16x16x32_bf16 v[86:89], v[196:199], v[180:183], v[86:89]
	v_mfma_f32_16x16x32_bf16 v[82:85], v[224:227], v[180:183], v[82:85]
	v_mfma_f32_16x16x32_bf16 v[70:73], v[196:199], v[188:191], v[70:73]
	v_mfma_f32_16x16x32_bf16 v[66:69], v[224:227], v[188:191], v[66:69]
	s_mov_b32 m0, s21
	v_lshl_add_u64 v[212:213], s[2:3], 0, v[130:131]
	s_barrier
	ds_read_b128 v[160:163], v147 offset:16384
	ds_read_b128 v[164:167], v147 offset:17408
	ds_read_b128 v[168:171], v147 offset:18432
	ds_read_b128 v[172:175], v147 offset:19456
	ds_read_b128 v[176:179], v147 offset:20480
	ds_read_b128 v[180:183], v147 offset:21504
	ds_read_b128 v[184:187], v147 offset:22528
	ds_read_b128 v[188:191], v147 offset:23552
	global_load_lds_dwordx4 v[212:213], off
	v_lshl_add_u64 v[214:215], s[2:3], 0, v[132:133]
	s_mov_b32 m0, s22
	s_nop 0
	global_load_lds_dwordx4 v[214:215], off
	s_waitcnt lgkmcnt(0)
	s_barrier
	v_mfma_f32_16x16x32_bf16 v[60:63], v[140:143], v[160:163], v[60:63]
	v_mfma_f32_16x16x32_bf16 v[56:59], v[152:155], v[160:163], v[56:59]
	v_mfma_f32_16x16x32_bf16 v[44:47], v[140:143], v[168:171], v[44:47]
	v_mfma_f32_16x16x32_bf16 v[40:43], v[152:155], v[168:171], v[40:43]
	v_mfma_f32_16x16x32_bf16 v[28:31], v[140:143], v[176:179], v[28:31]
	v_mfma_f32_16x16x32_bf16 v[24:27], v[152:155], v[176:179], v[24:27]
	v_mfma_f32_16x16x32_bf16 v[12:15], v[140:143], v[184:187], v[12:15]
	v_mfma_f32_16x16x32_bf16 v[8:11], v[152:155], v[184:187], v[8:11]
	v_mfma_f32_16x16x32_bf16 v[60:63], v[148:151], v[164:167], v[60:63]
	v_mfma_f32_16x16x32_bf16 v[56:59], v[156:159], v[164:167], v[56:59]
	v_mfma_f32_16x16x32_bf16 v[44:47], v[148:151], v[172:175], v[44:47]
	v_mfma_f32_16x16x32_bf16 v[40:43], v[156:159], v[172:175], v[40:43]
	v_mfma_f32_16x16x32_bf16 v[28:31], v[148:151], v[180:183], v[28:31]
	v_mfma_f32_16x16x32_bf16 v[24:27], v[156:159], v[180:183], v[24:27]
	v_mfma_f32_16x16x32_bf16 v[12:15], v[148:151], v[188:191], v[12:15]
	v_mfma_f32_16x16x32_bf16 v[8:11], v[156:159], v[188:191], v[8:11]
	s_barrier
; #define PG8_STAGE(bufoff, gbase, voff) do { _Pragma("unroll") for (int _i = 0; _i < 2; ++_i) \
;         __builtin_amdgcn_global_load_lds((const unsigned*)((const char*)(gbase) + (voff)[_i]), (LAS unsigned*)(lds + (bufoff) + ldsw + _i * 8192), 16, 0, 0); } while (0)
; #define PG8_LDA(dst, b, h) do { _Pragma("unroll") for (int m = 0; m < 4; ++m) _Pragma("unroll") for (int k = 0; k < 2; ++k) dst[m][k] = *(const LAS bf16x8*)(lds + PG8_SA(b, h) + aoff + m * 2048 + k * 1024); } while (0)
; #define PG8_LDB(dst, b, h) do { _Pragma("unroll") for (int n = 0; n < 2; ++n) _Pragma("unroll") for (int k = 0; k < 2; ++k) dst[n][k] = *(const LAS bf16x8*)(lds + PG8_SB(b, h) + boff + n * 2048 + k * 1024); } while (0)
; #define PG8_MMA(ai, bj, At, Bt) do { __builtin_amdgcn_s_setprio(1); _Pragma("unroll") for (int m = 0; m < 4; ++m) _Pragma("unroll") for (int n = 0; n < 2; ++n) _Pragma("unroll") for (int k = 0; k < 2; ++k) \
;         acc[ai][bj][m][n] = __builtin_amdgcn_mfma_f32_16x16x32_bf16(Bt[n][k], At[m][k], acc[ai][bj][m][n], 0, 0, 0); __builtin_amdgcn_s_setprio(0); } while (0)
; #define PG8_WAIT_V(n) asm volatile("s_waitcnt vmcnt(" #n ")" ::: "memory")
; #define PG8_WAIT_L(n) asm volatile("s_waitcnt lgkmcnt(" #n ")" ::: "memory")
; #define PG8_BAR __builtin_amdgcn_s_barrier()
; #define PG8_SCHED __builtin_amdgcn_sched_barrier(0)
;     ...
;             PG8_STAGE(PG8_SB(0, 1), b2 + hstep, voffB);
;             PG8_WAIT_V(6); PG8_BAR; PG8_MMA(1, 1, At, B1); PG8_BAR;
;             PG8_LDB(B0, 1, 0); PG8_SCHED; PG8_LDA(At, 1, 0); PG8_STAGE(PG8_SA(0, 1), a2 + hstep, voffA);
;             PG8_WAIT_L(8); PG8_BAR; PG8_WAIT_L(0); PG8_MMA(0, 0, At, B0); PG8_BAR; PG8_SCHED;
;             PG8_LDB(B1, 1, 1); PG8_STAGE(PG8_SB(1, 0), b3, voffB);
;             PG8_BAR; PG8_WAIT_L(0); PG8_MMA(0, 1, At, B1); PG8_BAR;
;             PG8_LDA(At, 1, 1); PG8_STAGE(PG8_SA(1, 0), a3, voffA);
;             PG8_BAR; PG8_WAIT_L(0); PG8_MMA(1, 0, At, B0); PG8_BAR; PG8_SCHED;
	s_add_u32 s8, s12, 0x84000
	s_addc_u32 s9, s13, 0
	s_add_i32 s35, s45, s20
	v_lshl_add_u64 v[140:141], s[8:9], 0, v[64:65]
	s_mov_b32 m0, s35
	s_nop 0
	global_load_lds_dwordx4 v[140:141], off
	v_lshl_add_u64 v[140:141], s[8:9], 0, v[134:135]
	s_add_i32 m0, s35, 0x2000
	s_nop 0
	global_load_lds_dwordx4 v[140:141], off
	s_waitcnt vmcnt(6)
	s_barrier
	v_mfma_f32_16x16x32_bf16 v[52:55], v[192:195], v[160:163], v[52:55]
	v_mfma_f32_16x16x32_bf16 v[48:51], v[220:223], v[160:163], v[48:51]
	v_mfma_f32_16x16x32_bf16 v[36:39], v[192:195], v[168:171], v[36:39]
	v_mfma_f32_16x16x32_bf16 v[32:35], v[220:223], v[168:171], v[32:35]
	v_mfma_f32_16x16x32_bf16 v[20:23], v[192:195], v[176:179], v[20:23]
	v_mfma_f32_16x16x32_bf16 v[16:19], v[220:223], v[176:179], v[16:19]
	v_mfma_f32_16x16x32_bf16 v[4:7], v[192:195], v[184:187], v[4:7]
	v_mfma_f32_16x16x32_bf16 v[0:3], v[220:223], v[184:187], v[0:3]
	v_mfma_f32_16x16x32_bf16 v[52:55], v[196:199], v[164:167], v[52:55]
	v_mfma_f32_16x16x32_bf16 v[48:51], v[224:227], v[164:167], v[48:51]
	v_mfma_f32_16x16x32_bf16 v[36:39], v[196:199], v[172:175], v[36:39]
	v_mfma_f32_16x16x32_bf16 v[32:35], v[224:227], v[172:175], v[32:35]
	v_mfma_f32_16x16x32_bf16 v[20:23], v[196:199], v[180:183], v[20:23]
	v_mfma_f32_16x16x32_bf16 v[16:19], v[224:227], v[180:183], v[16:19]
	v_mfma_f32_16x16x32_bf16 v[4:7], v[196:199], v[188:191], v[4:7]
	v_mfma_f32_16x16x32_bf16 v[0:3], v[224:227], v[188:191], v[0:3]
	s_add_i32 s8, 0, 0x18000
	v_add_u32_e32 v156, s8, v145
	s_barrier
	ds_read_b128 v[140:143], v156
	ds_read_b128 v[148:151], v156 offset:1024
	ds_read_b128 v[152:155], v156 offset:2048
	ds_read_b128 v[156:159], v156 offset:3072
	s_add_u32 s2, s2, 0x84000
	s_addc_u32 s3, s3, 0
	s_mov_b32 m0, s23
	v_lshl_add_u64 v[192:193], s[2:3], 0, v[130:131]
	ds_read_b128 v[160:163], v147 offset:32768
	ds_read_b128 v[164:167], v147 offset:33792
	ds_read_b128 v[168:171], v147 offset:34816
	ds_read_b128 v[172:175], v147 offset:35840
	ds_read_b128 v[176:179], v147 offset:36864
	ds_read_b128 v[180:183], v147 offset:37888
	ds_read_b128 v[184:187], v147 offset:38912
	ds_read_b128 v[188:191], v147 offset:39936
	global_load_lds_dwordx4 v[192:193], off
	v_lshl_add_u64 v[192:193], s[2:3], 0, v[132:133]
	s_mov_b32 m0, s24
	s_nop 0
	global_load_lds_dwordx4 v[192:193], off
	s_waitcnt lgkmcnt(0)
	s_barrier
	v_mfma_f32_16x16x32_bf16 v[126:129], v[140:143], v[160:163], v[126:129]
	v_mfma_f32_16x16x32_bf16 v[122:125], v[152:155], v[160:163], v[122:125]
	v_mfma_f32_16x16x32_bf16 v[110:113], v[140:143], v[168:171], v[110:113]
	v_mfma_f32_16x16x32_bf16 v[106:109], v[152:155], v[168:171], v[106:109]
	v_mfma_f32_16x16x32_bf16 v[94:97], v[140:143], v[176:179], v[94:97]
	v_mfma_f32_16x16x32_bf16 v[90:93], v[152:155], v[176:179], v[90:93]
	v_mfma_f32_16x16x32_bf16 v[78:81], v[140:143], v[184:187], v[78:81]
	v_mfma_f32_16x16x32_bf16 v[74:77], v[152:155], v[184:187], v[74:77]
	v_mfma_f32_16x16x32_bf16 v[126:129], v[148:151], v[164:167], v[126:129]
	v_mfma_f32_16x16x32_bf16 v[122:125], v[156:159], v[164:167], v[122:125]
	v_mfma_f32_16x16x32_bf16 v[110:113], v[148:151], v[172:175], v[110:113]
	v_mfma_f32_16x16x32_bf16 v[106:109], v[156:159], v[172:175], v[106:109]
	v_mfma_f32_16x16x32_bf16 v[94:97], v[148:151], v[180:183], v[94:97]
	v_mfma_f32_16x16x32_bf16 v[90:93], v[156:159], v[180:183], v[90:93]
	v_mfma_f32_16x16x32_bf16 v[78:81], v[148:151], v[188:191], v[78:81]
	v_mfma_f32_16x16x32_bf16 v[74:77], v[156:159], v[188:191], v[74:77]
	s_barrier
	s_add_i32 s9, 0, 0x1c000
	s_add_i32 s2, s8, s20
	v_add_u32_e32 v219, s9, v145
	v_lshl_add_u64 v[208:209], v[208:209], 0, s[16:17]
	s_mov_b32 m0, s2
	ds_read_b128 v[192:195], v219
	ds_read_b128 v[196:199], v219 offset:1024
	ds_read_b128 v[220:223], v219 offset:2048
	ds_read_b128 v[224:227], v219 offset:3072
	global_load_lds_dwordx4 v[208:209], off
	v_lshl_add_u64 v[208:209], v[210:211], 0, s[16:17]
	s_add_i32 m0, s2, 0x2000
	s_nop 0
	global_load_lds_dwordx4 v[208:209], off
	s_waitcnt lgkmcnt(0)
	s_barrier
	v_mfma_f32_16x16x32_bf16 v[118:121], v[192:195], v[160:163], v[118:121]
	v_mfma_f32_16x16x32_bf16 v[114:117], v[220:223], v[160:163], v[114:117]
	v_mfma_f32_16x16x32_bf16 v[102:105], v[192:195], v[168:171], v[102:105]
	v_mfma_f32_16x16x32_bf16 v[98:101], v[220:223], v[168:171], v[98:101]
	v_mfma_f32_16x16x32_bf16 v[86:89], v[192:195], v[176:179], v[86:89]
	v_mfma_f32_16x16x32_bf16 v[82:85], v[220:223], v[176:179], v[82:85]
	v_mfma_f32_16x16x32_bf16 v[70:73], v[192:195], v[184:187], v[70:73]
	v_mfma_f32_16x16x32_bf16 v[66:69], v[220:223], v[184:187], v[66:69]
	v_mfma_f32_16x16x32_bf16 v[118:121], v[196:199], v[164:167], v[118:121]
	v_mfma_f32_16x16x32_bf16 v[114:117], v[224:227], v[164:167], v[114:117]
	v_mfma_f32_16x16x32_bf16 v[102:105], v[196:199], v[172:175], v[102:105]
	v_mfma_f32_16x16x32_bf16 v[98:101], v[224:227], v[172:175], v[98:101]
	v_mfma_f32_16x16x32_bf16 v[86:89], v[196:199], v[180:183], v[86:89]
	v_mfma_f32_16x16x32_bf16 v[82:85], v[224:227], v[180:183], v[82:85]
	v_mfma_f32_16x16x32_bf16 v[70:73], v[196:199], v[188:191], v[70:73]
	v_mfma_f32_16x16x32_bf16 v[66:69], v[224:227], v[188:191], v[66:69]
	s_mov_b32 m0, s25
	v_lshl_add_u64 v[208:209], v[212:213], 0, s[16:17]
	s_barrier
	ds_read_b128 v[160:163], v147 offset:49152
	ds_read_b128 v[164:167], v147 offset:50176
	ds_read_b128 v[168:171], v147 offset:51200
	ds_read_b128 v[172:175], v147 offset:52224
	ds_read_b128 v[176:179], v147 offset:53248
	ds_read_b128 v[180:183], v147 offset:54272
	ds_read_b128 v[184:187], v147 offset:55296
	ds_read_b128 v[188:191], v147 offset:56320
	global_load_lds_dwordx4 v[208:209], off
	v_lshl_add_u64 v[208:209], v[214:215], 0, s[16:17]
	s_mov_b32 m0, s26
	s_nop 0
	global_load_lds_dwordx4 v[208:209], off
	s_waitcnt lgkmcnt(0)
	s_barrier
; __device__ __forceinline__ unsigned cvt_pk_bf16(float lo, float hi) { unsigned r; asm volatile("v_cvt_pk_bf16_f32 %0, %1, %2" : "=v"(r) : "v"(lo), "v"(hi)); return r; }
; #define PG8_STAGE(bufoff, gbase, voff) do { _Pragma("unroll") for (int _i = 0; _i < 2; ++_i) \
;         __builtin_amdgcn_global_load_lds((const unsigned*)((const char*)(gbase) + (voff)[_i]), (LAS unsigned*)(lds + (bufoff) + ldsw + _i * 8192), 16, 0, 0); } while (0)
; #define PG8_MMA(ai, bj, At, Bt) do { __builtin_amdgcn_s_setprio(1); _Pragma("unroll") for (int m = 0; m < 4; ++m) _Pragma("unroll") for (int n = 0; n < 2; ++n) _Pragma("unroll") for (int k = 0; k < 2; ++k) \
;         acc[ai][bj][m][n] = __builtin_amdgcn_mfma_f32_16x16x32_bf16(Bt[n][k], At[m][k], acc[ai][bj][m][n], 0, 0, 0); __builtin_amdgcn_s_setprio(0); } while (0)
; #define PG8_WAIT_V(n) asm volatile("s_waitcnt vmcnt(" #n ")" ::: "memory")
; #define PG8_WAIT_L(n) asm volatile("s_waitcnt lgkmcnt(" #n ")" ::: "memory")
; #define PG8_BAR __builtin_amdgcn_s_barrier()
; #define PG8_SCHED __builtin_amdgcn_sched_barrier(0)
;     __device__ __forceinline__ void operator()(const f32x4 (&acc)[2][2][4][2], const Unit& u, int wr, int wc, int fr, int fq) const {
;     ...
;             for (int m = 0; m < 4; ++m) { bf16_t* rowp = O + (size_t)(row0 + ai * HALF + m * 16) * LDF + col0;
; #pragma unroll
;                 for (int bj = 0; bj < 2; ++bj) { f32x4 v0 = acc[ai][bj][m][0], v1 = acc[ai][bj][m][1];
; #pragma unroll
;                     for (int j = 0; j < 4; ++j) { const float a = fmaxf(v0[j], 0.f), b = fmaxf(v1[j], 0.f); v0[j] = a * a; v1[j] = b * b; }
;                     u32x4 w; w.x = cvt_pk_bf16(v0[0], v0[1]); w.y = cvt_pk_bf16(v0[2], v0[3]); w.z = cvt_pk_bf16(v1[0], v1[1]); w.w = cvt_pk_bf16(v1[2], v1[3]);
;                     *(u32x4*)(rowp + bj * HALF) = w; } }
;     ...
;             PG8_BAR; PG8_WAIT_L(0); PG8_MMA(1, 0, At, B0); PG8_BAR; PG8_SCHED;
;             PG8_STAGE(PG8_SB(1, 1), b3 + hstep, voffB);
;             PG8_WAIT_V(6); PG8_BAR; PG8_MMA(1, 1, At, B1); PG8_BAR;
;         }
	v_mfma_f32_16x16x32_bf16 v[60:63], v[140:143], v[160:163], v[60:63]
	v_mfma_f32_16x16x32_bf16 v[56:59], v[152:155], v[160:163], v[56:59]
	v_mfma_f32_16x16x32_bf16 v[44:47], v[140:143], v[168:171], v[44:47]
	v_mfma_f32_16x16x32_bf16 v[40:43], v[152:155], v[168:171], v[40:43]
	v_mfma_f32_16x16x32_bf16 v[28:31], v[140:143], v[176:179], v[28:31]
	v_mfma_f32_16x16x32_bf16 v[24:27], v[152:155], v[176:179], v[24:27]
	v_mfma_f32_16x16x32_bf16 v[12:15], v[140:143], v[184:187], v[12:15]
	v_mfma_f32_16x16x32_bf16 v[8:11], v[152:155], v[184:187], v[8:11]
	v_mfma_f32_16x16x32_bf16 v[60:63], v[148:151], v[164:167], v[60:63]
	v_mfma_f32_16x16x32_bf16 v[56:59], v[156:159], v[164:167], v[56:59]
	v_mfma_f32_16x16x32_bf16 v[44:47], v[148:151], v[172:175], v[44:47]
	v_mfma_f32_16x16x32_bf16 v[40:43], v[156:159], v[172:175], v[40:43]
	v_mfma_f32_16x16x32_bf16 v[28:31], v[148:151], v[180:183], v[28:31]
	v_mfma_f32_16x16x32_bf16 v[24:27], v[156:159], v[180:183], v[24:27]
	v_mfma_f32_16x16x32_bf16 v[12:15], v[148:151], v[188:191], v[12:15]
	v_mfma_f32_16x16x32_bf16 v[8:11], v[156:159], v[188:191], v[8:11]
	s_barrier
	s_add_u32 s2, s12, 0x84080
	s_addc_u32 s3, s13, 0
	s_add_i32 s8, s9, s20
	v_lshl_add_u64 v[140:141], s[2:3], 0, v[64:65]
	s_mov_b32 m0, s8
	s_nop 0
	global_load_lds_dwordx4 v[140:141], off
	v_lshl_add_u64 v[140:141], s[2:3], 0, v[134:135]
	s_add_i32 m0, s8, 0x2000
	s_nop 0
	global_load_lds_dwordx4 v[140:141], off
	s_waitcnt vmcnt(6)
	s_barrier
	v_mfma_f32_16x16x32_bf16 v[52:55], v[192:195], v[160:163], v[52:55]
	v_mfma_f32_16x16x32_bf16 v[48:51], v[220:223], v[160:163], v[48:51]
	v_mfma_f32_16x16x32_bf16 v[36:39], v[192:195], v[168:171], v[36:39]
	v_mfma_f32_16x16x32_bf16 v[32:35], v[220:223], v[168:171], v[32:35]
	v_mfma_f32_16x16x32_bf16 v[20:23], v[192:195], v[176:179], v[20:23]
	v_mfma_f32_16x16x32_bf16 v[16:19], v[220:223], v[176:179], v[16:19]
	v_mfma_f32_16x16x32_bf16 v[4:7], v[192:195], v[184:187], v[4:7]
	v_mfma_f32_16x16x32_bf16 v[0:3], v[220:223], v[184:187], v[0:3]
	v_mfma_f32_16x16x32_bf16 v[52:55], v[196:199], v[164:167], v[52:55]
	v_mfma_f32_16x16x32_bf16 v[48:51], v[224:227], v[164:167], v[48:51]
	v_mfma_f32_16x16x32_bf16 v[36:39], v[196:199], v[172:175], v[36:39]
	v_mfma_f32_16x16x32_bf16 v[32:35], v[224:227], v[172:175], v[32:35]
	v_mfma_f32_16x16x32_bf16 v[20:23], v[196:199], v[180:183], v[20:23]
	v_mfma_f32_16x16x32_bf16 v[16:19], v[224:227], v[180:183], v[16:19]
	v_mfma_f32_16x16x32_bf16 v[4:7], v[196:199], v[188:191], v[4:7]
	v_mfma_f32_16x16x32_bf16 v[0:3], v[224:227], v[188:191], v[0:3]
	s_add_u32 s42, s42, 0x100
	s_addc_u32 s43, s43, 0
	s_cmp_ge_u32 s44, s40
	s_mov_b64 s[8:9], s[10:11]
	s_mov_b32 s2, s44
	s_barrier
	s_cbranch_scc0 .LBB0_120
	v_max_f32_e32 v122, 0, v122
	v_lshl_or_b32 v142, s37, 8, v146
	v_mul_f32_e32 v151, v122, v122
	v_max_f32_e32 v122, v127, v127
	v_max_f32_e32 v123, 0, v123
	v_max_f32_e32 v124, 0, v124
	v_lshl_add_u32 v150, s38, 8, v144
	v_ashrrev_i32_e32 v143, 31, v142
	v_mov_b64_e32 v[140:141], s[80:81]
	s_movk_i32 s8, 0x4080
	v_max_f32_e32 v122, 0, v122
	v_mul_f32_e32 v127, v123, v123
	v_max_f32_e32 v123, v128, v128
	v_mul_f32_e32 v128, v124, v124
	v_max_f32_e32 v124, v129, v129
	v_mad_i64_i32 v[148:149], s[2:3], v150, s8, v[140:141]
	v_lshlrev_b64 v[142:143], 1, v[142:143]
	v_max_f32_e32 v126, 0, v126
	v_mul_f32_e32 v122, v122, v122
	v_max_f32_e32 v123, 0, v123
	v_max_f32_e32 v124, 0, v124
	v_max_f32_e32 v125, 0, v125
	v_lshl_add_u64 v[148:149], v[148:149], 0, v[142:143]
	v_mul_f32_e32 v126, v126, v126
	v_mul_f32_e32 v123, v123, v123
	v_mul_f32_e32 v124, v124, v124
	v_mul_f32_e32 v125, v125, v125
	v_cvt_pk_bf16_f32 v122, v126, v122
	v_max_f32_e32 v114, 0, v114
	v_max_f32_e32 v115, 0, v115
	v_max_f32_e32 v116, 0, v116
	v_cvt_pk_bf16_f32 v123, v123, v124
	v_cvt_pk_bf16_f32 v124, v151, v127
	v_cvt_pk_bf16_f32 v125, v128, v125
	global_store_dwordx4 v[148:149], v[122:125], off
	s_nop 1
	v_mul_f32_e32 v122, v114, v114
	v_max_f32_e32 v114, v119, v119
	v_mul_f32_e32 v119, v115, v115
	v_max_f32_e32 v115, v120, v120
	v_mul_f32_e32 v120, v116, v116
	v_max_f32_e32 v116, v121, v121
	v_max_f32_e32 v114, 0, v114
	v_max_f32_e32 v115, 0, v115
	v_max_f32_e32 v116, 0, v116
	v_max_f32_e32 v118, 0, v118
	v_mul_f32_e32 v114, v114, v114
	v_mul_f32_e32 v115, v115, v115
	v_max_f32_e32 v117, 0, v117
	v_mul_f32_e32 v116, v116, v116
	v_mul_f32_e32 v118, v118, v118
	v_mul_f32_e32 v117, v117, v117
	v_cvt_pk_bf16_f32 v114, v118, v114
	v_cvt_pk_bf16_f32 v115, v115, v116
	v_cvt_pk_bf16_f32 v116, v122, v119
	v_max_f32_e32 v106, 0, v106
	v_cvt_pk_bf16_f32 v117, v120, v117
	global_store_dwordx4 v[148:149], v[114:117], off offset:256
	s_nop 1
	v_max_f32_e32 v107, 0, v107
	v_max_f32_e32 v108, 0, v108
	v_mul_f32_e32 v116, v106, v106
	v_max_f32_e32 v106, v111, v111
	v_or_b32_e32 v114, 16, v150
	v_max_f32_e32 v106, 0, v106
	v_mul_f32_e32 v111, v107, v107
	v_max_f32_e32 v107, v112, v112
	v_mul_f32_e32 v112, v108, v108
	v_max_f32_e32 v108, v113, v113
	v_mad_i64_i32 v[114:115], s[2:3], v114, s8, v[140:141]
	v_max_f32_e32 v110, 0, v110
	v_mul_f32_e32 v106, v106, v106
	v_max_f32_e32 v107, 0, v107
	v_max_f32_e32 v108, 0, v108
	v_max_f32_e32 v109, 0, v109
	v_lshl_add_u64 v[114:115], v[114:115], 0, v[142:143]
	v_mul_f32_e32 v110, v110, v110
	v_mul_f32_e32 v107, v107, v107
	v_mul_f32_e32 v108, v108, v108
	v_mul_f32_e32 v109, v109, v109
	v_cvt_pk_bf16_f32 v106, v110, v106
	v_max_f32_e32 v98, 0, v98
	v_max_f32_e32 v99, 0, v99
	v_max_f32_e32 v100, 0, v100
	v_cvt_pk_bf16_f32 v107, v107, v108
	v_cvt_pk_bf16_f32 v108, v116, v111
	v_cvt_pk_bf16_f32 v109, v112, v109
	global_store_dwordx4 v[114:115], v[106:109], off
	s_nop 1
	v_mul_f32_e32 v106, v98, v98
; __device__ __forceinline__ unsigned cvt_pk_bf16(float lo, float hi) { unsigned r; asm volatile("v_cvt_pk_bf16_f32 %0, %1, %2" : "=v"(r) : "v"(lo), "v"(hi)); return r; }
;     __device__ __forceinline__ void operator()(const f32x4 (&acc)[2][2][4][2], const Unit& u, int wr, int wc, int fr, int fq) const {
;     ...
;             for (int m = 0; m < 4; ++m) { bf16_t* rowp = O + (size_t)(row0 + ai * HALF + m * 16) * LDF + col0;
; #pragma unroll
;                 for (int bj = 0; bj < 2; ++bj) { f32x4 v0 = acc[ai][bj][m][0], v1 = acc[ai][bj][m][1];
; #pragma unroll
;                     for (int j = 0; j < 4; ++j) { const float a = fmaxf(v0[j], 0.f), b = fmaxf(v1[j], 0.f); v0[j] = a * a; v1[j] = b * b; }
;                     u32x4 w; w.x = cvt_pk_bf16(v0[0], v0[1]); w.y = cvt_pk_bf16(v0[2], v0[3]); w.z = cvt_pk_bf16(v1[0], v1[1]); w.w = cvt_pk_bf16(v1[2], v1[3]);
;                     *(u32x4*)(rowp + bj * HALF) = w; } }
	v_max_f32_e32 v98, v103, v103
	v_mul_f32_e32 v103, v99, v99
	v_max_f32_e32 v99, v104, v104
	v_mul_f32_e32 v104, v100, v100
	v_max_f32_e32 v100, v105, v105
	v_max_f32_e32 v98, 0, v98
	v_max_f32_e32 v99, 0, v99
	v_max_f32_e32 v100, 0, v100
	v_max_f32_e32 v102, 0, v102
	v_mul_f32_e32 v98, v98, v98
	v_mul_f32_e32 v99, v99, v99
	v_max_f32_e32 v101, 0, v101
	v_mul_f32_e32 v100, v100, v100
	v_mul_f32_e32 v102, v102, v102
	v_mul_f32_e32 v101, v101, v101
	v_cvt_pk_bf16_f32 v98, v102, v98
	v_cvt_pk_bf16_f32 v99, v99, v100
	v_cvt_pk_bf16_f32 v100, v106, v103
	v_max_f32_e32 v90, 0, v90
	v_cvt_pk_bf16_f32 v101, v104, v101
	global_store_dwordx4 v[114:115], v[98:101], off offset:256
	s_nop 1
	v_max_f32_e32 v91, 0, v91
	v_max_f32_e32 v92, 0, v92
	v_mul_f32_e32 v100, v90, v90
	v_max_f32_e32 v90, v95, v95
	v_or_b32_e32 v98, 32, v150
	v_max_f32_e32 v90, 0, v90
	v_mul_f32_e32 v95, v91, v91
	v_max_f32_e32 v91, v96, v96
	v_mul_f32_e32 v96, v92, v92
	v_max_f32_e32 v92, v97, v97
	v_mad_i64_i32 v[98:99], s[2:3], v98, s8, v[140:141]
	v_max_f32_e32 v94, 0, v94
	v_mul_f32_e32 v90, v90, v90
	v_max_f32_e32 v91, 0, v91
	v_max_f32_e32 v92, 0, v92
	v_max_f32_e32 v93, 0, v93
	v_lshl_add_u64 v[98:99], v[98:99], 0, v[142:143]
	v_mul_f32_e32 v94, v94, v94
	v_mul_f32_e32 v91, v91, v91
	v_mul_f32_e32 v92, v92, v92
	v_mul_f32_e32 v93, v93, v93
	v_cvt_pk_bf16_f32 v90, v94, v90
	v_max_f32_e32 v82, 0, v82
	v_max_f32_e32 v83, 0, v83
	v_max_f32_e32 v84, 0, v84
	v_cvt_pk_bf16_f32 v91, v91, v92
	v_cvt_pk_bf16_f32 v92, v100, v95
	v_cvt_pk_bf16_f32 v93, v96, v93
	global_store_dwordx4 v[98:99], v[90:93], off
	s_nop 1
	v_mul_f32_e32 v90, v82, v82
	v_max_f32_e32 v82, v87, v87
	v_mul_f32_e32 v87, v83, v83
	v_max_f32_e32 v83, v88, v88
	v_mul_f32_e32 v88, v84, v84
	v_max_f32_e32 v84, v89, v89
	v_max_f32_e32 v82, 0, v82
	v_max_f32_e32 v83, 0, v83
	v_max_f32_e32 v84, 0, v84
	v_max_f32_e32 v86, 0, v86
	v_mul_f32_e32 v82, v82, v82
	v_mul_f32_e32 v83, v83, v83
	v_max_f32_e32 v85, 0, v85
	v_mul_f32_e32 v84, v84, v84
	v_mul_f32_e32 v86, v86, v86
	v_mul_f32_e32 v85, v85, v85
	v_cvt_pk_bf16_f32 v82, v86, v82
	v_cvt_pk_bf16_f32 v83, v83, v84
	v_cvt_pk_bf16_f32 v84, v90, v87
	v_max_f32_e32 v74, 0, v74
	v_cvt_pk_bf16_f32 v85, v88, v85
	global_store_dwordx4 v[98:99], v[82:85], off offset:256
	s_nop 1
	v_max_f32_e32 v75, 0, v75
	v_max_f32_e32 v76, 0, v76
	v_mul_f32_e32 v84, v74, v74
	v_max_f32_e32 v74, v79, v79
	v_or_b32_e32 v82, 48, v150
	v_max_f32_e32 v74, 0, v74
	v_mul_f32_e32 v79, v75, v75
	v_max_f32_e32 v75, v80, v80
	v_mul_f32_e32 v80, v76, v76
	v_max_f32_e32 v76, v81, v81
	v_mad_i64_i32 v[82:83], s[2:3], v82, s8, v[140:141]
	v_max_f32_e32 v78, 0, v78
	v_mul_f32_e32 v74, v74, v74
	v_max_f32_e32 v75, 0, v75
	v_max_f32_e32 v76, 0, v76
	v_max_f32_e32 v77, 0, v77
	v_lshl_add_u64 v[82:83], v[82:83], 0, v[142:143]
	v_mul_f32_e32 v78, v78, v78
	v_mul_f32_e32 v75, v75, v75
	v_mul_f32_e32 v76, v76, v76
	v_mul_f32_e32 v77, v77, v77
	v_cvt_pk_bf16_f32 v74, v78, v74
	v_max_f32_e32 v66, 0, v66
	v_max_f32_e32 v67, 0, v67
	v_max_f32_e32 v68, 0, v68
	v_cvt_pk_bf16_f32 v75, v75, v76
	v_cvt_pk_bf16_f32 v76, v84, v79
	v_cvt_pk_bf16_f32 v77, v80, v77
	global_store_dwordx4 v[82:83], v[74:77], off
	s_nop 1
	v_mul_f32_e32 v74, v66, v66
	v_max_f32_e32 v66, v71, v71
	v_mul_f32_e32 v71, v67, v67
	v_max_f32_e32 v67, v72, v72
	v_mul_f32_e32 v72, v68, v68
	v_max_f32_e32 v68, v73, v73
	v_max_f32_e32 v66, 0, v66
	v_max_f32_e32 v67, 0, v67
	v_max_f32_e32 v68, 0, v68
	v_max_f32_e32 v70, 0, v70
	v_mul_f32_e32 v66, v66, v66
	v_mul_f32_e32 v67, v67, v67
	v_max_f32_e32 v69, 0, v69
	v_mul_f32_e32 v68, v68, v68
	v_mul_f32_e32 v70, v70, v70
	v_mul_f32_e32 v69, v69, v69
	v_cvt_pk_bf16_f32 v66, v70, v66
	v_cvt_pk_bf16_f32 v67, v67, v68
	v_cvt_pk_bf16_f32 v68, v74, v71
	v_max_f32_e32 v56, 0, v56
	v_cvt_pk_bf16_f32 v69, v72, v69
	global_store_dwordx4 v[82:83], v[66:69], off offset:256
	s_nop 1
	v_max_f32_e32 v57, 0, v57
	v_max_f32_e32 v58, 0, v58
	v_mul_f32_e32 v68, v56, v56
	v_max_f32_e32 v56, v61, v61
	v_add_u32_e32 v66, 0x80, v150
	v_max_f32_e32 v56, 0, v56
	v_mul_f32_e32 v61, v57, v57
	v_max_f32_e32 v57, v62, v62
	v_mul_f32_e32 v62, v58, v58
	v_max_f32_e32 v58, v63, v63
	v_mad_i64_i32 v[66:67], s[2:3], v66, s8, v[140:141]
	v_max_f32_e32 v60, 0, v60
	v_mul_f32_e32 v56, v56, v56
	v_max_f32_e32 v57, 0, v57
	v_max_f32_e32 v58, 0, v58
	v_max_f32_e32 v59, 0, v59
	v_lshl_add_u64 v[66:67], v[66:67], 0, v[142:143]
	v_mul_f32_e32 v60, v60, v60
	v_mul_f32_e32 v57, v57, v57
	v_mul_f32_e32 v58, v58, v58
	v_mul_f32_e32 v59, v59, v59
	v_cvt_pk_bf16_f32 v56, v60, v56
	v_max_f32_e32 v48, 0, v48
	v_max_f32_e32 v49, 0, v49
	v_max_f32_e32 v50, 0, v50
	v_cvt_pk_bf16_f32 v57, v57, v58
	v_cvt_pk_bf16_f32 v58, v68, v61
	v_cvt_pk_bf16_f32 v59, v62, v59
	global_store_dwordx4 v[66:67], v[56:59], off
	s_nop 1
	v_mul_f32_e32 v56, v48, v48
	v_max_f32_e32 v48, v53, v53
	v_mul_f32_e32 v53, v49, v49
	v_max_f32_e32 v49, v54, v54
	v_mul_f32_e32 v54, v50, v50
	v_max_f32_e32 v50, v55, v55
	v_max_f32_e32 v48, 0, v48
	v_max_f32_e32 v49, 0, v49
	v_max_f32_e32 v50, 0, v50
	v_max_f32_e32 v52, 0, v52
	v_mul_f32_e32 v48, v48, v48
	v_mul_f32_e32 v49, v49, v49
	v_max_f32_e32 v51, 0, v51
	v_mul_f32_e32 v50, v50, v50
	v_mul_f32_e32 v52, v52, v52
	v_mul_f32_e32 v51, v51, v51
	v_cvt_pk_bf16_f32 v48, v52, v48
; __device__ __forceinline__ unsigned cvt_pk_bf16(float lo, float hi) { unsigned r; asm volatile("v_cvt_pk_bf16_f32 %0, %1, %2" : "=v"(r) : "v"(lo), "v"(hi)); return r; }
; #define PG8_WAIT_V(n) asm volatile("s_waitcnt vmcnt(" #n ")" ::: "memory")
; #define PG8_BAR __builtin_amdgcn_s_barrier()
;     __device__ __forceinline__ void operator()(const f32x4 (&acc)[2][2][4][2], const Unit& u, int wr, int wc, int fr, int fq) const {
;     ...
;             for (int m = 0; m < 4; ++m) { bf16_t* rowp = O + (size_t)(row0 + ai * HALF + m * 16) * LDF + col0;
; #pragma unroll
;                 for (int bj = 0; bj < 2; ++bj) { f32x4 v0 = acc[ai][bj][m][0], v1 = acc[ai][bj][m][1];
; #pragma unroll
;                     for (int j = 0; j < 4; ++j) { const float a = fmaxf(v0[j], 0.f), b = fmaxf(v1[j], 0.f); v0[j] = a * a; v1[j] = b * b; }
;                     u32x4 w; w.x = cvt_pk_bf16(v0[0], v0[1]); w.y = cvt_pk_bf16(v0[2], v0[3]); w.z = cvt_pk_bf16(v1[0], v1[1]); w.w = cvt_pk_bf16(v1[2], v1[3]);
;                     *(u32x4*)(rowp + bj * HALF) = w; } }
;     ...
;         if (!has_next) break;
; #pragma unroll
;         for (int a = 0; a < 2; ++a)
; #pragma unroll
;             for (int b = 0; b < 2; ++b)
; #pragma unroll
;                 for (int m = 0; m < 4; ++m)
; #pragma unroll
;                     for (int n = 0; n < 2; ++n) acc[a][b][m][n] = (f32x4){0.f, 0.f, 0.f, 0.f};
;         cur = nxt; cA = nA; cB = nB; ++ui;
;     }
;     PG8_WAIT_V(0);
;     if (wr == 0) PG8_BAR;
;     PG8_BAR;
	v_cvt_pk_bf16_f32 v49, v49, v50
	v_cvt_pk_bf16_f32 v50, v56, v53
	v_max_f32_e32 v40, 0, v40
	v_cvt_pk_bf16_f32 v51, v54, v51
	global_store_dwordx4 v[66:67], v[48:51], off offset:256
	s_nop 1
	v_max_f32_e32 v41, 0, v41
	v_max_f32_e32 v42, 0, v42
	v_mul_f32_e32 v50, v40, v40
	v_max_f32_e32 v40, v45, v45
	v_add_u32_e32 v48, 0x90, v150
	v_max_f32_e32 v40, 0, v40
	v_mul_f32_e32 v45, v41, v41
	v_max_f32_e32 v41, v46, v46
	v_mul_f32_e32 v46, v42, v42
	v_max_f32_e32 v42, v47, v47
	v_mad_i64_i32 v[48:49], s[2:3], v48, s8, v[140:141]
	v_max_f32_e32 v44, 0, v44
	v_mul_f32_e32 v40, v40, v40
	v_max_f32_e32 v41, 0, v41
	v_max_f32_e32 v42, 0, v42
	v_max_f32_e32 v43, 0, v43
	v_lshl_add_u64 v[48:49], v[48:49], 0, v[142:143]
	v_mul_f32_e32 v44, v44, v44
	v_mul_f32_e32 v41, v41, v41
	v_mul_f32_e32 v42, v42, v42
	v_mul_f32_e32 v43, v43, v43
	v_cvt_pk_bf16_f32 v40, v44, v40
	v_max_f32_e32 v32, 0, v32
	v_max_f32_e32 v33, 0, v33
	v_max_f32_e32 v34, 0, v34
	v_cvt_pk_bf16_f32 v41, v41, v42
	v_cvt_pk_bf16_f32 v42, v50, v45
	v_cvt_pk_bf16_f32 v43, v46, v43
	global_store_dwordx4 v[48:49], v[40:43], off
	s_nop 1
	v_mul_f32_e32 v40, v32, v32
	v_max_f32_e32 v32, v37, v37
	v_mul_f32_e32 v37, v33, v33
	v_max_f32_e32 v33, v38, v38
	v_mul_f32_e32 v38, v34, v34
	v_max_f32_e32 v34, v39, v39
	v_max_f32_e32 v32, 0, v32
	v_max_f32_e32 v33, 0, v33
	v_max_f32_e32 v34, 0, v34
	v_max_f32_e32 v36, 0, v36
	v_mul_f32_e32 v32, v32, v32
	v_mul_f32_e32 v33, v33, v33
	v_max_f32_e32 v35, 0, v35
	v_mul_f32_e32 v34, v34, v34
	v_mul_f32_e32 v36, v36, v36
	v_mul_f32_e32 v35, v35, v35
	v_cvt_pk_bf16_f32 v32, v36, v32
	v_cvt_pk_bf16_f32 v33, v33, v34
	v_cvt_pk_bf16_f32 v34, v40, v37
	v_max_f32_e32 v24, 0, v24
	v_cvt_pk_bf16_f32 v35, v38, v35
	global_store_dwordx4 v[48:49], v[32:35], off offset:256
	s_nop 1
	v_max_f32_e32 v25, 0, v25
	v_max_f32_e32 v26, 0, v26
	v_mul_f32_e32 v34, v24, v24
	v_max_f32_e32 v24, v29, v29
	v_add_u32_e32 v32, 0xa0, v150
	v_max_f32_e32 v24, 0, v24
	v_mul_f32_e32 v29, v25, v25
	v_max_f32_e32 v25, v30, v30
	v_mul_f32_e32 v30, v26, v26
	v_max_f32_e32 v26, v31, v31
	v_mad_i64_i32 v[32:33], s[2:3], v32, s8, v[140:141]
	v_max_f32_e32 v28, 0, v28
	v_mul_f32_e32 v24, v24, v24
	v_max_f32_e32 v25, 0, v25
	v_max_f32_e32 v26, 0, v26
	v_max_f32_e32 v27, 0, v27
	v_lshl_add_u64 v[32:33], v[32:33], 0, v[142:143]
	v_mul_f32_e32 v28, v28, v28
	v_mul_f32_e32 v25, v25, v25
	v_mul_f32_e32 v26, v26, v26
	v_mul_f32_e32 v27, v27, v27
	v_cvt_pk_bf16_f32 v24, v28, v24
	v_max_f32_e32 v16, 0, v16
	v_max_f32_e32 v17, 0, v17
	v_max_f32_e32 v18, 0, v18
	v_cvt_pk_bf16_f32 v25, v25, v26
	v_cvt_pk_bf16_f32 v26, v34, v29
	v_cvt_pk_bf16_f32 v27, v30, v27
	global_store_dwordx4 v[32:33], v[24:27], off
	s_nop 1
	v_mul_f32_e32 v24, v16, v16
	v_max_f32_e32 v16, v21, v21
	v_mul_f32_e32 v21, v17, v17
	v_max_f32_e32 v17, v22, v22
	v_mul_f32_e32 v22, v18, v18
	v_max_f32_e32 v18, v23, v23
	v_max_f32_e32 v16, 0, v16
	v_max_f32_e32 v17, 0, v17
	v_max_f32_e32 v18, 0, v18
	v_max_f32_e32 v20, 0, v20
	v_mul_f32_e32 v16, v16, v16
	v_mul_f32_e32 v17, v17, v17
	v_max_f32_e32 v19, 0, v19
	v_mul_f32_e32 v18, v18, v18
	v_mul_f32_e32 v20, v20, v20
	v_mul_f32_e32 v19, v19, v19
	v_cvt_pk_bf16_f32 v16, v20, v16
	v_cvt_pk_bf16_f32 v17, v17, v18
	v_cvt_pk_bf16_f32 v18, v24, v21
	v_max_f32_e32 v8, 0, v8
	v_cvt_pk_bf16_f32 v19, v22, v19
	global_store_dwordx4 v[32:33], v[16:19], off offset:256
	s_nop 1
	v_max_f32_e32 v9, 0, v9
	v_max_f32_e32 v10, 0, v10
	v_mul_f32_e32 v18, v8, v8
	v_max_f32_e32 v8, v13, v13
	v_add_u32_e32 v16, 0xb0, v150
	v_max_f32_e32 v8, 0, v8
	v_mul_f32_e32 v13, v9, v9
	v_max_f32_e32 v9, v14, v14
	v_mul_f32_e32 v14, v10, v10
	v_max_f32_e32 v10, v15, v15
	v_mad_i64_i32 v[16:17], s[2:3], v16, s8, v[140:141]
	v_max_f32_e32 v12, 0, v12
	v_mul_f32_e32 v8, v8, v8
	v_max_f32_e32 v9, 0, v9
	v_max_f32_e32 v10, 0, v10
	v_max_f32_e32 v11, 0, v11
	v_lshl_add_u64 v[16:17], v[16:17], 0, v[142:143]
	v_mul_f32_e32 v12, v12, v12
	v_mul_f32_e32 v9, v9, v9
	v_mul_f32_e32 v10, v10, v10
	v_mul_f32_e32 v11, v11, v11
	v_cvt_pk_bf16_f32 v8, v12, v8
	v_max_f32_e32 v0, 0, v0
	v_max_f32_e32 v1, 0, v1
	v_max_f32_e32 v2, 0, v2
	v_cvt_pk_bf16_f32 v9, v9, v10
	v_cvt_pk_bf16_f32 v10, v18, v13
	v_cvt_pk_bf16_f32 v11, v14, v11
	global_store_dwordx4 v[16:17], v[8:11], off
	s_nop 1
	v_mul_f32_e32 v8, v0, v0
	v_max_f32_e32 v0, v5, v5
	v_mul_f32_e32 v5, v1, v1
	v_max_f32_e32 v1, v6, v6
	v_mul_f32_e32 v6, v2, v2
	v_max_f32_e32 v2, v7, v7
	v_max_f32_e32 v0, 0, v0
	v_max_f32_e32 v1, 0, v1
	v_max_f32_e32 v2, 0, v2
	v_max_f32_e32 v3, 0, v3
	v_max_f32_e32 v4, 0, v4
	v_mul_f32_e32 v0, v0, v0
	v_mul_f32_e32 v1, v1, v1
	v_mul_f32_e32 v2, v2, v2
	v_mul_f32_e32 v3, v3, v3
	s_and_b64 vcc, exec, s[4:5]
	s_mov_b32 s38, s34
	s_mov_b32 s37, s36
	s_mov_b32 s40, s39
	s_mov_b64 s[10:11], s[18:19]
	s_mov_b64 s[8:9], s[6:7]
	s_mov_b32 s18, s33
	v_readlane_b32 s35, v251, 41
	v_mul_f32_e32 v4, v4, v4
	v_cvt_pk_bf16_f32 v0, v4, v0
	v_cvt_pk_bf16_f32 v1, v1, v2
	v_cvt_pk_bf16_f32 v2, v8, v5
	v_cvt_pk_bf16_f32 v3, v6, v3
	global_store_dwordx4 v[16:17], v[0:3], off offset:256
	s_nop 1
	s_cbranch_vccz .LBB0_96
	s_waitcnt vmcnt(0)
	v_readlane_b32 s40, v251, 24
	v_readlane_b32 s28, v252, 58
	s_cmpk_gt_u32 s15, 0xff
	s_movk_i32 s27, 0x1000
	v_readlane_b32 s41, v251, 25
	v_readlane_b32 s29, v252, 59
	s_cbranch_scc1 .LBB0_124
	s_barrier

; #define PG8_STAGE(bufoff, gbase, voff) do { _Pragma("unroll") for (int _i = 0; _i < 2; ++_i) \
;         __builtin_amdgcn_global_load_lds((const unsigned*)((const char*)(gbase) + (voff)[_i]), (LAS unsigned*)(lds + (bufoff) + ldsw + _i * 8192), 16, 0, 0); } while (0)
; #define PG8_LDA(dst, b, h) do { _Pragma("unroll") for (int m = 0; m < 4; ++m) _Pragma("unroll") for (int k = 0; k < 2; ++k) dst[m][k] = *(const LAS bf16x8*)(lds + PG8_SA(b, h) + aoff + m * 2048 + k * 1024); } while (0)
; #define PG8_LDB(dst, b, h) do { _Pragma("unroll") for (int n = 0; n < 2; ++n) _Pragma("unroll") for (int k = 0; k < 2; ++k) dst[n][k] = *(const LAS bf16x8*)(lds + PG8_SB(b, h) + boff + n * 2048 + k * 1024); } while (0)
; #define PG8_MMA(ai, bj, At, Bt) do { __builtin_amdgcn_s_setprio(1); _Pragma("unroll") for (int m = 0; m < 4; ++m) _Pragma("unroll") for (int n = 0; n < 2; ++n) _Pragma("unroll") for (int k = 0; k < 2; ++k) \
;         acc[ai][bj][m][n] = __builtin_amdgcn_mfma_f32_16x16x32_bf16(Bt[n][k], At[m][k], acc[ai][bj][m][n], 0, 0, 0); __builtin_amdgcn_s_setprio(0); } while (0)
; #define PG8_WAIT_L(n) asm volatile("s_waitcnt lgkmcnt(" #n ")" ::: "memory")
; #define PG8_BAR __builtin_amdgcn_s_barrier()
; #define PG8_SCHED __builtin_amdgcn_sched_barrier(0)
;     ...
;             const char* a1 = cA + (size_t)(t + 1) * kstep;
;             const char* a2 = last ? nA : cA + (size_t)(t + 2) * kstep; const char* b2 = last ? nB : cB + (size_t)(t + 2) * kstep;
;             const char* a3 = a2 + kstep; const char* b3 = b2 + kstep;
;             PG8_LDB(B0, 0, 0); PG8_SCHED; PG8_LDA(At, 0, 0); PG8_STAGE(PG8_SA(1, 1), a1 + hstep, voffA);
;             PG8_WAIT_L(8); PG8_BAR; PG8_WAIT_L(0); PG8_MMA(0, 0, At, B0); PG8_BAR; PG8_SCHED;
;             PG8_LDB(B1, 0, 1); PG8_STAGE(PG8_SB(0, 0), b2, voffB);
;             PG8_BAR; PG8_WAIT_L(0); PG8_MMA(0, 1, At, B1); PG8_BAR;
;             PG8_LDA(At, 0, 1); PG8_STAGE(PG8_SA(0, 0), a2, voffA);
;             PG8_BAR; PG8_WAIT_L(0); PG8_MMA(1, 0, At, B0); PG8_BAR; PG8_SCHED;
.LBB0_146:
	s_add_u32 s2, s8, 0xe515c080
	s_addc_u32 s3, s9, -1
	s_cmp_lg_u32 s27, 28
	s_cselect_b32 s10, s2, 0
	s_cselect_b32 s11, s3, 0
	s_add_u32 s2, s6, s10
	s_addc_u32 s3, s7, s11
	s_add_i32 s28, 0, 0x10000
	v_add_u32_e32 v156, s28, v142
	ds_read_b128 v[144:147], v156
	ds_read_b128 v[148:151], v156 offset:1024
	ds_read_b128 v[152:155], v156 offset:2048
	ds_read_b128 v[156:159], v156 offset:3072
	s_add_u32 s10, s4, s10
	s_addc_u32 s11, s5, s11
	v_lshl_add_u64 v[192:193], v[136:137], 0, s[8:9]
	s_add_i32 m0, s20, 0xc000
	ds_read_b128 v[160:163], v143
	ds_read_b128 v[164:167], v143 offset:1024
	ds_read_b128 v[168:171], v143 offset:2048
	ds_read_b128 v[172:175], v143 offset:3072
	ds_read_b128 v[176:179], v143 offset:4096
	ds_read_b128 v[180:183], v143 offset:5120
	ds_read_b128 v[184:187], v143 offset:6144
	ds_read_b128 v[188:191], v143 offset:7168
	global_load_lds_dwordx4 v[192:193], off
	v_lshl_add_u64 v[192:193], v[138:139], 0, s[8:9]
	s_add_i32 m0, s20, 0xe000
	s_nop 0
	global_load_lds_dwordx4 v[192:193], off
	s_waitcnt lgkmcnt(0)
	s_barrier
	v_mfma_f32_16x16x32_bf16 v[126:129], v[144:147], v[160:163], v[126:129]
	v_mfma_f32_16x16x32_bf16 v[122:125], v[152:155], v[160:163], v[122:125]
	v_mfma_f32_16x16x32_bf16 v[110:113], v[144:147], v[168:171], v[110:113]
	v_mfma_f32_16x16x32_bf16 v[106:109], v[152:155], v[168:171], v[106:109]
	v_mfma_f32_16x16x32_bf16 v[94:97], v[144:147], v[176:179], v[94:97]
	v_mfma_f32_16x16x32_bf16 v[90:93], v[152:155], v[176:179], v[90:93]
	v_mfma_f32_16x16x32_bf16 v[78:81], v[144:147], v[184:187], v[78:81]
	v_mfma_f32_16x16x32_bf16 v[74:77], v[152:155], v[184:187], v[74:77]
	v_mfma_f32_16x16x32_bf16 v[126:129], v[148:151], v[164:167], v[126:129]
	v_mfma_f32_16x16x32_bf16 v[122:125], v[156:159], v[164:167], v[122:125]
	v_mfma_f32_16x16x32_bf16 v[110:113], v[148:151], v[172:175], v[110:113]
	v_mfma_f32_16x16x32_bf16 v[106:109], v[156:159], v[172:175], v[106:109]
	v_mfma_f32_16x16x32_bf16 v[94:97], v[148:151], v[180:183], v[94:97]
	v_mfma_f32_16x16x32_bf16 v[90:93], v[156:159], v[180:183], v[90:93]
	v_mfma_f32_16x16x32_bf16 v[78:81], v[148:151], v[188:191], v[78:81]
	v_mfma_f32_16x16x32_bf16 v[74:77], v[156:159], v[188:191], v[74:77]
	s_barrier
	s_add_i32 s31, 0, 0x14000
	s_add_i32 s28, s28, s15
	v_add_u32_e32 v208, s31, v142
	v_lshl_add_u64 v[228:229], s[10:11], 0, v[64:65]
	s_mov_b32 m0, s28
	ds_read_b128 v[192:195], v208
	ds_read_b128 v[196:199], v208 offset:1024
	ds_read_b128 v[220:223], v208 offset:2048
	ds_read_b128 v[224:227], v208 offset:3072
	global_load_lds_dwordx4 v[228:229], off
	v_lshl_add_u64 v[230:231], s[10:11], 0, v[130:131]
	s_add_i32 m0, s28, 0x2000
	s_nop 0
	global_load_lds_dwordx4 v[230:231], off
	s_waitcnt lgkmcnt(0)
	s_barrier
	v_mfma_f32_16x16x32_bf16 v[118:121], v[192:195], v[160:163], v[118:121]
	v_mfma_f32_16x16x32_bf16 v[114:117], v[220:223], v[160:163], v[114:117]
	v_mfma_f32_16x16x32_bf16 v[102:105], v[192:195], v[168:171], v[102:105]
	v_mfma_f32_16x16x32_bf16 v[98:101], v[220:223], v[168:171], v[98:101]
	v_mfma_f32_16x16x32_bf16 v[86:89], v[192:195], v[176:179], v[86:89]
	v_mfma_f32_16x16x32_bf16 v[82:85], v[220:223], v[176:179], v[82:85]
	v_mfma_f32_16x16x32_bf16 v[70:73], v[192:195], v[184:187], v[70:73]
	v_mfma_f32_16x16x32_bf16 v[66:69], v[220:223], v[184:187], v[66:69]
	v_mfma_f32_16x16x32_bf16 v[118:121], v[196:199], v[164:167], v[118:121]
	v_mfma_f32_16x16x32_bf16 v[114:117], v[224:227], v[164:167], v[114:117]
	v_mfma_f32_16x16x32_bf16 v[102:105], v[196:199], v[172:175], v[102:105]
	v_mfma_f32_16x16x32_bf16 v[98:101], v[224:227], v[172:175], v[98:101]
	v_mfma_f32_16x16x32_bf16 v[86:89], v[196:199], v[180:183], v[86:89]
	v_mfma_f32_16x16x32_bf16 v[82:85], v[224:227], v[180:183], v[82:85]
	v_mfma_f32_16x16x32_bf16 v[70:73], v[196:199], v[188:191], v[70:73]
	v_mfma_f32_16x16x32_bf16 v[66:69], v[224:227], v[188:191], v[66:69]
	s_mov_b32 m0, s20
	v_lshl_add_u64 v[232:233], s[2:3], 0, v[134:135]
	s_barrier
	ds_read_b128 v[160:163], v143 offset:16384
	ds_read_b128 v[164:167], v143 offset:17408
	ds_read_b128 v[168:171], v143 offset:18432
	ds_read_b128 v[172:175], v143 offset:19456
	ds_read_b128 v[176:179], v143 offset:20480
	ds_read_b128 v[180:183], v143 offset:21504
	ds_read_b128 v[184:187], v143 offset:22528
	ds_read_b128 v[188:191], v143 offset:23552
	global_load_lds_dwordx4 v[232:233], off
	v_lshl_add_u64 v[234:235], s[2:3], 0, v[132:133]
	s_mov_b32 m0, s21
	s_nop 0
	global_load_lds_dwordx4 v[234:235], off
	s_waitcnt lgkmcnt(0)
	s_barrier
	v_mfma_f32_16x16x32_bf16 v[60:63], v[144:147], v[160:163], v[60:63]
	v_mfma_f32_16x16x32_bf16 v[56:59], v[152:155], v[160:163], v[56:59]
	v_mfma_f32_16x16x32_bf16 v[44:47], v[144:147], v[168:171], v[44:47]
	v_mfma_f32_16x16x32_bf16 v[40:43], v[152:155], v[168:171], v[40:43]
	v_mfma_f32_16x16x32_bf16 v[28:31], v[144:147], v[176:179], v[28:31]
	v_mfma_f32_16x16x32_bf16 v[24:27], v[152:155], v[176:179], v[24:27]
	v_mfma_f32_16x16x32_bf16 v[12:15], v[144:147], v[184:187], v[12:15]
	v_mfma_f32_16x16x32_bf16 v[8:11], v[152:155], v[184:187], v[8:11]
	v_mfma_f32_16x16x32_bf16 v[60:63], v[148:151], v[164:167], v[60:63]
	v_mfma_f32_16x16x32_bf16 v[56:59], v[156:159], v[164:167], v[56:59]
	v_mfma_f32_16x16x32_bf16 v[44:47], v[148:151], v[172:175], v[44:47]
	v_mfma_f32_16x16x32_bf16 v[40:43], v[156:159], v[172:175], v[40:43]
	v_mfma_f32_16x16x32_bf16 v[28:31], v[148:151], v[180:183], v[28:31]
	v_mfma_f32_16x16x32_bf16 v[24:27], v[156:159], v[180:183], v[24:27]
	v_mfma_f32_16x16x32_bf16 v[12:15], v[148:151], v[188:191], v[12:15]
	v_mfma_f32_16x16x32_bf16 v[8:11], v[156:159], v[188:191], v[8:11]
	s_barrier
; #define PG8_STAGE(bufoff, gbase, voff) do { _Pragma("unroll") for (int _i = 0; _i < 2; ++_i) \
;         __builtin_amdgcn_global_load_lds((const unsigned*)((const char*)(gbase) + (voff)[_i]), (LAS unsigned*)(lds + (bufoff) + ldsw + _i * 8192), 16, 0, 0); } while (0)
; #define PG8_LDA(dst, b, h) do { _Pragma("unroll") for (int m = 0; m < 4; ++m) _Pragma("unroll") for (int k = 0; k < 2; ++k) dst[m][k] = *(const LAS bf16x8*)(lds + PG8_SA(b, h) + aoff + m * 2048 + k * 1024); } while (0)
; #define PG8_LDB(dst, b, h) do { _Pragma("unroll") for (int n = 0; n < 2; ++n) _Pragma("unroll") for (int k = 0; k < 2; ++k) dst[n][k] = *(const LAS bf16x8*)(lds + PG8_SB(b, h) + boff + n * 2048 + k * 1024); } while (0)
; #define PG8_MMA(ai, bj, At, Bt) do { __builtin_amdgcn_s_setprio(1); _Pragma("unroll") for (int m = 0; m < 4; ++m) _Pragma("unroll") for (int n = 0; n < 2; ++n) _Pragma("unroll") for (int k = 0; k < 2; ++k) \
;         acc[ai][bj][m][n] = __builtin_amdgcn_mfma_f32_16x16x32_bf16(Bt[n][k], At[m][k], acc[ai][bj][m][n], 0, 0, 0); __builtin_amdgcn_s_setprio(0); } while (0)
; #define PG8_WAIT_V(n) asm volatile("s_waitcnt vmcnt(" #n ")" ::: "memory")
; #define PG8_WAIT_L(n) asm volatile("s_waitcnt lgkmcnt(" #n ")" ::: "memory")
; #define PG8_BAR __builtin_amdgcn_s_barrier()
; #define PG8_SCHED __builtin_amdgcn_sched_barrier(0)
;     ...
;             PG8_STAGE(PG8_SB(0, 1), b2 + hstep, voffB);
;             PG8_WAIT_V(6); PG8_BAR; PG8_MMA(1, 1, At, B1); PG8_BAR;
;             PG8_LDB(B0, 1, 0); PG8_SCHED; PG8_LDA(At, 1, 0); PG8_STAGE(PG8_SA(0, 1), a2 + hstep, voffA);
;             PG8_WAIT_L(8); PG8_BAR; PG8_WAIT_L(0); PG8_MMA(0, 0, At, B0); PG8_BAR; PG8_SCHED;
;             PG8_LDB(B1, 1, 1); PG8_STAGE(PG8_SB(1, 0), b3, voffB);
;             PG8_BAR; PG8_WAIT_L(0); PG8_MMA(0, 1, At, B1); PG8_BAR;
;             PG8_LDA(At, 1, 1); PG8_STAGE(PG8_SA(1, 0), a3, voffA);
;             PG8_BAR; PG8_WAIT_L(0); PG8_MMA(1, 0, At, B0); PG8_BAR; PG8_SCHED;
	s_add_u32 s28, s10, 0x84000
	s_addc_u32 s29, s11, 0
	s_add_i32 s31, s31, s15
	v_lshl_add_u64 v[144:145], s[28:29], 0, v[64:65]
	s_mov_b32 m0, s31
	s_nop 0
	global_load_lds_dwordx4 v[144:145], off
	v_lshl_add_u64 v[144:145], s[28:29], 0, v[130:131]
	s_add_i32 m0, s31, 0x2000
	s_nop 0
	global_load_lds_dwordx4 v[144:145], off
	s_waitcnt vmcnt(6)
	s_barrier
	v_mfma_f32_16x16x32_bf16 v[52:55], v[192:195], v[160:163], v[52:55]
	v_mfma_f32_16x16x32_bf16 v[48:51], v[220:223], v[160:163], v[48:51]
	v_mfma_f32_16x16x32_bf16 v[36:39], v[192:195], v[168:171], v[36:39]
	v_mfma_f32_16x16x32_bf16 v[32:35], v[220:223], v[168:171], v[32:35]
	v_mfma_f32_16x16x32_bf16 v[20:23], v[192:195], v[176:179], v[20:23]
	v_mfma_f32_16x16x32_bf16 v[16:19], v[220:223], v[176:179], v[16:19]
	v_mfma_f32_16x16x32_bf16 v[4:7], v[192:195], v[184:187], v[4:7]
	v_mfma_f32_16x16x32_bf16 v[0:3], v[220:223], v[184:187], v[0:3]
	v_mfma_f32_16x16x32_bf16 v[52:55], v[196:199], v[164:167], v[52:55]
	v_mfma_f32_16x16x32_bf16 v[48:51], v[224:227], v[164:167], v[48:51]
	v_mfma_f32_16x16x32_bf16 v[36:39], v[196:199], v[172:175], v[36:39]
	v_mfma_f32_16x16x32_bf16 v[32:35], v[224:227], v[172:175], v[32:35]
	v_mfma_f32_16x16x32_bf16 v[20:23], v[196:199], v[180:183], v[20:23]
	v_mfma_f32_16x16x32_bf16 v[16:19], v[224:227], v[180:183], v[16:19]
	v_mfma_f32_16x16x32_bf16 v[4:7], v[196:199], v[188:191], v[4:7]
	v_mfma_f32_16x16x32_bf16 v[0:3], v[224:227], v[188:191], v[0:3]
	s_add_i32 s28, 0, 0x18000
	v_add_u32_e32 v156, s28, v142
	s_barrier
	ds_read_b128 v[144:147], v156
	ds_read_b128 v[148:151], v156 offset:1024
	ds_read_b128 v[152:155], v156 offset:2048
	ds_read_b128 v[156:159], v156 offset:3072
	s_add_u32 s2, s2, 0x84000
	s_addc_u32 s3, s3, 0
	s_mov_b32 m0, s22
	v_lshl_add_u64 v[192:193], s[2:3], 0, v[134:135]
	ds_read_b128 v[160:163], v143 offset:32768
	ds_read_b128 v[164:167], v143 offset:33792
	ds_read_b128 v[168:171], v143 offset:34816
	ds_read_b128 v[172:175], v143 offset:35840
	ds_read_b128 v[176:179], v143 offset:36864
	ds_read_b128 v[180:183], v143 offset:37888
	ds_read_b128 v[184:187], v143 offset:38912
	ds_read_b128 v[188:191], v143 offset:39936
	global_load_lds_dwordx4 v[192:193], off
	v_lshl_add_u64 v[192:193], s[2:3], 0, v[132:133]
	s_mov_b32 m0, s23
	s_nop 0
	global_load_lds_dwordx4 v[192:193], off
	s_waitcnt lgkmcnt(0)
	s_barrier
	v_mfma_f32_16x16x32_bf16 v[126:129], v[144:147], v[160:163], v[126:129]
	v_mfma_f32_16x16x32_bf16 v[122:125], v[152:155], v[160:163], v[122:125]
	v_mfma_f32_16x16x32_bf16 v[110:113], v[144:147], v[168:171], v[110:113]
	v_mfma_f32_16x16x32_bf16 v[106:109], v[152:155], v[168:171], v[106:109]
	v_mfma_f32_16x16x32_bf16 v[94:97], v[144:147], v[176:179], v[94:97]
	v_mfma_f32_16x16x32_bf16 v[90:93], v[152:155], v[176:179], v[90:93]
	v_mfma_f32_16x16x32_bf16 v[78:81], v[144:147], v[184:187], v[78:81]
	v_mfma_f32_16x16x32_bf16 v[74:77], v[152:155], v[184:187], v[74:77]
	v_mfma_f32_16x16x32_bf16 v[126:129], v[148:151], v[164:167], v[126:129]
	v_mfma_f32_16x16x32_bf16 v[122:125], v[156:159], v[164:167], v[122:125]
	v_mfma_f32_16x16x32_bf16 v[110:113], v[148:151], v[172:175], v[110:113]
	v_mfma_f32_16x16x32_bf16 v[106:109], v[156:159], v[172:175], v[106:109]
	v_mfma_f32_16x16x32_bf16 v[94:97], v[148:151], v[180:183], v[94:97]
	v_mfma_f32_16x16x32_bf16 v[90:93], v[156:159], v[180:183], v[90:93]
	v_mfma_f32_16x16x32_bf16 v[78:81], v[148:151], v[188:191], v[78:81]
	v_mfma_f32_16x16x32_bf16 v[74:77], v[156:159], v[188:191], v[74:77]
	s_barrier
	s_add_i32 s29, 0, 0x1c000
	s_add_i32 s2, s28, s15
	v_add_u32_e32 v208, s29, v142
	v_lshl_add_u64 v[228:229], v[228:229], 0, s[16:17]
	s_mov_b32 m0, s2
	ds_read_b128 v[192:195], v208
	ds_read_b128 v[196:199], v208 offset:1024
	ds_read_b128 v[220:223], v208 offset:2048
	ds_read_b128 v[224:227], v208 offset:3072
	global_load_lds_dwordx4 v[228:229], off
	v_lshl_add_u64 v[228:229], v[230:231], 0, s[16:17]
	s_add_i32 m0, s2, 0x2000
	s_nop 0
	global_load_lds_dwordx4 v[228:229], off
	s_waitcnt lgkmcnt(0)
	s_barrier
	v_mfma_f32_16x16x32_bf16 v[118:121], v[192:195], v[160:163], v[118:121]
	v_mfma_f32_16x16x32_bf16 v[114:117], v[220:223], v[160:163], v[114:117]
	v_mfma_f32_16x16x32_bf16 v[102:105], v[192:195], v[168:171], v[102:105]
	v_mfma_f32_16x16x32_bf16 v[98:101], v[220:223], v[168:171], v[98:101]
	v_mfma_f32_16x16x32_bf16 v[86:89], v[192:195], v[176:179], v[86:89]
	v_mfma_f32_16x16x32_bf16 v[82:85], v[220:223], v[176:179], v[82:85]
	v_mfma_f32_16x16x32_bf16 v[70:73], v[192:195], v[184:187], v[70:73]
	v_mfma_f32_16x16x32_bf16 v[66:69], v[220:223], v[184:187], v[66:69]
	v_mfma_f32_16x16x32_bf16 v[118:121], v[196:199], v[164:167], v[118:121]
	v_mfma_f32_16x16x32_bf16 v[114:117], v[224:227], v[164:167], v[114:117]
	v_mfma_f32_16x16x32_bf16 v[102:105], v[196:199], v[172:175], v[102:105]
	v_mfma_f32_16x16x32_bf16 v[98:101], v[224:227], v[172:175], v[98:101]
	v_mfma_f32_16x16x32_bf16 v[86:89], v[196:199], v[180:183], v[86:89]
	v_mfma_f32_16x16x32_bf16 v[82:85], v[224:227], v[180:183], v[82:85]
	v_mfma_f32_16x16x32_bf16 v[70:73], v[196:199], v[188:191], v[70:73]
	v_mfma_f32_16x16x32_bf16 v[66:69], v[224:227], v[188:191], v[66:69]
	s_mov_b32 m0, s25
	v_lshl_add_u64 v[228:229], v[232:233], 0, s[16:17]
	s_barrier
	ds_read_b128 v[160:163], v143 offset:49152
	ds_read_b128 v[164:167], v143 offset:50176
	ds_read_b128 v[168:171], v143 offset:51200
	ds_read_b128 v[172:175], v143 offset:52224
	ds_read_b128 v[176:179], v143 offset:53248
	ds_read_b128 v[180:183], v143 offset:54272
	ds_read_b128 v[184:187], v143 offset:55296
	ds_read_b128 v[188:191], v143 offset:56320
	global_load_lds_dwordx4 v[228:229], off
	v_lshl_add_u64 v[228:229], v[234:235], 0, s[16:17]
	s_mov_b32 m0, s26
	s_nop 0
	global_load_lds_dwordx4 v[228:229], off
	s_waitcnt lgkmcnt(0)
	s_barrier
; __device__ __forceinline__ unsigned cvt_pk_bf16(float lo, float hi) { unsigned r; asm volatile("v_cvt_pk_bf16_f32 %0, %1, %2" : "=v"(r) : "v"(lo), "v"(hi)); return r; }
; #define PG8_STAGE(bufoff, gbase, voff) do { _Pragma("unroll") for (int _i = 0; _i < 2; ++_i) \
;         __builtin_amdgcn_global_load_lds((const unsigned*)((const char*)(gbase) + (voff)[_i]), (LAS unsigned*)(lds + (bufoff) + ldsw + _i * 8192), 16, 0, 0); } while (0)
; #define PG8_MMA(ai, bj, At, Bt) do { __builtin_amdgcn_s_setprio(1); _Pragma("unroll") for (int m = 0; m < 4; ++m) _Pragma("unroll") for (int n = 0; n < 2; ++n) _Pragma("unroll") for (int k = 0; k < 2; ++k) \
;         acc[ai][bj][m][n] = __builtin_amdgcn_mfma_f32_16x16x32_bf16(Bt[n][k], At[m][k], acc[ai][bj][m][n], 0, 0, 0); __builtin_amdgcn_s_setprio(0); } while (0)
; #define PG8_WAIT_V(n) asm volatile("s_waitcnt vmcnt(" #n ")" ::: "memory")
; #define PG8_WAIT_L(n) asm volatile("s_waitcnt lgkmcnt(" #n ")" ::: "memory")
; #define PG8_BAR __builtin_amdgcn_s_barrier()
; #define PG8_SCHED __builtin_amdgcn_sched_barrier(0)
;     __device__ __forceinline__ void operator()(const f32x4 (&acc)[2][2][4][2], const Unit& u, int wr, int wc, int fr, int fq) const {
;     ...
;             for (int m = 0; m < 4; ++m) { bf16_t* rowp = O + (size_t)(row0 + ai * HALF + m * 16) * LDF + col0;
; #pragma unroll
;                 for (int bj = 0; bj < 2; ++bj) { f32x4 v0 = acc[ai][bj][m][0], v1 = acc[ai][bj][m][1];
; #pragma unroll
;                     for (int j = 0; j < 4; ++j) { const float a = fmaxf(v0[j], 0.f), b = fmaxf(v1[j], 0.f); v0[j] = a * a; v1[j] = b * b; }
;                     u32x4 w; w.x = cvt_pk_bf16(v0[0], v0[1]); w.y = cvt_pk_bf16(v0[2], v0[3]); w.z = cvt_pk_bf16(v1[0], v1[1]); w.w = cvt_pk_bf16(v1[2], v1[3]);
;                     *(u32x4*)(rowp + bj * HALF) = w; } }
;     ...
;             PG8_BAR; PG8_WAIT_L(0); PG8_MMA(1, 0, At, B0); PG8_BAR; PG8_SCHED;
;             PG8_STAGE(PG8_SB(1, 1), b3 + hstep, voffB);
;             PG8_WAIT_V(6); PG8_BAR; PG8_MMA(1, 1, At, B1); PG8_BAR;
;         }
	v_mfma_f32_16x16x32_bf16 v[60:63], v[144:147], v[160:163], v[60:63]
	v_mfma_f32_16x16x32_bf16 v[56:59], v[152:155], v[160:163], v[56:59]
	v_mfma_f32_16x16x32_bf16 v[44:47], v[144:147], v[168:171], v[44:47]
	v_mfma_f32_16x16x32_bf16 v[40:43], v[152:155], v[168:171], v[40:43]
	v_mfma_f32_16x16x32_bf16 v[28:31], v[144:147], v[176:179], v[28:31]
	v_mfma_f32_16x16x32_bf16 v[24:27], v[152:155], v[176:179], v[24:27]
	v_mfma_f32_16x16x32_bf16 v[12:15], v[144:147], v[184:187], v[12:15]
	v_mfma_f32_16x16x32_bf16 v[8:11], v[152:155], v[184:187], v[8:11]
	v_mfma_f32_16x16x32_bf16 v[60:63], v[148:151], v[164:167], v[60:63]
	v_mfma_f32_16x16x32_bf16 v[56:59], v[156:159], v[164:167], v[56:59]
	v_mfma_f32_16x16x32_bf16 v[44:47], v[148:151], v[172:175], v[44:47]
	v_mfma_f32_16x16x32_bf16 v[40:43], v[156:159], v[172:175], v[40:43]
	v_mfma_f32_16x16x32_bf16 v[28:31], v[148:151], v[180:183], v[28:31]
	v_mfma_f32_16x16x32_bf16 v[24:27], v[156:159], v[180:183], v[24:27]
	v_mfma_f32_16x16x32_bf16 v[12:15], v[148:151], v[188:191], v[12:15]
	v_mfma_f32_16x16x32_bf16 v[8:11], v[156:159], v[188:191], v[8:11]
	s_barrier
	s_add_u32 s2, s10, 0x84080
	s_addc_u32 s3, s11, 0
	s_add_i32 s10, s29, s15
	v_lshl_add_u64 v[144:145], s[2:3], 0, v[64:65]
	s_mov_b32 m0, s10
	s_nop 0
	global_load_lds_dwordx4 v[144:145], off
	v_lshl_add_u64 v[144:145], s[2:3], 0, v[130:131]
	s_add_i32 m0, s10, 0x2000
	s_nop 0
	global_load_lds_dwordx4 v[144:145], off
	s_waitcnt vmcnt(6)
	s_barrier
	v_mfma_f32_16x16x32_bf16 v[52:55], v[192:195], v[160:163], v[52:55]
	v_mfma_f32_16x16x32_bf16 v[48:51], v[220:223], v[160:163], v[48:51]
	v_mfma_f32_16x16x32_bf16 v[36:39], v[192:195], v[168:171], v[36:39]
	v_mfma_f32_16x16x32_bf16 v[32:35], v[220:223], v[168:171], v[32:35]
	v_mfma_f32_16x16x32_bf16 v[20:23], v[192:195], v[176:179], v[20:23]
	v_mfma_f32_16x16x32_bf16 v[16:19], v[220:223], v[176:179], v[16:19]
	v_mfma_f32_16x16x32_bf16 v[4:7], v[192:195], v[184:187], v[4:7]
	v_mfma_f32_16x16x32_bf16 v[0:3], v[220:223], v[184:187], v[0:3]
	v_mfma_f32_16x16x32_bf16 v[52:55], v[196:199], v[164:167], v[52:55]
	v_mfma_f32_16x16x32_bf16 v[48:51], v[224:227], v[164:167], v[48:51]
	v_mfma_f32_16x16x32_bf16 v[36:39], v[196:199], v[172:175], v[36:39]
	v_mfma_f32_16x16x32_bf16 v[32:35], v[224:227], v[172:175], v[32:35]
	v_mfma_f32_16x16x32_bf16 v[20:23], v[196:199], v[180:183], v[20:23]
	v_mfma_f32_16x16x32_bf16 v[16:19], v[224:227], v[180:183], v[16:19]
	v_mfma_f32_16x16x32_bf16 v[4:7], v[196:199], v[188:191], v[4:7]
	v_mfma_f32_16x16x32_bf16 v[0:3], v[224:227], v[188:191], v[0:3]
	s_add_i32 s27, s27, 2
	s_add_u32 s8, s8, 0x100
	s_addc_u32 s9, s9, 0
	s_cmp_gt_u32 s27, 29
	s_barrier
	s_cbranch_scc0 .LBB0_146
	s_lshl_b32 s2, s19, 8
	v_max_f32_e32 v122, 0, v122
	s_or_b32 s2, s24, s2
	v_mul_f32_e32 v135, v122, v122
	v_max_f32_e32 v122, v127, v127
	v_max_f32_e32 v123, 0, v123
	v_max_f32_e32 v124, 0, v124
	v_lshl_add_u32 v134, s18, 8, v141
	v_or_b32_e32 v64, s2, v140
	v_mov_b64_e32 v[130:131], s[80:81]
	s_movk_i32 s4, 0x4080
	v_max_f32_e32 v122, 0, v122
	v_mul_f32_e32 v127, v123, v123
	v_max_f32_e32 v123, v128, v128
	v_mul_f32_e32 v128, v124, v124
	v_max_f32_e32 v124, v129, v129
	v_mad_i64_i32 v[132:133], s[2:3], v134, s4, v[130:131]
	v_lshlrev_b32_e32 v64, 1, v64
	v_max_f32_e32 v126, 0, v126
	v_mul_f32_e32 v122, v122, v122
	v_max_f32_e32 v123, 0, v123
	v_max_f32_e32 v124, 0, v124
	v_max_f32_e32 v125, 0, v125
	v_lshl_add_u64 v[132:133], v[132:133], 0, v[64:65]
	v_mul_f32_e32 v126, v126, v126
	v_mul_f32_e32 v123, v123, v123
	v_mul_f32_e32 v124, v124, v124
	v_mul_f32_e32 v125, v125, v125
	v_cvt_pk_bf16_f32 v122, v126, v122
	v_max_f32_e32 v114, 0, v114
	v_max_f32_e32 v115, 0, v115
	v_max_f32_e32 v116, 0, v116
	v_cvt_pk_bf16_f32 v123, v123, v124
	v_cvt_pk_bf16_f32 v124, v135, v127
	v_cvt_pk_bf16_f32 v125, v128, v125
	global_store_dwordx4 v[132:133], v[122:125], off
	s_nop 1
	v_mul_f32_e32 v122, v114, v114
	v_max_f32_e32 v114, v119, v119
	v_mul_f32_e32 v119, v115, v115
	v_max_f32_e32 v115, v120, v120
	v_mul_f32_e32 v120, v116, v116
	v_max_f32_e32 v116, v121, v121
	v_max_f32_e32 v114, 0, v114
	v_max_f32_e32 v115, 0, v115
	v_max_f32_e32 v116, 0, v116
	v_max_f32_e32 v118, 0, v118
	v_mul_f32_e32 v114, v114, v114
	v_mul_f32_e32 v115, v115, v115
	v_max_f32_e32 v117, 0, v117
	v_mul_f32_e32 v116, v116, v116
	v_mul_f32_e32 v118, v118, v118
	v_mul_f32_e32 v117, v117, v117
	v_cvt_pk_bf16_f32 v114, v118, v114
	v_cvt_pk_bf16_f32 v115, v115, v116
	v_cvt_pk_bf16_f32 v116, v122, v119
	v_max_f32_e32 v106, 0, v106
	v_cvt_pk_bf16_f32 v117, v120, v117
	global_store_dwordx4 v[132:133], v[114:117], off offset:256
	s_nop 1
	v_max_f32_e32 v107, 0, v107
	v_max_f32_e32 v108, 0, v108
	v_mul_f32_e32 v116, v106, v106
	v_max_f32_e32 v106, v111, v111
	v_or_b32_e32 v114, 16, v134
	v_max_f32_e32 v106, 0, v106
	v_mul_f32_e32 v111, v107, v107
	v_max_f32_e32 v107, v112, v112
	v_mul_f32_e32 v112, v108, v108
	v_max_f32_e32 v108, v113, v113
	v_mad_i64_i32 v[114:115], s[2:3], v114, s4, v[130:131]
	v_max_f32_e32 v110, 0, v110
	v_mul_f32_e32 v106, v106, v106
	v_max_f32_e32 v107, 0, v107
	v_max_f32_e32 v108, 0, v108
	v_max_f32_e32 v109, 0, v109
	v_lshl_add_u64 v[114:115], v[114:115], 0, v[64:65]
	v_mul_f32_e32 v110, v110, v110
	v_mul_f32_e32 v107, v107, v107
	v_mul_f32_e32 v108, v108, v108
	v_mul_f32_e32 v109, v109, v109
	v_cvt_pk_bf16_f32 v106, v110, v106
	v_max_f32_e32 v98, 0, v98
	v_max_f32_e32 v99, 0, v99
	v_max_f32_e32 v100, 0, v100
	v_cvt_pk_bf16_f32 v107, v107, v108
	v_cvt_pk_bf16_f32 v108, v116, v111
	v_cvt_pk_bf16_f32 v109, v112, v109
	global_store_dwordx4 v[114:115], v[106:109], off
	s_nop 1
	v_mul_f32_e32 v106, v98, v98
	v_max_f32_e32 v98, v103, v103
; __device__ __forceinline__ unsigned cvt_pk_bf16(float lo, float hi) { unsigned r; asm volatile("v_cvt_pk_bf16_f32 %0, %1, %2" : "=v"(r) : "v"(lo), "v"(hi)); return r; }
;     __device__ __forceinline__ void operator()(const f32x4 (&acc)[2][2][4][2], const Unit& u, int wr, int wc, int fr, int fq) const {
;     ...
;             for (int m = 0; m < 4; ++m) { bf16_t* rowp = O + (size_t)(row0 + ai * HALF + m * 16) * LDF + col0;
; #pragma unroll
;                 for (int bj = 0; bj < 2; ++bj) { f32x4 v0 = acc[ai][bj][m][0], v1 = acc[ai][bj][m][1];
; #pragma unroll
;                     for (int j = 0; j < 4; ++j) { const float a = fmaxf(v0[j], 0.f), b = fmaxf(v1[j], 0.f); v0[j] = a * a; v1[j] = b * b; }
;                     u32x4 w; w.x = cvt_pk_bf16(v0[0], v0[1]); w.y = cvt_pk_bf16(v0[2], v0[3]); w.z = cvt_pk_bf16(v1[0], v1[1]); w.w = cvt_pk_bf16(v1[2], v1[3]);
;                     *(u32x4*)(rowp + bj * HALF) = w; } }
	v_mul_f32_e32 v103, v99, v99
	v_max_f32_e32 v99, v104, v104
	v_mul_f32_e32 v104, v100, v100
	v_max_f32_e32 v100, v105, v105
	v_max_f32_e32 v98, 0, v98
	v_max_f32_e32 v99, 0, v99
	v_max_f32_e32 v100, 0, v100
	v_max_f32_e32 v102, 0, v102
	v_mul_f32_e32 v98, v98, v98
	v_mul_f32_e32 v99, v99, v99
	v_max_f32_e32 v101, 0, v101
	v_mul_f32_e32 v100, v100, v100
	v_mul_f32_e32 v102, v102, v102
	v_mul_f32_e32 v101, v101, v101
	v_cvt_pk_bf16_f32 v98, v102, v98
	v_cvt_pk_bf16_f32 v99, v99, v100
	v_cvt_pk_bf16_f32 v100, v106, v103
	v_max_f32_e32 v90, 0, v90
	v_cvt_pk_bf16_f32 v101, v104, v101
	global_store_dwordx4 v[114:115], v[98:101], off offset:256
	s_nop 1
	v_max_f32_e32 v91, 0, v91
	v_max_f32_e32 v92, 0, v92
	v_mul_f32_e32 v100, v90, v90
	v_max_f32_e32 v90, v95, v95
	v_or_b32_e32 v98, 32, v134
	v_max_f32_e32 v90, 0, v90
	v_mul_f32_e32 v95, v91, v91
	v_max_f32_e32 v91, v96, v96
	v_mul_f32_e32 v96, v92, v92
	v_max_f32_e32 v92, v97, v97
	v_mad_i64_i32 v[98:99], s[2:3], v98, s4, v[130:131]
	v_max_f32_e32 v94, 0, v94
	v_mul_f32_e32 v90, v90, v90
	v_max_f32_e32 v91, 0, v91
	v_max_f32_e32 v92, 0, v92
	v_max_f32_e32 v93, 0, v93
	v_lshl_add_u64 v[98:99], v[98:99], 0, v[64:65]
	v_mul_f32_e32 v94, v94, v94
	v_mul_f32_e32 v91, v91, v91
	v_mul_f32_e32 v92, v92, v92
	v_mul_f32_e32 v93, v93, v93
	v_cvt_pk_bf16_f32 v90, v94, v90
	v_max_f32_e32 v82, 0, v82
	v_max_f32_e32 v83, 0, v83
	v_max_f32_e32 v84, 0, v84
	v_cvt_pk_bf16_f32 v91, v91, v92
	v_cvt_pk_bf16_f32 v92, v100, v95
	v_cvt_pk_bf16_f32 v93, v96, v93
	global_store_dwordx4 v[98:99], v[90:93], off
	s_nop 1
	v_mul_f32_e32 v90, v82, v82
	v_max_f32_e32 v82, v87, v87
	v_mul_f32_e32 v87, v83, v83
	v_max_f32_e32 v83, v88, v88
	v_mul_f32_e32 v88, v84, v84
	v_max_f32_e32 v84, v89, v89
	v_max_f32_e32 v82, 0, v82
	v_max_f32_e32 v83, 0, v83
	v_max_f32_e32 v84, 0, v84
	v_max_f32_e32 v86, 0, v86
	v_mul_f32_e32 v82, v82, v82
	v_mul_f32_e32 v83, v83, v83
	v_max_f32_e32 v85, 0, v85
	v_mul_f32_e32 v84, v84, v84
	v_mul_f32_e32 v86, v86, v86
	v_mul_f32_e32 v85, v85, v85
	v_cvt_pk_bf16_f32 v82, v86, v82
	v_cvt_pk_bf16_f32 v83, v83, v84
	v_cvt_pk_bf16_f32 v84, v90, v87
	v_max_f32_e32 v74, 0, v74
	v_cvt_pk_bf16_f32 v85, v88, v85
	global_store_dwordx4 v[98:99], v[82:85], off offset:256
	s_nop 1
	v_max_f32_e32 v75, 0, v75
	v_max_f32_e32 v76, 0, v76
	v_mul_f32_e32 v84, v74, v74
	v_max_f32_e32 v74, v79, v79
	v_or_b32_e32 v82, 48, v134
	v_max_f32_e32 v74, 0, v74
	v_mul_f32_e32 v79, v75, v75
	v_max_f32_e32 v75, v80, v80
	v_mul_f32_e32 v80, v76, v76
	v_max_f32_e32 v76, v81, v81
	v_mad_i64_i32 v[82:83], s[2:3], v82, s4, v[130:131]
	v_max_f32_e32 v78, 0, v78
	v_mul_f32_e32 v74, v74, v74
	v_max_f32_e32 v75, 0, v75
	v_max_f32_e32 v76, 0, v76
	v_max_f32_e32 v77, 0, v77
	v_lshl_add_u64 v[82:83], v[82:83], 0, v[64:65]
	v_mul_f32_e32 v78, v78, v78
	v_mul_f32_e32 v75, v75, v75
	v_mul_f32_e32 v76, v76, v76
	v_mul_f32_e32 v77, v77, v77
	v_cvt_pk_bf16_f32 v74, v78, v74
	v_max_f32_e32 v66, 0, v66
	v_max_f32_e32 v67, 0, v67
	v_max_f32_e32 v68, 0, v68
	v_cvt_pk_bf16_f32 v75, v75, v76
	v_cvt_pk_bf16_f32 v76, v84, v79
	v_cvt_pk_bf16_f32 v77, v80, v77
	global_store_dwordx4 v[82:83], v[74:77], off
	s_nop 1
	v_mul_f32_e32 v74, v66, v66
	v_max_f32_e32 v66, v71, v71
	v_mul_f32_e32 v71, v67, v67
	v_max_f32_e32 v67, v72, v72
	v_mul_f32_e32 v72, v68, v68
	v_max_f32_e32 v68, v73, v73
	v_max_f32_e32 v66, 0, v66
	v_max_f32_e32 v67, 0, v67
	v_max_f32_e32 v68, 0, v68
	v_max_f32_e32 v70, 0, v70
	v_mul_f32_e32 v66, v66, v66
	v_mul_f32_e32 v67, v67, v67
	v_max_f32_e32 v69, 0, v69
	v_mul_f32_e32 v68, v68, v68
	v_mul_f32_e32 v70, v70, v70
	v_mul_f32_e32 v69, v69, v69
	v_cvt_pk_bf16_f32 v66, v70, v66
	v_cvt_pk_bf16_f32 v67, v67, v68
	v_cvt_pk_bf16_f32 v68, v74, v71
	v_max_f32_e32 v56, 0, v56
	v_cvt_pk_bf16_f32 v69, v72, v69
	global_store_dwordx4 v[82:83], v[66:69], off offset:256
	s_nop 1
	v_max_f32_e32 v57, 0, v57
	v_max_f32_e32 v58, 0, v58
	v_mul_f32_e32 v68, v56, v56
	v_max_f32_e32 v56, v61, v61
	v_add_u32_e32 v66, 0x80, v134
	v_max_f32_e32 v56, 0, v56
	v_mul_f32_e32 v61, v57, v57
	v_max_f32_e32 v57, v62, v62
	v_mul_f32_e32 v62, v58, v58
	v_max_f32_e32 v58, v63, v63
	v_mad_i64_i32 v[66:67], s[2:3], v66, s4, v[130:131]
	v_max_f32_e32 v60, 0, v60
	v_mul_f32_e32 v56, v56, v56
	v_max_f32_e32 v57, 0, v57
	v_max_f32_e32 v58, 0, v58
	v_max_f32_e32 v59, 0, v59
	v_lshl_add_u64 v[66:67], v[66:67], 0, v[64:65]
	v_mul_f32_e32 v60, v60, v60
	v_mul_f32_e32 v57, v57, v57
	v_mul_f32_e32 v58, v58, v58
	v_mul_f32_e32 v59, v59, v59
	v_cvt_pk_bf16_f32 v56, v60, v56
	v_max_f32_e32 v48, 0, v48
	v_max_f32_e32 v49, 0, v49
	v_max_f32_e32 v50, 0, v50
	v_cvt_pk_bf16_f32 v57, v57, v58
	v_cvt_pk_bf16_f32 v58, v68, v61
	v_cvt_pk_bf16_f32 v59, v62, v59
	global_store_dwordx4 v[66:67], v[56:59], off
	s_nop 1
	v_mul_f32_e32 v56, v48, v48
	v_max_f32_e32 v48, v53, v53
	v_mul_f32_e32 v53, v49, v49
	v_max_f32_e32 v49, v54, v54
	v_mul_f32_e32 v54, v50, v50
	v_max_f32_e32 v50, v55, v55
	v_max_f32_e32 v48, 0, v48
	v_max_f32_e32 v49, 0, v49
	v_max_f32_e32 v50, 0, v50
	v_max_f32_e32 v52, 0, v52
	v_mul_f32_e32 v48, v48, v48
	v_mul_f32_e32 v49, v49, v49
; __device__ __forceinline__ unsigned cvt_pk_bf16(float lo, float hi) { unsigned r; asm volatile("v_cvt_pk_bf16_f32 %0, %1, %2" : "=v"(r) : "v"(lo), "v"(hi)); return r; }
; #define PG8_WAIT_V(n) asm volatile("s_waitcnt vmcnt(" #n ")" ::: "memory")
; #define PG8_BAR __builtin_amdgcn_s_barrier()
;     __device__ __forceinline__ void operator()(const f32x4 (&acc)[2][2][4][2], const Unit& u, int wr, int wc, int fr, int fq) const {
;     ...
;             for (int m = 0; m < 4; ++m) { bf16_t* rowp = O + (size_t)(row0 + ai * HALF + m * 16) * LDF + col0;
; #pragma unroll
;                 for (int bj = 0; bj < 2; ++bj) { f32x4 v0 = acc[ai][bj][m][0], v1 = acc[ai][bj][m][1];
; #pragma unroll
;                     for (int j = 0; j < 4; ++j) { const float a = fmaxf(v0[j], 0.f), b = fmaxf(v1[j], 0.f); v0[j] = a * a; v1[j] = b * b; }
;                     u32x4 w; w.x = cvt_pk_bf16(v0[0], v0[1]); w.y = cvt_pk_bf16(v0[2], v0[3]); w.z = cvt_pk_bf16(v1[0], v1[1]); w.w = cvt_pk_bf16(v1[2], v1[3]);
;                     *(u32x4*)(rowp + bj * HALF) = w; } }
;     ...
;     PG8_WAIT_V(0);
;     if (wr == 0) PG8_BAR;
;     PG8_BAR;
	v_max_f32_e32 v51, 0, v51
	v_mul_f32_e32 v50, v50, v50
	v_mul_f32_e32 v52, v52, v52
	v_mul_f32_e32 v51, v51, v51
	v_cvt_pk_bf16_f32 v48, v52, v48
	v_cvt_pk_bf16_f32 v49, v49, v50
	v_cvt_pk_bf16_f32 v50, v56, v53
	v_max_f32_e32 v40, 0, v40
	v_cvt_pk_bf16_f32 v51, v54, v51
	global_store_dwordx4 v[66:67], v[48:51], off offset:256
	s_nop 1
	v_max_f32_e32 v41, 0, v41
	v_max_f32_e32 v42, 0, v42
	v_mul_f32_e32 v50, v40, v40
	v_max_f32_e32 v40, v45, v45
	v_add_u32_e32 v48, 0x90, v134
	v_max_f32_e32 v40, 0, v40
	v_mul_f32_e32 v45, v41, v41
	v_max_f32_e32 v41, v46, v46
	v_mul_f32_e32 v46, v42, v42
	v_max_f32_e32 v42, v47, v47
	v_mad_i64_i32 v[48:49], s[2:3], v48, s4, v[130:131]
	v_max_f32_e32 v44, 0, v44
	v_mul_f32_e32 v40, v40, v40
	v_max_f32_e32 v41, 0, v41
	v_max_f32_e32 v42, 0, v42
	v_max_f32_e32 v43, 0, v43
	v_lshl_add_u64 v[48:49], v[48:49], 0, v[64:65]
	v_mul_f32_e32 v44, v44, v44
	v_mul_f32_e32 v41, v41, v41
	v_mul_f32_e32 v42, v42, v42
	v_mul_f32_e32 v43, v43, v43
	v_cvt_pk_bf16_f32 v40, v44, v40
	v_max_f32_e32 v32, 0, v32
	v_max_f32_e32 v33, 0, v33
	v_max_f32_e32 v34, 0, v34
	v_cvt_pk_bf16_f32 v41, v41, v42
	v_cvt_pk_bf16_f32 v42, v50, v45
	v_cvt_pk_bf16_f32 v43, v46, v43
	global_store_dwordx4 v[48:49], v[40:43], off
	s_nop 1
	v_mul_f32_e32 v40, v32, v32
	v_max_f32_e32 v32, v37, v37
	v_mul_f32_e32 v37, v33, v33
	v_max_f32_e32 v33, v38, v38
	v_mul_f32_e32 v38, v34, v34
	v_max_f32_e32 v34, v39, v39
	v_max_f32_e32 v32, 0, v32
	v_max_f32_e32 v33, 0, v33
	v_max_f32_e32 v34, 0, v34
	v_max_f32_e32 v36, 0, v36
	v_mul_f32_e32 v32, v32, v32
	v_mul_f32_e32 v33, v33, v33
	v_max_f32_e32 v35, 0, v35
	v_mul_f32_e32 v34, v34, v34
	v_mul_f32_e32 v36, v36, v36
	v_mul_f32_e32 v35, v35, v35
	v_cvt_pk_bf16_f32 v32, v36, v32
	v_cvt_pk_bf16_f32 v33, v33, v34
	v_cvt_pk_bf16_f32 v34, v40, v37
	v_max_f32_e32 v24, 0, v24
	v_cvt_pk_bf16_f32 v35, v38, v35
	global_store_dwordx4 v[48:49], v[32:35], off offset:256
	s_nop 1
	v_max_f32_e32 v25, 0, v25
	v_max_f32_e32 v26, 0, v26
	v_mul_f32_e32 v34, v24, v24
	v_max_f32_e32 v24, v29, v29
	v_add_u32_e32 v32, 0xa0, v134
	v_max_f32_e32 v24, 0, v24
	v_mul_f32_e32 v29, v25, v25
	v_max_f32_e32 v25, v30, v30
	v_mul_f32_e32 v30, v26, v26
	v_max_f32_e32 v26, v31, v31
	v_mad_i64_i32 v[32:33], s[2:3], v32, s4, v[130:131]
	v_max_f32_e32 v28, 0, v28
	v_mul_f32_e32 v24, v24, v24
	v_max_f32_e32 v25, 0, v25
	v_max_f32_e32 v26, 0, v26
	v_max_f32_e32 v27, 0, v27
	v_lshl_add_u64 v[32:33], v[32:33], 0, v[64:65]
	v_mul_f32_e32 v28, v28, v28
	v_mul_f32_e32 v25, v25, v25
	v_mul_f32_e32 v26, v26, v26
	v_mul_f32_e32 v27, v27, v27
	v_cvt_pk_bf16_f32 v24, v28, v24
	v_max_f32_e32 v16, 0, v16
	v_max_f32_e32 v17, 0, v17
	v_max_f32_e32 v18, 0, v18
	v_cvt_pk_bf16_f32 v25, v25, v26
	v_cvt_pk_bf16_f32 v26, v34, v29
	v_cvt_pk_bf16_f32 v27, v30, v27
	global_store_dwordx4 v[32:33], v[24:27], off
	s_nop 1
	v_mul_f32_e32 v24, v16, v16
	v_max_f32_e32 v16, v21, v21
	v_mul_f32_e32 v21, v17, v17
	v_max_f32_e32 v17, v22, v22
	v_mul_f32_e32 v22, v18, v18
	v_max_f32_e32 v18, v23, v23
	v_max_f32_e32 v16, 0, v16
	v_max_f32_e32 v17, 0, v17
	v_max_f32_e32 v18, 0, v18
	v_max_f32_e32 v20, 0, v20
	v_mul_f32_e32 v16, v16, v16
	v_mul_f32_e32 v17, v17, v17
	v_max_f32_e32 v19, 0, v19
	v_mul_f32_e32 v18, v18, v18
	v_mul_f32_e32 v20, v20, v20
	v_mul_f32_e32 v19, v19, v19
	v_cvt_pk_bf16_f32 v16, v20, v16
	v_cvt_pk_bf16_f32 v17, v17, v18
	v_cvt_pk_bf16_f32 v18, v24, v21
	v_max_f32_e32 v8, 0, v8
	v_cvt_pk_bf16_f32 v19, v22, v19
	global_store_dwordx4 v[32:33], v[16:19], off offset:256
	s_nop 1
	v_max_f32_e32 v9, 0, v9
	v_max_f32_e32 v10, 0, v10
	v_mul_f32_e32 v18, v8, v8
	v_max_f32_e32 v8, v13, v13
	v_add_u32_e32 v16, 0xb0, v134
	v_max_f32_e32 v8, 0, v8
	v_mul_f32_e32 v13, v9, v9
	v_max_f32_e32 v9, v14, v14
	v_mul_f32_e32 v14, v10, v10
	v_max_f32_e32 v10, v15, v15
	v_mad_i64_i32 v[16:17], s[2:3], v16, s4, v[130:131]
	v_max_f32_e32 v12, 0, v12
	v_mul_f32_e32 v8, v8, v8
	v_max_f32_e32 v9, 0, v9
	v_max_f32_e32 v10, 0, v10
	v_max_f32_e32 v11, 0, v11
	v_lshl_add_u64 v[16:17], v[16:17], 0, v[64:65]
	v_mul_f32_e32 v12, v12, v12
	v_mul_f32_e32 v9, v9, v9
	v_mul_f32_e32 v10, v10, v10
	v_mul_f32_e32 v11, v11, v11
	v_cvt_pk_bf16_f32 v8, v12, v8
	v_max_f32_e32 v0, 0, v0
	v_max_f32_e32 v1, 0, v1
	v_max_f32_e32 v2, 0, v2
	v_cvt_pk_bf16_f32 v9, v9, v10
	v_cvt_pk_bf16_f32 v10, v18, v13
	v_cvt_pk_bf16_f32 v11, v14, v11
	global_store_dwordx4 v[16:17], v[8:11], off
	s_nop 1
	v_mul_f32_e32 v8, v0, v0
	v_max_f32_e32 v0, v5, v5
	v_mul_f32_e32 v5, v1, v1
	v_max_f32_e32 v1, v6, v6
	v_mul_f32_e32 v6, v2, v2
	v_max_f32_e32 v2, v7, v7
	v_max_f32_e32 v0, 0, v0
	v_max_f32_e32 v1, 0, v1
	v_max_f32_e32 v2, 0, v2
	v_max_f32_e32 v3, 0, v3
	v_max_f32_e32 v4, 0, v4
	v_mul_f32_e32 v0, v0, v0
	v_mul_f32_e32 v1, v1, v1
	v_mul_f32_e32 v2, v2, v2
	v_mul_f32_e32 v3, v3, v3
	v_mul_f32_e32 v4, v4, v4
	v_cvt_pk_bf16_f32 v0, v4, v0
	v_cvt_pk_bf16_f32 v1, v1, v2
	v_cvt_pk_bf16_f32 v2, v8, v5
	v_cvt_pk_bf16_f32 v3, v6, v3
	global_store_dwordx4 v[16:17], v[0:3], off offset:256
	s_nop 1
	s_waitcnt vmcnt(0)
	s_cmpk_lt_u32 s14, 0x100
	s_movk_i32 s27, 0x1000
	s_cbranch_scc0 .LBB0_149
	s_barrier

; #define PG8_STAGE(bufoff, gbase, voff) do { _Pragma("unroll") for (int _i = 0; _i < 2; ++_i) \
;         __builtin_amdgcn_global_load_lds((const unsigned*)((const char*)(gbase) + (voff)[_i]), (LAS unsigned*)(lds + (bufoff) + ldsw + _i * 8192), 16, 0, 0); } while (0)
; #define PG8_LDA(dst, b, h) do { _Pragma("unroll") for (int m = 0; m < 4; ++m) _Pragma("unroll") for (int k = 0; k < 2; ++k) dst[m][k] = *(const LAS bf16x8*)(lds + PG8_SA(b, h) + aoff + m * 2048 + k * 1024); } while (0)
; #define PG8_LDB(dst, b, h) do { _Pragma("unroll") for (int n = 0; n < 2; ++n) _Pragma("unroll") for (int k = 0; k < 2; ++k) dst[n][k] = *(const LAS bf16x8*)(lds + PG8_SB(b, h) + boff + n * 2048 + k * 1024); } while (0)
; #define PG8_MMA(ai, bj, At, Bt) do { __builtin_amdgcn_s_setprio(1); _Pragma("unroll") for (int m = 0; m < 4; ++m) _Pragma("unroll") for (int n = 0; n < 2; ++n) _Pragma("unroll") for (int k = 0; k < 2; ++k) \
;         acc[ai][bj][m][n] = __builtin_amdgcn_mfma_f32_16x16x32_bf16(Bt[n][k], At[m][k], acc[ai][bj][m][n], 0, 0, 0); __builtin_amdgcn_s_setprio(0); } while (0)
; #define PG8_WAIT_L(n) asm volatile("s_waitcnt lgkmcnt(" #n ")" ::: "memory")
; #define PG8_BAR __builtin_amdgcn_s_barrier()
; #define PG8_SCHED __builtin_amdgcn_sched_barrier(0)
;     ...
;             const char* a1 = cA + (size_t)(t + 1) * kstep;
;             const char* a2 = last ? nA : cA + (size_t)(t + 2) * kstep; const char* b2 = last ? nB : cB + (size_t)(t + 2) * kstep;
;             const char* a3 = a2 + kstep; const char* b3 = b2 + kstep;
;             PG8_LDB(B0, 0, 0); PG8_SCHED; PG8_LDA(At, 0, 0); PG8_STAGE(PG8_SA(1, 1), a1 + hstep, voffA);
;             PG8_WAIT_L(8); PG8_BAR; PG8_WAIT_L(0); PG8_MMA(0, 0, At, B0); PG8_BAR; PG8_SCHED;
;             PG8_LDB(B1, 0, 1); PG8_STAGE(PG8_SB(0, 0), b2, voffB);
;             PG8_BAR; PG8_WAIT_L(0); PG8_MMA(0, 1, At, B1); PG8_BAR;
;             PG8_LDA(At, 0, 1); PG8_STAGE(PG8_SA(0, 0), a2, voffA);
;             PG8_BAR; PG8_WAIT_L(0); PG8_MMA(1, 0, At, B0); PG8_BAR; PG8_SCHED;
.LBB0_475:
	s_or_b32 s94, s12, 1
	s_add_i32 s12, s12, 2
	s_mov_b32 s13, s95
	s_lshl_b64 s[2:3], s[12:13], 7
	s_add_u32 s7, s24, s2
	s_addc_u32 s13, s25, s3
	s_and_b64 vcc, s[44:45], exec
	s_cselect_b32 vcc_hi, s85, s13
	s_cselect_b32 vcc_lo, s84, s7
	s_add_u32 s7, s42, s2
	s_addc_u32 s13, s43, s3
	s_add_i32 s35, 0, 0x10000
	v_add_u32_e32 v64, s35, v220
	ds_read_b128 v[134:137], v64
	ds_read_b128 v[138:141], v64 offset:1024
	ds_read_b128 v[142:145], v64 offset:2048
	ds_read_b128 v[146:149], v64 offset:3072
	s_and_b64 s[2:3], s[44:45], exec
	s_cselect_b32 s45, s9, s13
	s_cselect_b32 s44, s8, s7
	s_lshl_b64 s[2:3], s[94:95], 7
	s_add_u32 s2, s47, s2
	s_addc_u32 s3, s89, s3
	v_lshl_add_u64 v[182:183], s[2:3], 0, v[130:131]
	s_add_i32 m0, s19, 0xc000
	ds_read_b128 v[150:153], v229
	ds_read_b128 v[154:157], v229 offset:1024
	ds_read_b128 v[158:161], v229 offset:2048
	ds_read_b128 v[162:165], v229 offset:3072
	ds_read_b128 v[166:169], v229 offset:4096
	ds_read_b128 v[170:173], v229 offset:5120
	ds_read_b128 v[174:177], v229 offset:6144
	ds_read_b128 v[178:181], v229 offset:7168
	global_load_lds_dwordx4 v[182:183], off
	v_lshl_add_u64 v[182:183], s[2:3], 0, v[132:133]
	s_add_i32 m0, s19, 0xe000
	s_nop 0
	global_load_lds_dwordx4 v[182:183], off
	s_waitcnt lgkmcnt(0)
	s_barrier
	v_mfma_f32_16x16x32_bf16 v[118:121], v[134:137], v[150:153], v[118:121]
	v_mfma_f32_16x16x32_bf16 v[114:117], v[142:145], v[150:153], v[114:117]
	v_mfma_f32_16x16x32_bf16 v[102:105], v[134:137], v[158:161], v[102:105]
	v_mfma_f32_16x16x32_bf16 v[98:101], v[142:145], v[158:161], v[98:101]
	v_mfma_f32_16x16x32_bf16 v[86:89], v[134:137], v[166:169], v[86:89]
	v_mfma_f32_16x16x32_bf16 v[82:85], v[142:145], v[166:169], v[82:85]
	v_mfma_f32_16x16x32_bf16 v[70:73], v[134:137], v[174:177], v[70:73]
	v_mfma_f32_16x16x32_bf16 v[66:69], v[142:145], v[174:177], v[66:69]
	v_mfma_f32_16x16x32_bf16 v[118:121], v[138:141], v[154:157], v[118:121]
	v_mfma_f32_16x16x32_bf16 v[114:117], v[146:149], v[154:157], v[114:117]
	v_mfma_f32_16x16x32_bf16 v[102:105], v[138:141], v[162:165], v[102:105]
	v_mfma_f32_16x16x32_bf16 v[98:101], v[146:149], v[162:165], v[98:101]
	v_mfma_f32_16x16x32_bf16 v[86:89], v[138:141], v[170:173], v[86:89]
	v_mfma_f32_16x16x32_bf16 v[82:85], v[146:149], v[170:173], v[82:85]
	v_mfma_f32_16x16x32_bf16 v[70:73], v[138:141], v[178:181], v[70:73]
	v_mfma_f32_16x16x32_bf16 v[66:69], v[146:149], v[178:181], v[66:69]
	s_barrier
	s_add_i32 s7, 0, 0x14000
	s_add_i32 s2, s35, s18
	v_add_u32_e32 v64, s7, v220
	v_lshl_add_u64 v[198:199], s[44:45], 0, v[130:131]
	s_mov_b32 m0, s2
	ds_read_b128 v[182:185], v64
	ds_read_b128 v[186:189], v64 offset:1024
	ds_read_b128 v[190:193], v64 offset:2048
	ds_read_b128 v[194:197], v64 offset:3072
	global_load_lds_dwordx4 v[198:199], off
	v_lshl_add_u64 v[246:247], s[44:45], 0, v[132:133]
	s_add_i32 m0, s2, 0x2000
	s_nop 0
	global_load_lds_dwordx4 v[246:247], off
	s_waitcnt lgkmcnt(0)
	s_barrier
	v_mfma_f32_16x16x32_bf16 v[126:129], v[182:185], v[150:153], v[126:129]
	v_mfma_f32_16x16x32_bf16 v[122:125], v[190:193], v[150:153], v[122:125]
	v_mfma_f32_16x16x32_bf16 v[110:113], v[182:185], v[158:161], v[110:113]
	v_mfma_f32_16x16x32_bf16 v[106:109], v[190:193], v[158:161], v[106:109]
	v_mfma_f32_16x16x32_bf16 v[94:97], v[182:185], v[166:169], v[94:97]
	v_mfma_f32_16x16x32_bf16 v[90:93], v[190:193], v[166:169], v[90:93]
	v_mfma_f32_16x16x32_bf16 v[78:81], v[182:185], v[174:177], v[78:81]
	v_mfma_f32_16x16x32_bf16 v[74:77], v[190:193], v[174:177], v[74:77]
	v_mfma_f32_16x16x32_bf16 v[126:129], v[186:189], v[154:157], v[126:129]
	v_mfma_f32_16x16x32_bf16 v[122:125], v[194:197], v[154:157], v[122:125]
	v_mfma_f32_16x16x32_bf16 v[110:113], v[186:189], v[162:165], v[110:113]
	v_mfma_f32_16x16x32_bf16 v[106:109], v[194:197], v[162:165], v[106:109]
	v_mfma_f32_16x16x32_bf16 v[94:97], v[186:189], v[170:173], v[94:97]
	v_mfma_f32_16x16x32_bf16 v[90:93], v[194:197], v[170:173], v[90:93]
	v_mfma_f32_16x16x32_bf16 v[78:81], v[186:189], v[178:181], v[78:81]
	v_mfma_f32_16x16x32_bf16 v[74:77], v[194:197], v[178:181], v[74:77]
	s_mov_b32 m0, s19
	v_lshl_add_u64 v[212:213], vcc, 0, v[130:131]
	s_barrier
	ds_read_b128 v[150:153], v229 offset:16384
	ds_read_b128 v[154:157], v229 offset:17408
	ds_read_b128 v[158:161], v229 offset:18432
	ds_read_b128 v[162:165], v229 offset:19456
	ds_read_b128 v[166:169], v229 offset:20480
	ds_read_b128 v[170:173], v229 offset:21504
	ds_read_b128 v[174:177], v229 offset:22528
	ds_read_b128 v[178:181], v229 offset:23552
	global_load_lds_dwordx4 v[212:213], off
	v_lshl_add_u64 v[208:209], vcc, 0, v[132:133]
	s_mov_b32 m0, s21
	s_nop 0
	global_load_lds_dwordx4 v[208:209], off
	s_waitcnt lgkmcnt(0)
	s_barrier
	v_mfma_f32_16x16x32_bf16 v[52:55], v[134:137], v[150:153], v[52:55]
	v_mfma_f32_16x16x32_bf16 v[48:51], v[142:145], v[150:153], v[48:51]
	v_mfma_f32_16x16x32_bf16 v[36:39], v[134:137], v[158:161], v[36:39]
	v_mfma_f32_16x16x32_bf16 v[32:35], v[142:145], v[158:161], v[32:35]
	v_mfma_f32_16x16x32_bf16 v[20:23], v[134:137], v[166:169], v[20:23]
	v_mfma_f32_16x16x32_bf16 v[16:19], v[142:145], v[166:169], v[16:19]
	v_mfma_f32_16x16x32_bf16 v[4:7], v[134:137], v[174:177], v[4:7]
	v_mfma_f32_16x16x32_bf16 v[0:3], v[142:145], v[174:177], v[0:3]
	v_mfma_f32_16x16x32_bf16 v[52:55], v[138:141], v[154:157], v[52:55]
	v_mfma_f32_16x16x32_bf16 v[48:51], v[146:149], v[154:157], v[48:51]
	v_mfma_f32_16x16x32_bf16 v[36:39], v[138:141], v[162:165], v[36:39]
	v_mfma_f32_16x16x32_bf16 v[32:35], v[146:149], v[162:165], v[32:35]
	v_mfma_f32_16x16x32_bf16 v[20:23], v[138:141], v[170:173], v[20:23]
	v_mfma_f32_16x16x32_bf16 v[16:19], v[146:149], v[170:173], v[16:19]
	v_mfma_f32_16x16x32_bf16 v[4:7], v[138:141], v[178:181], v[4:7]
	v_mfma_f32_16x16x32_bf16 v[0:3], v[146:149], v[178:181], v[0:3]
	s_barrier
; #define PG8_STAGE(bufoff, gbase, voff) do { _Pragma("unroll") for (int _i = 0; _i < 2; ++_i) \
;         __builtin_amdgcn_global_load_lds((const unsigned*)((const char*)(gbase) + (voff)[_i]), (LAS unsigned*)(lds + (bufoff) + ldsw + _i * 8192), 16, 0, 0); } while (0)
; #define PG8_LDA(dst, b, h) do { _Pragma("unroll") for (int m = 0; m < 4; ++m) _Pragma("unroll") for (int k = 0; k < 2; ++k) dst[m][k] = *(const LAS bf16x8*)(lds + PG8_SA(b, h) + aoff + m * 2048 + k * 1024); } while (0)
; #define PG8_LDB(dst, b, h) do { _Pragma("unroll") for (int n = 0; n < 2; ++n) _Pragma("unroll") for (int k = 0; k < 2; ++k) dst[n][k] = *(const LAS bf16x8*)(lds + PG8_SB(b, h) + boff + n * 2048 + k * 1024); } while (0)
; #define PG8_MMA(ai, bj, At, Bt) do { __builtin_amdgcn_s_setprio(1); _Pragma("unroll") for (int m = 0; m < 4; ++m) _Pragma("unroll") for (int n = 0; n < 2; ++n) _Pragma("unroll") for (int k = 0; k < 2; ++k) \
;         acc[ai][bj][m][n] = __builtin_amdgcn_mfma_f32_16x16x32_bf16(Bt[n][k], At[m][k], acc[ai][bj][m][n], 0, 0, 0); __builtin_amdgcn_s_setprio(0); } while (0)
; #define PG8_WAIT_V(n) asm volatile("s_waitcnt vmcnt(" #n ")" ::: "memory")
; #define PG8_WAIT_L(n) asm volatile("s_waitcnt lgkmcnt(" #n ")" ::: "memory")
; #define PG8_BAR __builtin_amdgcn_s_barrier()
; #define PG8_SCHED __builtin_amdgcn_sched_barrier(0)
;     ...
;             PG8_STAGE(PG8_SB(0, 1), b2 + hstep, voffB);
;             PG8_WAIT_V(6); PG8_BAR; PG8_MMA(1, 1, At, B1); PG8_BAR;
;             PG8_LDB(B0, 1, 0); PG8_SCHED; PG8_LDA(At, 1, 0); PG8_STAGE(PG8_SA(0, 1), a2 + hstep, voffA);
;             PG8_WAIT_L(8); PG8_BAR; PG8_WAIT_L(0); PG8_MMA(0, 0, At, B0); PG8_BAR; PG8_SCHED;
;             PG8_LDB(B1, 1, 1); PG8_STAGE(PG8_SB(1, 0), b3, voffB);
;             PG8_BAR; PG8_WAIT_L(0); PG8_MMA(0, 1, At, B1); PG8_BAR;
;             PG8_LDA(At, 1, 1); PG8_STAGE(PG8_SA(1, 0), a3, voffA);
;             PG8_BAR; PG8_WAIT_L(0); PG8_MMA(1, 0, At, B0); PG8_BAR; PG8_SCHED;
	s_add_u32 s2, s44, s82
	s_addc_u32 s3, s45, 0
	s_add_i32 s7, s7, s18
	v_lshl_add_u64 v[210:211], s[2:3], 0, v[130:131]
	s_mov_b32 m0, s7
	v_lshl_add_u64 v[214:215], s[2:3], 0, v[132:133]
	global_load_lds_dwordx4 v[210:211], off
	s_add_i32 m0, s7, 0x2000
	s_nop 0
	global_load_lds_dwordx4 v[214:215], off
	s_waitcnt vmcnt(6)
	s_barrier
	v_mfma_f32_16x16x32_bf16 v[60:63], v[182:185], v[150:153], v[60:63]
	v_mfma_f32_16x16x32_bf16 v[56:59], v[190:193], v[150:153], v[56:59]
	v_mfma_f32_16x16x32_bf16 v[44:47], v[182:185], v[158:161], v[44:47]
	v_mfma_f32_16x16x32_bf16 v[40:43], v[190:193], v[158:161], v[40:43]
	v_mfma_f32_16x16x32_bf16 v[28:31], v[182:185], v[166:169], v[28:31]
	v_mfma_f32_16x16x32_bf16 v[24:27], v[190:193], v[166:169], v[24:27]
	v_mfma_f32_16x16x32_bf16 v[12:15], v[182:185], v[174:177], v[12:15]
	v_mfma_f32_16x16x32_bf16 v[8:11], v[190:193], v[174:177], v[8:11]
	v_mfma_f32_16x16x32_bf16 v[60:63], v[186:189], v[154:157], v[60:63]
	v_mfma_f32_16x16x32_bf16 v[56:59], v[194:197], v[154:157], v[56:59]
	v_mfma_f32_16x16x32_bf16 v[44:47], v[186:189], v[162:165], v[44:47]
	v_mfma_f32_16x16x32_bf16 v[40:43], v[194:197], v[162:165], v[40:43]
	v_mfma_f32_16x16x32_bf16 v[28:31], v[186:189], v[170:173], v[28:31]
	v_mfma_f32_16x16x32_bf16 v[24:27], v[194:197], v[170:173], v[24:27]
	v_mfma_f32_16x16x32_bf16 v[12:15], v[186:189], v[178:181], v[12:15]
	v_mfma_f32_16x16x32_bf16 v[8:11], v[194:197], v[178:181], v[8:11]
	s_add_i32 s7, 0, 0x18000
	v_add_u32_e32 v64, s7, v220
	s_barrier
	ds_read_b128 v[134:137], v64
	ds_read_b128 v[138:141], v64 offset:1024
	ds_read_b128 v[142:145], v64 offset:2048
	ds_read_b128 v[146:149], v64 offset:3072
	s_add_u32 s2, vcc_lo, s82
	s_addc_u32 s3, vcc_hi, 0
	s_mov_b32 m0, s31
	v_lshl_add_u64 v[182:183], s[2:3], 0, v[130:131]
	ds_read_b128 v[150:153], v229 offset:32768
	ds_read_b128 v[154:157], v229 offset:33792
	ds_read_b128 v[158:161], v229 offset:34816
	ds_read_b128 v[162:165], v229 offset:35840
	ds_read_b128 v[166:169], v229 offset:36864
	ds_read_b128 v[170:173], v229 offset:37888
	ds_read_b128 v[174:177], v229 offset:38912
	ds_read_b128 v[178:181], v229 offset:39936
	global_load_lds_dwordx4 v[182:183], off
	v_lshl_add_u64 v[182:183], s[2:3], 0, v[132:133]
	s_mov_b32 m0, s83
	s_nop 0
	global_load_lds_dwordx4 v[182:183], off
	s_waitcnt lgkmcnt(0)
	s_barrier
	v_mfma_f32_16x16x32_bf16 v[118:121], v[134:137], v[150:153], v[118:121]
	v_mfma_f32_16x16x32_bf16 v[114:117], v[142:145], v[150:153], v[114:117]
	v_mfma_f32_16x16x32_bf16 v[102:105], v[134:137], v[158:161], v[102:105]
	v_mfma_f32_16x16x32_bf16 v[98:101], v[142:145], v[158:161], v[98:101]
	v_mfma_f32_16x16x32_bf16 v[86:89], v[134:137], v[166:169], v[86:89]
	v_mfma_f32_16x16x32_bf16 v[82:85], v[142:145], v[166:169], v[82:85]
	v_mfma_f32_16x16x32_bf16 v[70:73], v[134:137], v[174:177], v[70:73]
	v_mfma_f32_16x16x32_bf16 v[66:69], v[142:145], v[174:177], v[66:69]
	v_mfma_f32_16x16x32_bf16 v[118:121], v[138:141], v[154:157], v[118:121]
	v_mfma_f32_16x16x32_bf16 v[114:117], v[146:149], v[154:157], v[114:117]
	v_mfma_f32_16x16x32_bf16 v[102:105], v[138:141], v[162:165], v[102:105]
	v_mfma_f32_16x16x32_bf16 v[98:101], v[146:149], v[162:165], v[98:101]
	v_mfma_f32_16x16x32_bf16 v[86:89], v[138:141], v[170:173], v[86:89]
	v_mfma_f32_16x16x32_bf16 v[82:85], v[146:149], v[170:173], v[82:85]
	v_mfma_f32_16x16x32_bf16 v[70:73], v[138:141], v[178:181], v[70:73]
	v_mfma_f32_16x16x32_bf16 v[66:69], v[146:149], v[178:181], v[66:69]
	s_barrier
	s_add_i32 s2, 0, 0x1c000
	s_add_i32 s3, s7, s18
	v_add_u32_e32 v64, s2, v220
	v_lshl_add_u64 v[198:199], v[198:199], 0, s[16:17]
	s_mov_b32 m0, s3
	ds_read_b128 v[182:185], v64
	ds_read_b128 v[186:189], v64 offset:1024
	ds_read_b128 v[190:193], v64 offset:2048
	ds_read_b128 v[194:197], v64 offset:3072
	global_load_lds_dwordx4 v[198:199], off
	v_lshl_add_u64 v[198:199], v[246:247], 0, s[16:17]
	s_add_i32 m0, s3, 0x2000
	s_nop 0
	global_load_lds_dwordx4 v[198:199], off
	s_waitcnt lgkmcnt(0)
	s_barrier
; #define PG8_STAGE(bufoff, gbase, voff) do { _Pragma("unroll") for (int _i = 0; _i < 2; ++_i) \
;         __builtin_amdgcn_global_load_lds((const unsigned*)((const char*)(gbase) + (voff)[_i]), (LAS unsigned*)(lds + (bufoff) + ldsw + _i * 8192), 16, 0, 0); } while (0)
; #define PG8_MMA(ai, bj, At, Bt) do { __builtin_amdgcn_s_setprio(1); _Pragma("unroll") for (int m = 0; m < 4; ++m) _Pragma("unroll") for (int n = 0; n < 2; ++n) _Pragma("unroll") for (int k = 0; k < 2; ++k) \
;         acc[ai][bj][m][n] = __builtin_amdgcn_mfma_f32_16x16x32_bf16(Bt[n][k], At[m][k], acc[ai][bj][m][n], 0, 0, 0); __builtin_amdgcn_s_setprio(0); } while (0)
; #define PG8_WAIT_V(n) asm volatile("s_waitcnt vmcnt(" #n ")" ::: "memory")
; #define PG8_WAIT_L(n) asm volatile("s_waitcnt lgkmcnt(" #n ")" ::: "memory")
; #define PG8_BAR __builtin_amdgcn_s_barrier()
; #define PG8_SCHED __builtin_amdgcn_sched_barrier(0)
;     ...
;             PG8_BAR; PG8_WAIT_L(0); PG8_MMA(1, 0, At, B0); PG8_BAR; PG8_SCHED;
;             PG8_STAGE(PG8_SB(1, 1), b3 + hstep, voffB);
;             PG8_WAIT_V(6); PG8_BAR; PG8_MMA(1, 1, At, B1); PG8_BAR;
;         }
	v_mfma_f32_16x16x32_bf16 v[126:129], v[182:185], v[150:153], v[126:129]
	v_mfma_f32_16x16x32_bf16 v[122:125], v[190:193], v[150:153], v[122:125]
	v_mfma_f32_16x16x32_bf16 v[110:113], v[182:185], v[158:161], v[110:113]
	v_mfma_f32_16x16x32_bf16 v[106:109], v[190:193], v[158:161], v[106:109]
	v_mfma_f32_16x16x32_bf16 v[94:97], v[182:185], v[166:169], v[94:97]
	v_mfma_f32_16x16x32_bf16 v[90:93], v[190:193], v[166:169], v[90:93]
	v_mfma_f32_16x16x32_bf16 v[78:81], v[182:185], v[174:177], v[78:81]
	v_mfma_f32_16x16x32_bf16 v[74:77], v[190:193], v[174:177], v[74:77]
	v_mfma_f32_16x16x32_bf16 v[126:129], v[186:189], v[154:157], v[126:129]
	v_mfma_f32_16x16x32_bf16 v[122:125], v[194:197], v[154:157], v[122:125]
	v_mfma_f32_16x16x32_bf16 v[110:113], v[186:189], v[162:165], v[110:113]
	v_mfma_f32_16x16x32_bf16 v[106:109], v[194:197], v[162:165], v[106:109]
	v_mfma_f32_16x16x32_bf16 v[94:97], v[186:189], v[170:173], v[94:97]
	v_mfma_f32_16x16x32_bf16 v[90:93], v[194:197], v[170:173], v[90:93]
	v_mfma_f32_16x16x32_bf16 v[78:81], v[186:189], v[178:181], v[78:81]
	v_mfma_f32_16x16x32_bf16 v[74:77], v[194:197], v[178:181], v[74:77]
	s_mov_b32 m0, s36
	v_lshl_add_u64 v[198:199], v[212:213], 0, s[16:17]
	s_barrier
	ds_read_b128 v[150:153], v229 offset:49152
	ds_read_b128 v[154:157], v229 offset:50176
	ds_read_b128 v[158:161], v229 offset:51200
	ds_read_b128 v[162:165], v229 offset:52224
	ds_read_b128 v[166:169], v229 offset:53248
	ds_read_b128 v[170:173], v229 offset:54272
	ds_read_b128 v[174:177], v229 offset:55296
	ds_read_b128 v[178:181], v229 offset:56320
	global_load_lds_dwordx4 v[198:199], off
	v_lshl_add_u64 v[198:199], v[208:209], 0, s[16:17]
	s_mov_b32 m0, s37
	s_nop 0
	global_load_lds_dwordx4 v[198:199], off
	s_waitcnt lgkmcnt(0)
	s_barrier
	v_mfma_f32_16x16x32_bf16 v[52:55], v[134:137], v[150:153], v[52:55]
	v_mfma_f32_16x16x32_bf16 v[48:51], v[142:145], v[150:153], v[48:51]
	v_mfma_f32_16x16x32_bf16 v[36:39], v[134:137], v[158:161], v[36:39]
	v_mfma_f32_16x16x32_bf16 v[32:35], v[142:145], v[158:161], v[32:35]
	v_mfma_f32_16x16x32_bf16 v[20:23], v[134:137], v[166:169], v[20:23]
	v_mfma_f32_16x16x32_bf16 v[16:19], v[142:145], v[166:169], v[16:19]
	v_mfma_f32_16x16x32_bf16 v[4:7], v[134:137], v[174:177], v[4:7]
	v_mfma_f32_16x16x32_bf16 v[0:3], v[142:145], v[174:177], v[0:3]
	v_mfma_f32_16x16x32_bf16 v[52:55], v[138:141], v[154:157], v[52:55]
	v_mfma_f32_16x16x32_bf16 v[48:51], v[146:149], v[154:157], v[48:51]
	v_mfma_f32_16x16x32_bf16 v[36:39], v[138:141], v[162:165], v[36:39]
	v_mfma_f32_16x16x32_bf16 v[32:35], v[146:149], v[162:165], v[32:35]
	v_mfma_f32_16x16x32_bf16 v[20:23], v[138:141], v[170:173], v[20:23]
	v_mfma_f32_16x16x32_bf16 v[16:19], v[146:149], v[170:173], v[16:19]
	v_mfma_f32_16x16x32_bf16 v[4:7], v[138:141], v[178:181], v[4:7]
	v_mfma_f32_16x16x32_bf16 v[0:3], v[146:149], v[178:181], v[0:3]
	s_barrier
	s_add_i32 s2, s2, s18
	v_lshl_add_u64 v[134:135], v[210:211], 0, s[16:17]
	s_mov_b32 m0, s2
	s_nop 0
	global_load_lds_dwordx4 v[134:135], off
	v_lshl_add_u64 v[134:135], v[214:215], 0, s[16:17]
	s_add_i32 m0, s2, 0x2000
	s_nop 0
	global_load_lds_dwordx4 v[134:135], off
	s_waitcnt vmcnt(6)
	s_barrier
	v_mfma_f32_16x16x32_bf16 v[60:63], v[182:185], v[150:153], v[60:63]
	v_mfma_f32_16x16x32_bf16 v[56:59], v[190:193], v[150:153], v[56:59]
	v_mfma_f32_16x16x32_bf16 v[44:47], v[182:185], v[158:161], v[44:47]
	v_mfma_f32_16x16x32_bf16 v[40:43], v[190:193], v[158:161], v[40:43]
	v_mfma_f32_16x16x32_bf16 v[28:31], v[182:185], v[166:169], v[28:31]
	v_mfma_f32_16x16x32_bf16 v[24:27], v[190:193], v[166:169], v[24:27]
	v_mfma_f32_16x16x32_bf16 v[12:15], v[182:185], v[174:177], v[12:15]
	v_mfma_f32_16x16x32_bf16 v[8:11], v[190:193], v[174:177], v[8:11]
	v_mfma_f32_16x16x32_bf16 v[60:63], v[186:189], v[154:157], v[60:63]
	v_mfma_f32_16x16x32_bf16 v[56:59], v[194:197], v[154:157], v[56:59]
	v_mfma_f32_16x16x32_bf16 v[44:47], v[186:189], v[162:165], v[44:47]
	v_mfma_f32_16x16x32_bf16 v[40:43], v[194:197], v[162:165], v[40:43]
	v_mfma_f32_16x16x32_bf16 v[28:31], v[186:189], v[170:173], v[28:31]
	v_mfma_f32_16x16x32_bf16 v[24:27], v[194:197], v[170:173], v[24:27]
	v_mfma_f32_16x16x32_bf16 v[12:15], v[186:189], v[178:181], v[12:15]
	v_mfma_f32_16x16x32_bf16 v[8:11], v[194:197], v[178:181], v[8:11]
	s_cmp_ge_u32 s12, s6
	s_barrier
	s_cbranch_scc1 .LBB0_482

; #define PG8_STAGE(bufoff, gbase, voff) do { _Pragma("unroll") for (int _i = 0; _i < 2; ++_i) \
;         __builtin_amdgcn_global_load_lds((const unsigned*)((const char*)(gbase) + (voff)[_i]), (LAS unsigned*)(lds + (bufoff) + ldsw + _i * 8192), 16, 0, 0); } while (0)
; #define PG8_LDA(dst, b, h) do { _Pragma("unroll") for (int m = 0; m < 4; ++m) _Pragma("unroll") for (int k = 0; k < 2; ++k) dst[m][k] = *(const LAS bf16x8*)(lds + PG8_SA(b, h) + aoff + m * 2048 + k * 1024); } while (0)
; #define PG8_LDB(dst, b, h) do { _Pragma("unroll") for (int n = 0; n < 2; ++n) _Pragma("unroll") for (int k = 0; k < 2; ++k) dst[n][k] = *(const LAS bf16x8*)(lds + PG8_SB(b, h) + boff + n * 2048 + k * 1024); } while (0)
; #define PG8_MMA(ai, bj, At, Bt) do { __builtin_amdgcn_s_setprio(1); _Pragma("unroll") for (int m = 0; m < 4; ++m) _Pragma("unroll") for (int n = 0; n < 2; ++n) _Pragma("unroll") for (int k = 0; k < 2; ++k) \
;         acc[ai][bj][m][n] = __builtin_amdgcn_mfma_f32_16x16x32_bf16(Bt[n][k], At[m][k], acc[ai][bj][m][n], 0, 0, 0); __builtin_amdgcn_s_setprio(0); } while (0)
; #define PG8_WAIT_L(n) asm volatile("s_waitcnt lgkmcnt(" #n ")" ::: "memory")
; #define PG8_BAR __builtin_amdgcn_s_barrier()
; #define PG8_SCHED __builtin_amdgcn_sched_barrier(0)
;     ...
;             const char* a1 = cA + (size_t)(t + 1) * kstep;
;             const char* a2 = last ? nA : cA + (size_t)(t + 2) * kstep; const char* b2 = last ? nB : cB + (size_t)(t + 2) * kstep;
;             const char* a3 = a2 + kstep; const char* b3 = b2 + kstep;
;             PG8_LDB(B0, 0, 0); PG8_SCHED; PG8_LDA(At, 0, 0); PG8_STAGE(PG8_SA(1, 1), a1 + hstep, voffA);
;             PG8_WAIT_L(8); PG8_BAR; PG8_WAIT_L(0); PG8_MMA(0, 0, At, B0); PG8_BAR; PG8_SCHED;
;             PG8_LDB(B1, 0, 1); PG8_STAGE(PG8_SB(0, 0), b2, voffB);
;             PG8_BAR; PG8_WAIT_L(0); PG8_MMA(0, 1, At, B1); PG8_BAR;
;             PG8_LDA(At, 0, 1); PG8_STAGE(PG8_SA(0, 0), a2, voffA);
;             PG8_BAR; PG8_WAIT_L(0); PG8_MMA(1, 0, At, B0); PG8_BAR; PG8_SCHED;
.LBB0_1275:
	s_add_u32 s2, s6, 0xe767c080
	s_addc_u32 s3, s7, -1
	s_cmp_lg_u32 s23, 28
	s_cselect_b32 s8, s2, 0
	s_cselect_b32 s9, s3, 0
	s_add_u32 s2, s4, s8
	s_addc_u32 s3, s5, s9
	s_add_i32 s24, 0, 0x10000
	v_add_u32_e32 v152, s24, v138
	ds_read_b128 v[140:143], v152
	ds_read_b128 v[144:147], v152 offset:1024
	ds_read_b128 v[148:151], v152 offset:2048
	ds_read_b128 v[152:155], v152 offset:3072
	s_add_u32 s8, s0, s8
	s_addc_u32 s9, s1, s9
	v_lshl_add_u64 v[188:189], v[132:133], 0, s[6:7]
	s_add_i32 m0, s15, 0xc000
	ds_read_b128 v[156:159], v139
	ds_read_b128 v[160:163], v139 offset:1024
	ds_read_b128 v[164:167], v139 offset:2048
	ds_read_b128 v[168:171], v139 offset:3072
	ds_read_b128 v[172:175], v139 offset:4096
	ds_read_b128 v[176:179], v139 offset:5120
	ds_read_b128 v[180:183], v139 offset:6144
	ds_read_b128 v[184:187], v139 offset:7168
	global_load_lds_dwordx4 v[188:189], off
	v_lshl_add_u64 v[188:189], v[134:135], 0, s[6:7]
	s_add_i32 m0, s15, 0xe000
	s_nop 0
	global_load_lds_dwordx4 v[188:189], off
	s_waitcnt lgkmcnt(0)
	s_barrier
	v_mfma_f32_16x16x32_bf16 v[126:129], v[140:143], v[156:159], v[126:129]
	v_mfma_f32_16x16x32_bf16 v[122:125], v[148:151], v[156:159], v[122:125]
	v_mfma_f32_16x16x32_bf16 v[110:113], v[140:143], v[164:167], v[110:113]
	v_mfma_f32_16x16x32_bf16 v[106:109], v[148:151], v[164:167], v[106:109]
	v_mfma_f32_16x16x32_bf16 v[94:97], v[140:143], v[172:175], v[94:97]
	v_mfma_f32_16x16x32_bf16 v[90:93], v[148:151], v[172:175], v[90:93]
	v_mfma_f32_16x16x32_bf16 v[78:81], v[140:143], v[180:183], v[78:81]
	v_mfma_f32_16x16x32_bf16 v[74:77], v[148:151], v[180:183], v[74:77]
	v_mfma_f32_16x16x32_bf16 v[126:129], v[144:147], v[160:163], v[126:129]
	v_mfma_f32_16x16x32_bf16 v[122:125], v[152:155], v[160:163], v[122:125]
	v_mfma_f32_16x16x32_bf16 v[110:113], v[144:147], v[168:171], v[110:113]
	v_mfma_f32_16x16x32_bf16 v[106:109], v[152:155], v[168:171], v[106:109]
	v_mfma_f32_16x16x32_bf16 v[94:97], v[144:147], v[176:179], v[94:97]
	v_mfma_f32_16x16x32_bf16 v[90:93], v[152:155], v[176:179], v[90:93]
	v_mfma_f32_16x16x32_bf16 v[78:81], v[144:147], v[184:187], v[78:81]
	v_mfma_f32_16x16x32_bf16 v[74:77], v[152:155], v[184:187], v[74:77]
	s_barrier
	s_add_i32 s26, 0, 0x14000
	s_add_i32 s24, s24, s14
	v_add_u32_e32 v208, s26, v138
	v_lshl_add_u64 v[224:225], s[8:9], 0, v[64:65]
	s_mov_b32 m0, s24
	ds_read_b128 v[188:191], v208
	ds_read_b128 v[192:195], v208 offset:1024
	ds_read_b128 v[196:199], v208 offset:2048
	ds_read_b128 v[220:223], v208 offset:3072
	global_load_lds_dwordx4 v[224:225], off
	v_lshl_add_u64 v[226:227], s[8:9], 0, v[130:131]
	s_add_i32 m0, s24, 0x2000
	s_nop 0
	global_load_lds_dwordx4 v[226:227], off
	s_waitcnt lgkmcnt(0)
	s_barrier
	v_mfma_f32_16x16x32_bf16 v[118:121], v[188:191], v[156:159], v[118:121]
	v_mfma_f32_16x16x32_bf16 v[114:117], v[196:199], v[156:159], v[114:117]
	v_mfma_f32_16x16x32_bf16 v[102:105], v[188:191], v[164:167], v[102:105]
	v_mfma_f32_16x16x32_bf16 v[98:101], v[196:199], v[164:167], v[98:101]
	v_mfma_f32_16x16x32_bf16 v[86:89], v[188:191], v[172:175], v[86:89]
	v_mfma_f32_16x16x32_bf16 v[82:85], v[196:199], v[172:175], v[82:85]
	v_mfma_f32_16x16x32_bf16 v[70:73], v[188:191], v[180:183], v[70:73]
	v_mfma_f32_16x16x32_bf16 v[66:69], v[196:199], v[180:183], v[66:69]
	v_mfma_f32_16x16x32_bf16 v[118:121], v[192:195], v[160:163], v[118:121]
	v_mfma_f32_16x16x32_bf16 v[114:117], v[220:223], v[160:163], v[114:117]
	v_mfma_f32_16x16x32_bf16 v[102:105], v[192:195], v[168:171], v[102:105]
	v_mfma_f32_16x16x32_bf16 v[98:101], v[220:223], v[168:171], v[98:101]
	v_mfma_f32_16x16x32_bf16 v[86:89], v[192:195], v[176:179], v[86:89]
	v_mfma_f32_16x16x32_bf16 v[82:85], v[220:223], v[176:179], v[82:85]
	v_mfma_f32_16x16x32_bf16 v[70:73], v[192:195], v[184:187], v[70:73]
	v_mfma_f32_16x16x32_bf16 v[66:69], v[220:223], v[184:187], v[66:69]
	s_mov_b32 m0, s15
	v_lshl_add_u64 v[228:229], s[2:3], 0, v[64:65]
	s_barrier
	ds_read_b128 v[156:159], v139 offset:16384
	ds_read_b128 v[160:163], v139 offset:17408
	ds_read_b128 v[164:167], v139 offset:18432
	ds_read_b128 v[168:171], v139 offset:19456
	ds_read_b128 v[172:175], v139 offset:20480
	ds_read_b128 v[176:179], v139 offset:21504
	ds_read_b128 v[180:183], v139 offset:22528
	ds_read_b128 v[184:187], v139 offset:23552
	global_load_lds_dwordx4 v[228:229], off
	v_lshl_add_u64 v[230:231], s[2:3], 0, v[130:131]
	s_mov_b32 m0, s18
	s_nop 0
	global_load_lds_dwordx4 v[230:231], off
	s_waitcnt lgkmcnt(0)
	s_barrier
	v_mfma_f32_16x16x32_bf16 v[60:63], v[140:143], v[156:159], v[60:63]
	v_mfma_f32_16x16x32_bf16 v[56:59], v[148:151], v[156:159], v[56:59]
	v_mfma_f32_16x16x32_bf16 v[44:47], v[140:143], v[164:167], v[44:47]
	v_mfma_f32_16x16x32_bf16 v[40:43], v[148:151], v[164:167], v[40:43]
	v_mfma_f32_16x16x32_bf16 v[28:31], v[140:143], v[172:175], v[28:31]
	v_mfma_f32_16x16x32_bf16 v[24:27], v[148:151], v[172:175], v[24:27]
	v_mfma_f32_16x16x32_bf16 v[12:15], v[140:143], v[180:183], v[12:15]
	v_mfma_f32_16x16x32_bf16 v[8:11], v[148:151], v[180:183], v[8:11]
	v_mfma_f32_16x16x32_bf16 v[60:63], v[144:147], v[160:163], v[60:63]
	v_mfma_f32_16x16x32_bf16 v[56:59], v[152:155], v[160:163], v[56:59]
	v_mfma_f32_16x16x32_bf16 v[44:47], v[144:147], v[168:171], v[44:47]
	v_mfma_f32_16x16x32_bf16 v[40:43], v[152:155], v[168:171], v[40:43]
	v_mfma_f32_16x16x32_bf16 v[28:31], v[144:147], v[176:179], v[28:31]
	v_mfma_f32_16x16x32_bf16 v[24:27], v[152:155], v[176:179], v[24:27]
	v_mfma_f32_16x16x32_bf16 v[12:15], v[144:147], v[184:187], v[12:15]
	v_mfma_f32_16x16x32_bf16 v[8:11], v[152:155], v[184:187], v[8:11]
	s_barrier
; #define PG8_STAGE(bufoff, gbase, voff) do { _Pragma("unroll") for (int _i = 0; _i < 2; ++_i) \
;         __builtin_amdgcn_global_load_lds((const unsigned*)((const char*)(gbase) + (voff)[_i]), (LAS unsigned*)(lds + (bufoff) + ldsw + _i * 8192), 16, 0, 0); } while (0)
; #define PG8_LDA(dst, b, h) do { _Pragma("unroll") for (int m = 0; m < 4; ++m) _Pragma("unroll") for (int k = 0; k < 2; ++k) dst[m][k] = *(const LAS bf16x8*)(lds + PG8_SA(b, h) + aoff + m * 2048 + k * 1024); } while (0)
; #define PG8_LDB(dst, b, h) do { _Pragma("unroll") for (int n = 0; n < 2; ++n) _Pragma("unroll") for (int k = 0; k < 2; ++k) dst[n][k] = *(const LAS bf16x8*)(lds + PG8_SB(b, h) + boff + n * 2048 + k * 1024); } while (0)
; #define PG8_MMA(ai, bj, At, Bt) do { __builtin_amdgcn_s_setprio(1); _Pragma("unroll") for (int m = 0; m < 4; ++m) _Pragma("unroll") for (int n = 0; n < 2; ++n) _Pragma("unroll") for (int k = 0; k < 2; ++k) \
;         acc[ai][bj][m][n] = __builtin_amdgcn_mfma_f32_16x16x32_bf16(Bt[n][k], At[m][k], acc[ai][bj][m][n], 0, 0, 0); __builtin_amdgcn_s_setprio(0); } while (0)
; #define PG8_WAIT_V(n) asm volatile("s_waitcnt vmcnt(" #n ")" ::: "memory")
; #define PG8_WAIT_L(n) asm volatile("s_waitcnt lgkmcnt(" #n ")" ::: "memory")
; #define PG8_BAR __builtin_amdgcn_s_barrier()
; #define PG8_SCHED __builtin_amdgcn_sched_barrier(0)
;     ...
;             PG8_STAGE(PG8_SB(0, 1), b2 + hstep, voffB);
;             PG8_WAIT_V(6); PG8_BAR; PG8_MMA(1, 1, At, B1); PG8_BAR;
;             PG8_LDB(B0, 1, 0); PG8_SCHED; PG8_LDA(At, 1, 0); PG8_STAGE(PG8_SA(0, 1), a2 + hstep, voffA);
;             PG8_WAIT_L(8); PG8_BAR; PG8_WAIT_L(0); PG8_MMA(0, 0, At, B0); PG8_BAR; PG8_SCHED;
;             PG8_LDB(B1, 1, 1); PG8_STAGE(PG8_SB(1, 0), b3, voffB);
;             PG8_BAR; PG8_WAIT_L(0); PG8_MMA(0, 1, At, B1); PG8_BAR;
;             PG8_LDA(At, 1, 1); PG8_STAGE(PG8_SA(1, 0), a3, voffA);
;             PG8_BAR; PG8_WAIT_L(0); PG8_MMA(1, 0, At, B0); PG8_BAR; PG8_SCHED;
	s_add_u32 s24, s8, 0x84000
	s_addc_u32 s25, s9, 0
	s_add_i32 s26, s26, s14
	v_lshl_add_u64 v[140:141], s[24:25], 0, v[64:65]
	s_mov_b32 m0, s26
	s_nop 0
	global_load_lds_dwordx4 v[140:141], off
	v_lshl_add_u64 v[140:141], s[24:25], 0, v[130:131]
	s_add_i32 m0, s26, 0x2000
	s_nop 0
	global_load_lds_dwordx4 v[140:141], off
	s_waitcnt vmcnt(6)
	s_barrier
	v_mfma_f32_16x16x32_bf16 v[52:55], v[188:191], v[156:159], v[52:55]
	v_mfma_f32_16x16x32_bf16 v[48:51], v[196:199], v[156:159], v[48:51]
	v_mfma_f32_16x16x32_bf16 v[36:39], v[188:191], v[164:167], v[36:39]
	v_mfma_f32_16x16x32_bf16 v[32:35], v[196:199], v[164:167], v[32:35]
	v_mfma_f32_16x16x32_bf16 v[20:23], v[188:191], v[172:175], v[20:23]
	v_mfma_f32_16x16x32_bf16 v[16:19], v[196:199], v[172:175], v[16:19]
	v_mfma_f32_16x16x32_bf16 v[4:7], v[188:191], v[180:183], v[4:7]
	v_mfma_f32_16x16x32_bf16 v[0:3], v[196:199], v[180:183], v[0:3]
	v_mfma_f32_16x16x32_bf16 v[52:55], v[192:195], v[160:163], v[52:55]
	v_mfma_f32_16x16x32_bf16 v[48:51], v[220:223], v[160:163], v[48:51]
	v_mfma_f32_16x16x32_bf16 v[36:39], v[192:195], v[168:171], v[36:39]
	v_mfma_f32_16x16x32_bf16 v[32:35], v[220:223], v[168:171], v[32:35]
	v_mfma_f32_16x16x32_bf16 v[20:23], v[192:195], v[176:179], v[20:23]
	v_mfma_f32_16x16x32_bf16 v[16:19], v[220:223], v[176:179], v[16:19]
	v_mfma_f32_16x16x32_bf16 v[4:7], v[192:195], v[184:187], v[4:7]
	v_mfma_f32_16x16x32_bf16 v[0:3], v[220:223], v[184:187], v[0:3]
	s_add_i32 s24, 0, 0x18000
	v_add_u32_e32 v152, s24, v138
	s_barrier
	ds_read_b128 v[140:143], v152
	ds_read_b128 v[144:147], v152 offset:1024
	ds_read_b128 v[148:151], v152 offset:2048
	ds_read_b128 v[152:155], v152 offset:3072
	s_add_u32 s2, s2, 0x84000
	s_addc_u32 s3, s3, 0
	s_mov_b32 m0, s19
	v_lshl_add_u64 v[188:189], s[2:3], 0, v[64:65]
	ds_read_b128 v[156:159], v139 offset:32768
	ds_read_b128 v[160:163], v139 offset:33792
	ds_read_b128 v[164:167], v139 offset:34816
	ds_read_b128 v[168:171], v139 offset:35840
	ds_read_b128 v[172:175], v139 offset:36864
	ds_read_b128 v[176:179], v139 offset:37888
	ds_read_b128 v[180:183], v139 offset:38912
	ds_read_b128 v[184:187], v139 offset:39936
	global_load_lds_dwordx4 v[188:189], off
	v_lshl_add_u64 v[188:189], s[2:3], 0, v[130:131]
	s_mov_b32 m0, s20
	s_nop 0
	global_load_lds_dwordx4 v[188:189], off
	s_waitcnt lgkmcnt(0)
	s_barrier
	v_mfma_f32_16x16x32_bf16 v[126:129], v[140:143], v[156:159], v[126:129]
	v_mfma_f32_16x16x32_bf16 v[122:125], v[148:151], v[156:159], v[122:125]
	v_mfma_f32_16x16x32_bf16 v[110:113], v[140:143], v[164:167], v[110:113]
	v_mfma_f32_16x16x32_bf16 v[106:109], v[148:151], v[164:167], v[106:109]
	v_mfma_f32_16x16x32_bf16 v[94:97], v[140:143], v[172:175], v[94:97]
	v_mfma_f32_16x16x32_bf16 v[90:93], v[148:151], v[172:175], v[90:93]
	v_mfma_f32_16x16x32_bf16 v[78:81], v[140:143], v[180:183], v[78:81]
	v_mfma_f32_16x16x32_bf16 v[74:77], v[148:151], v[180:183], v[74:77]
	v_mfma_f32_16x16x32_bf16 v[126:129], v[144:147], v[160:163], v[126:129]
	v_mfma_f32_16x16x32_bf16 v[122:125], v[152:155], v[160:163], v[122:125]
	v_mfma_f32_16x16x32_bf16 v[110:113], v[144:147], v[168:171], v[110:113]
	v_mfma_f32_16x16x32_bf16 v[106:109], v[152:155], v[168:171], v[106:109]
	v_mfma_f32_16x16x32_bf16 v[94:97], v[144:147], v[176:179], v[94:97]
	v_mfma_f32_16x16x32_bf16 v[90:93], v[152:155], v[176:179], v[90:93]
	v_mfma_f32_16x16x32_bf16 v[78:81], v[144:147], v[184:187], v[78:81]
	v_mfma_f32_16x16x32_bf16 v[74:77], v[152:155], v[184:187], v[74:77]
	s_barrier
	s_add_i32 s25, 0, 0x1c000
	s_add_i32 s2, s24, s14
	v_add_u32_e32 v208, s25, v138
	v_lshl_add_u64 v[224:225], v[224:225], 0, s[16:17]
	s_mov_b32 m0, s2
	ds_read_b128 v[188:191], v208
	ds_read_b128 v[192:195], v208 offset:1024
	ds_read_b128 v[196:199], v208 offset:2048
	ds_read_b128 v[220:223], v208 offset:3072
	global_load_lds_dwordx4 v[224:225], off
	v_lshl_add_u64 v[224:225], v[226:227], 0, s[16:17]
	s_add_i32 m0, s2, 0x2000
	s_nop 0
	global_load_lds_dwordx4 v[224:225], off
	s_waitcnt lgkmcnt(0)
	s_barrier
	v_mfma_f32_16x16x32_bf16 v[118:121], v[188:191], v[156:159], v[118:121]
	v_mfma_f32_16x16x32_bf16 v[114:117], v[196:199], v[156:159], v[114:117]
	v_mfma_f32_16x16x32_bf16 v[102:105], v[188:191], v[164:167], v[102:105]
	v_mfma_f32_16x16x32_bf16 v[98:101], v[196:199], v[164:167], v[98:101]
	v_mfma_f32_16x16x32_bf16 v[86:89], v[188:191], v[172:175], v[86:89]
	v_mfma_f32_16x16x32_bf16 v[82:85], v[196:199], v[172:175], v[82:85]
	v_mfma_f32_16x16x32_bf16 v[70:73], v[188:191], v[180:183], v[70:73]
	v_mfma_f32_16x16x32_bf16 v[66:69], v[196:199], v[180:183], v[66:69]
	v_mfma_f32_16x16x32_bf16 v[118:121], v[192:195], v[160:163], v[118:121]
	v_mfma_f32_16x16x32_bf16 v[114:117], v[220:223], v[160:163], v[114:117]
	v_mfma_f32_16x16x32_bf16 v[102:105], v[192:195], v[168:171], v[102:105]
	v_mfma_f32_16x16x32_bf16 v[98:101], v[220:223], v[168:171], v[98:101]
	v_mfma_f32_16x16x32_bf16 v[86:89], v[192:195], v[176:179], v[86:89]
	v_mfma_f32_16x16x32_bf16 v[82:85], v[220:223], v[176:179], v[82:85]
	v_mfma_f32_16x16x32_bf16 v[70:73], v[192:195], v[184:187], v[70:73]
	v_mfma_f32_16x16x32_bf16 v[66:69], v[220:223], v[184:187], v[66:69]
	s_mov_b32 m0, s21
	v_lshl_add_u64 v[224:225], v[228:229], 0, s[16:17]
	s_barrier
; #define PG8_STAGE(bufoff, gbase, voff) do { _Pragma("unroll") for (int _i = 0; _i < 2; ++_i) \
;         __builtin_amdgcn_global_load_lds((const unsigned*)((const char*)(gbase) + (voff)[_i]), (LAS unsigned*)(lds + (bufoff) + ldsw + _i * 8192), 16, 0, 0); } while (0)
; #define PG8_LDA(dst, b, h) do { _Pragma("unroll") for (int m = 0; m < 4; ++m) _Pragma("unroll") for (int k = 0; k < 2; ++k) dst[m][k] = *(const LAS bf16x8*)(lds + PG8_SA(b, h) + aoff + m * 2048 + k * 1024); } while (0)
; #define PG8_MMA(ai, bj, At, Bt) do { __builtin_amdgcn_s_setprio(1); _Pragma("unroll") for (int m = 0; m < 4; ++m) _Pragma("unroll") for (int n = 0; n < 2; ++n) _Pragma("unroll") for (int k = 0; k < 2; ++k) \
;         acc[ai][bj][m][n] = __builtin_amdgcn_mfma_f32_16x16x32_bf16(Bt[n][k], At[m][k], acc[ai][bj][m][n], 0, 0, 0); __builtin_amdgcn_s_setprio(0); } while (0)
; #define PG8_WAIT_V(n) asm volatile("s_waitcnt vmcnt(" #n ")" ::: "memory")
; #define PG8_WAIT_L(n) asm volatile("s_waitcnt lgkmcnt(" #n ")" ::: "memory")
; #define PG8_BAR __builtin_amdgcn_s_barrier()
; #define PG8_SCHED __builtin_amdgcn_sched_barrier(0)
; __device__ __forceinline__ f32x4 gelu4(const f32x4 x) {
;     const f32x4 t = x * x, a = x * (t * -0.10294324f + -2.3022082f);
;     f32x4 e; e[0] = __builtin_amdgcn_exp2f(a[0]); e[1] = __builtin_amdgcn_exp2f(a[1]); e[2] = __builtin_amdgcn_exp2f(a[2]); e[3] = __builtin_amdgcn_exp2f(a[3]);
;     const f32x4 d = e + 1.0f;
;     f32x4 r; r[0] = __builtin_amdgcn_rcpf(d[0]); r[1] = __builtin_amdgcn_rcpf(d[1]); r[2] = __builtin_amdgcn_rcpf(d[2]); r[3] = __builtin_amdgcn_rcpf(d[3]);
;     return x * r;
; }
;     ...
;             PG8_LDA(At, 1, 1); PG8_STAGE(PG8_SA(1, 0), a3, voffA);
;             PG8_BAR; PG8_WAIT_L(0); PG8_MMA(1, 0, At, B0); PG8_BAR; PG8_SCHED;
;             PG8_STAGE(PG8_SB(1, 1), b3 + hstep, voffB);
;             PG8_WAIT_V(6); PG8_BAR; PG8_MMA(1, 1, At, B1); PG8_BAR;
;         }
	ds_read_b128 v[156:159], v139 offset:49152
	ds_read_b128 v[160:163], v139 offset:50176
	ds_read_b128 v[164:167], v139 offset:51200
	ds_read_b128 v[168:171], v139 offset:52224
	ds_read_b128 v[172:175], v139 offset:53248
	ds_read_b128 v[176:179], v139 offset:54272
	ds_read_b128 v[180:183], v139 offset:55296
	ds_read_b128 v[184:187], v139 offset:56320
	global_load_lds_dwordx4 v[224:225], off
	v_lshl_add_u64 v[224:225], v[230:231], 0, s[16:17]
	s_mov_b32 m0, s22
	s_nop 0
	global_load_lds_dwordx4 v[224:225], off
	s_waitcnt lgkmcnt(0)
	s_barrier
	v_mfma_f32_16x16x32_bf16 v[60:63], v[140:143], v[156:159], v[60:63]
	v_mfma_f32_16x16x32_bf16 v[56:59], v[148:151], v[156:159], v[56:59]
	v_mfma_f32_16x16x32_bf16 v[44:47], v[140:143], v[164:167], v[44:47]
	v_mfma_f32_16x16x32_bf16 v[40:43], v[148:151], v[164:167], v[40:43]
	v_mfma_f32_16x16x32_bf16 v[28:31], v[140:143], v[172:175], v[28:31]
	v_mfma_f32_16x16x32_bf16 v[24:27], v[148:151], v[172:175], v[24:27]
	v_mfma_f32_16x16x32_bf16 v[12:15], v[140:143], v[180:183], v[12:15]
	v_mfma_f32_16x16x32_bf16 v[8:11], v[148:151], v[180:183], v[8:11]
	v_mfma_f32_16x16x32_bf16 v[60:63], v[144:147], v[160:163], v[60:63]
	v_mfma_f32_16x16x32_bf16 v[56:59], v[152:155], v[160:163], v[56:59]
	v_mfma_f32_16x16x32_bf16 v[44:47], v[144:147], v[168:171], v[44:47]
	v_mfma_f32_16x16x32_bf16 v[40:43], v[152:155], v[168:171], v[40:43]
	v_mfma_f32_16x16x32_bf16 v[28:31], v[144:147], v[176:179], v[28:31]
	v_mfma_f32_16x16x32_bf16 v[24:27], v[152:155], v[176:179], v[24:27]
	v_mfma_f32_16x16x32_bf16 v[12:15], v[144:147], v[184:187], v[12:15]
	v_mfma_f32_16x16x32_bf16 v[8:11], v[152:155], v[184:187], v[8:11]
	s_barrier
	s_add_u32 s2, s8, 0x84080
	s_addc_u32 s3, s9, 0
	s_add_i32 s8, s25, s14
	v_lshl_add_u64 v[140:141], s[2:3], 0, v[64:65]
	s_mov_b32 m0, s8
	s_nop 0
	global_load_lds_dwordx4 v[140:141], off
	v_lshl_add_u64 v[140:141], s[2:3], 0, v[130:131]
	s_add_i32 m0, s8, 0x2000
	s_nop 0
	global_load_lds_dwordx4 v[140:141], off
	s_waitcnt vmcnt(6)
	s_barrier
	v_mfma_f32_16x16x32_bf16 v[52:55], v[188:191], v[156:159], v[52:55]
	v_mfma_f32_16x16x32_bf16 v[48:51], v[196:199], v[156:159], v[48:51]
	v_mfma_f32_16x16x32_bf16 v[36:39], v[188:191], v[164:167], v[36:39]
	v_mfma_f32_16x16x32_bf16 v[32:35], v[196:199], v[164:167], v[32:35]
	v_mfma_f32_16x16x32_bf16 v[20:23], v[188:191], v[172:175], v[20:23]
	v_mfma_f32_16x16x32_bf16 v[16:19], v[196:199], v[172:175], v[16:19]
	v_mfma_f32_16x16x32_bf16 v[4:7], v[188:191], v[180:183], v[4:7]
	v_mfma_f32_16x16x32_bf16 v[0:3], v[196:199], v[180:183], v[0:3]
	v_mfma_f32_16x16x32_bf16 v[52:55], v[192:195], v[160:163], v[52:55]
	v_mfma_f32_16x16x32_bf16 v[48:51], v[220:223], v[160:163], v[48:51]
	v_mfma_f32_16x16x32_bf16 v[36:39], v[192:195], v[168:171], v[36:39]
	v_mfma_f32_16x16x32_bf16 v[32:35], v[220:223], v[168:171], v[32:35]
	v_mfma_f32_16x16x32_bf16 v[20:23], v[192:195], v[176:179], v[20:23]
	v_mfma_f32_16x16x32_bf16 v[16:19], v[220:223], v[176:179], v[16:19]
	v_mfma_f32_16x16x32_bf16 v[4:7], v[192:195], v[184:187], v[4:7]
	v_mfma_f32_16x16x32_bf16 v[0:3], v[220:223], v[184:187], v[0:3]
	s_add_i32 s23, s23, 2
	s_add_u32 s6, s6, 0x100
	s_addc_u32 s7, s7, 0
	s_cmp_gt_u32 s23, 29
	s_barrier
	s_cbranch_scc0 .LBB0_1275
	s_add_i32 s0, s11, -2
	s_cmp_lt_u32 s0, 8
	s_cselect_b64 s[2:3], -1, 0
	s_cmp_gt_u32 s0, 7
	s_cbranch_scc1 .LBB0_1278
	s_mov_b32 s0, 0xc0135761
	v_pk_mul_f32 v[130:131], v[128:129], v[128:129]
	v_pk_mul_f32 v[132:133], v[126:127], v[126:127]
	v_mov_b64_e32 v[134:135], s[0:1]
	s_mov_b32 s0, 0xbdd2d3e8
	v_pk_fma_f32 v[130:131], v[130:131], s[0:1], v[134:135] op_sel_hi:[1,0,0]
	v_pk_fma_f32 v[132:133], v[132:133], s[0:1], v[134:135] op_sel_hi:[1,0,0]
	v_pk_mul_f32 v[130:131], v[128:129], v[130:131]
	v_pk_mul_f32 v[132:133], v[126:127], v[132:133]
	v_exp_f32_e32 v130, v130
	v_exp_f32_e32 v132, v132
	v_exp_f32_e32 v131, v131
	v_exp_f32_e32 v133, v133
	v_pk_add_f32 v[130:131], v[130:131], 1.0 op_sel_hi:[1,0]
	v_pk_add_f32 v[132:133], v[132:133], 1.0 op_sel_hi:[1,0]
	v_rcp_f32_e32 v130, v130
	v_rcp_f32_e32 v132, v132
	v_rcp_f32_e32 v131, v131
	v_rcp_f32_e32 v133, v133
	v_pk_mul_f32 v[128:129], v[128:129], v[130:131]
	v_pk_mul_f32 v[126:127], v[126:127], v[132:133]

; #define PG8_STAGE(bufoff, gbase, voff) do { _Pragma("unroll") for (int _i = 0; _i < 2; ++_i) \
;         __builtin_amdgcn_global_load_lds((const unsigned*)((const char*)(gbase) + (voff)[_i]), (LAS unsigned*)(lds + (bufoff) + ldsw + _i * 8192), 16, 0, 0); } while (0)
; #define PG8_LDA(dst, b, h) do { _Pragma("unroll") for (int m = 0; m < 4; ++m) _Pragma("unroll") for (int k = 0; k < 2; ++k) dst[m][k] = *(const LAS bf16x8*)(lds + PG8_SA(b, h) + aoff + m * 2048 + k * 1024); } while (0)
; #define PG8_LDB(dst, b, h) do { _Pragma("unroll") for (int n = 0; n < 2; ++n) _Pragma("unroll") for (int k = 0; k < 2; ++k) dst[n][k] = *(const LAS bf16x8*)(lds + PG8_SB(b, h) + boff + n * 2048 + k * 1024); } while (0)
; #define PG8_MMA(ai, bj, At, Bt) do { __builtin_amdgcn_s_setprio(1); _Pragma("unroll") for (int m = 0; m < 4; ++m) _Pragma("unroll") for (int n = 0; n < 2; ++n) _Pragma("unroll") for (int k = 0; k < 2; ++k) \
;         acc[ai][bj][m][n] = __builtin_amdgcn_mfma_f32_16x16x32_bf16(Bt[n][k], At[m][k], acc[ai][bj][m][n], 0, 0, 0); __builtin_amdgcn_s_setprio(0); } while (0)
; #define PG8_WAIT_L(n) asm volatile("s_waitcnt lgkmcnt(" #n ")" ::: "memory")
; #define PG8_BAR __builtin_amdgcn_s_barrier()
; #define PG8_SCHED __builtin_amdgcn_sched_barrier(0)
;     ...
;             const char* a1 = cA + (size_t)(t + 1) * kstep;
;             const char* a2 = last ? nA : cA + (size_t)(t + 2) * kstep; const char* b2 = last ? nB : cB + (size_t)(t + 2) * kstep;
;             const char* a3 = a2 + kstep; const char* b3 = b2 + kstep;
;             PG8_LDB(B0, 0, 0); PG8_SCHED; PG8_LDA(At, 0, 0); PG8_STAGE(PG8_SA(1, 1), a1 + hstep, voffA);
;             PG8_WAIT_L(8); PG8_BAR; PG8_WAIT_L(0); PG8_MMA(0, 0, At, B0); PG8_BAR; PG8_SCHED;
;             PG8_LDB(B1, 0, 1); PG8_STAGE(PG8_SB(0, 0), b2, voffB);
;             PG8_BAR; PG8_WAIT_L(0); PG8_MMA(0, 1, At, B1); PG8_BAR;
;             PG8_LDA(At, 0, 1); PG8_STAGE(PG8_SA(0, 0), a2, voffA);
;             PG8_BAR; PG8_WAIT_L(0); PG8_MMA(1, 0, At, B0); PG8_BAR; PG8_SCHED;
.LBB0_1441:
	s_add_u32 s4, s0, 0x100
	s_addc_u32 s5, s1, 0
	s_add_i32 s43, 0, 0x10000
	v_add_u32_e32 v140, s43, v143
	ds_read_b128 v[136:139], v140
	ds_read_b128 v[146:149], v140 offset:1024
	ds_read_b128 v[150:153], v140 offset:2048
	ds_read_b128 v[154:157], v140 offset:3072
	s_cmp_eq_u32 s42, 28
	s_cselect_b32 s3, s21, s5
	s_cselect_b32 s2, s20, s4
	s_cselect_b32 s9, s23, s41
	s_cselect_b32 s8, s22, s40
	v_lshl_add_u64 v[140:141], s[0:1], 0, v[132:133]
	s_add_i32 m0, s12, 0xc000
	ds_read_b128 v[158:161], v145
	ds_read_b128 v[162:165], v145 offset:1024
	ds_read_b128 v[166:169], v145 offset:2048
	ds_read_b128 v[170:173], v145 offset:3072
	ds_read_b128 v[174:177], v145 offset:4096
	ds_read_b128 v[178:181], v145 offset:5120
	ds_read_b128 v[182:185], v145 offset:6144
	ds_read_b128 v[186:189], v145 offset:7168
	global_load_lds_dwordx4 v[140:141], off
	v_lshl_add_u64 v[140:141], s[0:1], 0, v[134:135]
	s_add_i32 m0, s12, 0xe000
	s_nop 0
	global_load_lds_dwordx4 v[140:141], off
	s_waitcnt lgkmcnt(0)
	s_barrier
	v_mfma_f32_16x16x32_bf16 v[126:129], v[136:139], v[158:161], v[126:129]
	v_mfma_f32_16x16x32_bf16 v[122:125], v[150:153], v[158:161], v[122:125]
	v_mfma_f32_16x16x32_bf16 v[110:113], v[136:139], v[166:169], v[110:113]
	v_mfma_f32_16x16x32_bf16 v[106:109], v[150:153], v[166:169], v[106:109]
	v_mfma_f32_16x16x32_bf16 v[94:97], v[136:139], v[174:177], v[94:97]
	v_mfma_f32_16x16x32_bf16 v[90:93], v[150:153], v[174:177], v[90:93]
	v_mfma_f32_16x16x32_bf16 v[78:81], v[136:139], v[182:185], v[78:81]
	v_mfma_f32_16x16x32_bf16 v[74:77], v[150:153], v[182:185], v[74:77]
	v_mfma_f32_16x16x32_bf16 v[126:129], v[146:149], v[162:165], v[126:129]
	v_mfma_f32_16x16x32_bf16 v[122:125], v[154:157], v[162:165], v[122:125]
	v_mfma_f32_16x16x32_bf16 v[110:113], v[146:149], v[170:173], v[110:113]
	v_mfma_f32_16x16x32_bf16 v[106:109], v[154:157], v[170:173], v[106:109]
	v_mfma_f32_16x16x32_bf16 v[94:97], v[146:149], v[178:181], v[94:97]
	v_mfma_f32_16x16x32_bf16 v[90:93], v[154:157], v[178:181], v[90:93]
	v_mfma_f32_16x16x32_bf16 v[78:81], v[146:149], v[186:189], v[78:81]
	v_mfma_f32_16x16x32_bf16 v[74:77], v[154:157], v[186:189], v[74:77]
	s_barrier
	s_add_i32 s44, 0, 0x14000
	v_add_u32_e32 v140, s44, v143
	s_add_i32 s0, s43, s11
	ds_read_b128 v[190:193], v140
	ds_read_b128 v[194:197], v140 offset:1024
	ds_read_b128 v[220:223], v140 offset:2048
	ds_read_b128 v[224:227], v140 offset:3072
	v_lshl_add_u64 v[140:141], s[8:9], 0, v[64:65]
	s_mov_b32 m0, s0
	v_lshl_add_u64 v[198:199], s[8:9], 0, v[130:131]
	global_load_lds_dwordx4 v[140:141], off
	s_add_i32 m0, s0, 0x2000
	s_nop 0
	global_load_lds_dwordx4 v[198:199], off
	s_waitcnt lgkmcnt(0)
	s_barrier
	v_mfma_f32_16x16x32_bf16 v[118:121], v[190:193], v[158:161], v[118:121]
	v_mfma_f32_16x16x32_bf16 v[114:117], v[220:223], v[158:161], v[114:117]
	v_mfma_f32_16x16x32_bf16 v[102:105], v[190:193], v[166:169], v[102:105]
	v_mfma_f32_16x16x32_bf16 v[98:101], v[220:223], v[166:169], v[98:101]
	v_mfma_f32_16x16x32_bf16 v[86:89], v[190:193], v[174:177], v[86:89]
	v_mfma_f32_16x16x32_bf16 v[82:85], v[220:223], v[174:177], v[82:85]
	v_mfma_f32_16x16x32_bf16 v[70:73], v[190:193], v[182:185], v[70:73]
	v_mfma_f32_16x16x32_bf16 v[66:69], v[220:223], v[182:185], v[66:69]
	v_mfma_f32_16x16x32_bf16 v[118:121], v[194:197], v[162:165], v[118:121]
	v_mfma_f32_16x16x32_bf16 v[114:117], v[224:227], v[162:165], v[114:117]
	v_mfma_f32_16x16x32_bf16 v[102:105], v[194:197], v[170:173], v[102:105]
	v_mfma_f32_16x16x32_bf16 v[98:101], v[224:227], v[170:173], v[98:101]
	v_mfma_f32_16x16x32_bf16 v[86:89], v[194:197], v[178:181], v[86:89]
	v_mfma_f32_16x16x32_bf16 v[82:85], v[224:227], v[178:181], v[82:85]
	v_mfma_f32_16x16x32_bf16 v[70:73], v[194:197], v[186:189], v[70:73]
	v_mfma_f32_16x16x32_bf16 v[66:69], v[224:227], v[186:189], v[66:69]
	s_mov_b32 m0, s12
	v_lshl_add_u64 v[228:229], s[2:3], 0, v[64:65]
	s_barrier
	ds_read_b128 v[158:161], v145 offset:16384
	ds_read_b128 v[162:165], v145 offset:17408
	ds_read_b128 v[166:169], v145 offset:18432
	ds_read_b128 v[170:173], v145 offset:19456
	ds_read_b128 v[174:177], v145 offset:20480
	ds_read_b128 v[178:181], v145 offset:21504
	ds_read_b128 v[182:185], v145 offset:22528
	ds_read_b128 v[186:189], v145 offset:23552
	global_load_lds_dwordx4 v[228:229], off
	v_lshl_add_u64 v[230:231], s[2:3], 0, v[130:131]
	s_mov_b32 m0, s13
	s_nop 0
	global_load_lds_dwordx4 v[230:231], off
	s_waitcnt lgkmcnt(0)
	s_barrier
	v_mfma_f32_16x16x32_bf16 v[60:63], v[136:139], v[158:161], v[60:63]
	v_mfma_f32_16x16x32_bf16 v[56:59], v[150:153], v[158:161], v[56:59]
	v_mfma_f32_16x16x32_bf16 v[44:47], v[136:139], v[166:169], v[44:47]
	v_mfma_f32_16x16x32_bf16 v[40:43], v[150:153], v[166:169], v[40:43]
	v_mfma_f32_16x16x32_bf16 v[28:31], v[136:139], v[174:177], v[28:31]
	v_mfma_f32_16x16x32_bf16 v[24:27], v[150:153], v[174:177], v[24:27]
	v_mfma_f32_16x16x32_bf16 v[12:15], v[136:139], v[182:185], v[12:15]
	v_mfma_f32_16x16x32_bf16 v[8:11], v[150:153], v[182:185], v[8:11]
	v_mfma_f32_16x16x32_bf16 v[60:63], v[146:149], v[162:165], v[60:63]
	v_mfma_f32_16x16x32_bf16 v[56:59], v[154:157], v[162:165], v[56:59]
	v_mfma_f32_16x16x32_bf16 v[44:47], v[146:149], v[170:173], v[44:47]
	v_mfma_f32_16x16x32_bf16 v[40:43], v[154:157], v[170:173], v[40:43]
	v_mfma_f32_16x16x32_bf16 v[28:31], v[146:149], v[178:181], v[28:31]
	v_mfma_f32_16x16x32_bf16 v[24:27], v[154:157], v[178:181], v[24:27]
	v_mfma_f32_16x16x32_bf16 v[12:15], v[146:149], v[186:189], v[12:15]
	v_mfma_f32_16x16x32_bf16 v[8:11], v[154:157], v[186:189], v[8:11]
	s_barrier
; #define PG8_STAGE(bufoff, gbase, voff) do { _Pragma("unroll") for (int _i = 0; _i < 2; ++_i) \
;         __builtin_amdgcn_global_load_lds((const unsigned*)((const char*)(gbase) + (voff)[_i]), (LAS unsigned*)(lds + (bufoff) + ldsw + _i * 8192), 16, 0, 0); } while (0)
; #define PG8_LDA(dst, b, h) do { _Pragma("unroll") for (int m = 0; m < 4; ++m) _Pragma("unroll") for (int k = 0; k < 2; ++k) dst[m][k] = *(const LAS bf16x8*)(lds + PG8_SA(b, h) + aoff + m * 2048 + k * 1024); } while (0)
; #define PG8_LDB(dst, b, h) do { _Pragma("unroll") for (int n = 0; n < 2; ++n) _Pragma("unroll") for (int k = 0; k < 2; ++k) dst[n][k] = *(const LAS bf16x8*)(lds + PG8_SB(b, h) + boff + n * 2048 + k * 1024); } while (0)
; #define PG8_MMA(ai, bj, At, Bt) do { __builtin_amdgcn_s_setprio(1); _Pragma("unroll") for (int m = 0; m < 4; ++m) _Pragma("unroll") for (int n = 0; n < 2; ++n) _Pragma("unroll") for (int k = 0; k < 2; ++k) \
;         acc[ai][bj][m][n] = __builtin_amdgcn_mfma_f32_16x16x32_bf16(Bt[n][k], At[m][k], acc[ai][bj][m][n], 0, 0, 0); __builtin_amdgcn_s_setprio(0); } while (0)
; #define PG8_WAIT_V(n) asm volatile("s_waitcnt vmcnt(" #n ")" ::: "memory")
; #define PG8_WAIT_L(n) asm volatile("s_waitcnt lgkmcnt(" #n ")" ::: "memory")
; #define PG8_BAR __builtin_amdgcn_s_barrier()
; #define PG8_SCHED __builtin_amdgcn_sched_barrier(0)
;     ...
;             PG8_STAGE(PG8_SB(0, 1), b2 + hstep, voffB);
;             PG8_WAIT_V(6); PG8_BAR; PG8_MMA(1, 1, At, B1); PG8_BAR;
;             PG8_LDB(B0, 1, 0); PG8_SCHED; PG8_LDA(At, 1, 0); PG8_STAGE(PG8_SA(0, 1), a2 + hstep, voffA);
;             PG8_WAIT_L(8); PG8_BAR; PG8_WAIT_L(0); PG8_MMA(0, 0, At, B0); PG8_BAR; PG8_SCHED;
;             PG8_LDB(B1, 1, 1); PG8_STAGE(PG8_SB(1, 0), b3, voffB);
;             PG8_BAR; PG8_WAIT_L(0); PG8_MMA(0, 1, At, B1); PG8_BAR;
;             PG8_LDA(At, 1, 1); PG8_STAGE(PG8_SA(1, 0), a3, voffA);
	s_add_u32 s0, s8, 0x84000
	s_addc_u32 s1, s9, 0
	s_add_i32 s43, s44, s11
	v_lshl_add_u64 v[136:137], s[0:1], 0, v[64:65]
	s_mov_b32 m0, s43
	s_nop 0
	global_load_lds_dwordx4 v[136:137], off
	v_lshl_add_u64 v[136:137], s[0:1], 0, v[130:131]
	s_add_i32 m0, s43, 0x2000
	s_nop 0
	global_load_lds_dwordx4 v[136:137], off
	s_waitcnt vmcnt(6)
	s_barrier
	v_mfma_f32_16x16x32_bf16 v[52:55], v[190:193], v[158:161], v[52:55]
	v_mfma_f32_16x16x32_bf16 v[48:51], v[220:223], v[158:161], v[48:51]
	v_mfma_f32_16x16x32_bf16 v[36:39], v[190:193], v[166:169], v[36:39]
	v_mfma_f32_16x16x32_bf16 v[32:35], v[220:223], v[166:169], v[32:35]
	v_mfma_f32_16x16x32_bf16 v[20:23], v[190:193], v[174:177], v[20:23]
	v_mfma_f32_16x16x32_bf16 v[16:19], v[220:223], v[174:177], v[16:19]
	v_mfma_f32_16x16x32_bf16 v[4:7], v[190:193], v[182:185], v[4:7]
	v_mfma_f32_16x16x32_bf16 v[0:3], v[220:223], v[182:185], v[0:3]
	v_mfma_f32_16x16x32_bf16 v[52:55], v[194:197], v[162:165], v[52:55]
	v_mfma_f32_16x16x32_bf16 v[48:51], v[224:227], v[162:165], v[48:51]
	v_mfma_f32_16x16x32_bf16 v[36:39], v[194:197], v[170:173], v[36:39]
	v_mfma_f32_16x16x32_bf16 v[32:35], v[224:227], v[170:173], v[32:35]
	v_mfma_f32_16x16x32_bf16 v[20:23], v[194:197], v[178:181], v[20:23]
	v_mfma_f32_16x16x32_bf16 v[16:19], v[224:227], v[178:181], v[16:19]
	v_mfma_f32_16x16x32_bf16 v[4:7], v[194:197], v[186:189], v[4:7]
	v_mfma_f32_16x16x32_bf16 v[0:3], v[224:227], v[186:189], v[0:3]
	s_add_i32 s43, 0, 0x18000
	v_add_u32_e32 v154, s43, v143
	s_barrier
	ds_read_b128 v[136:139], v154
	ds_read_b128 v[146:149], v154 offset:1024
	ds_read_b128 v[150:153], v154 offset:2048
	ds_read_b128 v[154:157], v154 offset:3072
	s_add_u32 s0, s2, 0x84000
	s_addc_u32 s1, s3, 0
	s_mov_b32 m0, s14
	v_lshl_add_u64 v[190:191], s[0:1], 0, v[64:65]
	ds_read_b128 v[158:161], v145 offset:32768
	ds_read_b128 v[162:165], v145 offset:33792
	ds_read_b128 v[166:169], v145 offset:34816
	ds_read_b128 v[170:173], v145 offset:35840
	ds_read_b128 v[174:177], v145 offset:36864
	ds_read_b128 v[178:181], v145 offset:37888
	ds_read_b128 v[182:185], v145 offset:38912
	ds_read_b128 v[186:189], v145 offset:39936
	global_load_lds_dwordx4 v[190:191], off
	v_lshl_add_u64 v[190:191], s[0:1], 0, v[130:131]
	s_mov_b32 m0, s15
	s_nop 0
	global_load_lds_dwordx4 v[190:191], off
	s_waitcnt lgkmcnt(0)
	s_barrier
	v_mfma_f32_16x16x32_bf16 v[126:129], v[136:139], v[158:161], v[126:129]
	v_mfma_f32_16x16x32_bf16 v[122:125], v[150:153], v[158:161], v[122:125]
	v_mfma_f32_16x16x32_bf16 v[110:113], v[136:139], v[166:169], v[110:113]
	v_mfma_f32_16x16x32_bf16 v[106:109], v[150:153], v[166:169], v[106:109]
	v_mfma_f32_16x16x32_bf16 v[94:97], v[136:139], v[174:177], v[94:97]
	v_mfma_f32_16x16x32_bf16 v[90:93], v[150:153], v[174:177], v[90:93]
	v_mfma_f32_16x16x32_bf16 v[78:81], v[136:139], v[182:185], v[78:81]
	v_mfma_f32_16x16x32_bf16 v[74:77], v[150:153], v[182:185], v[74:77]
	v_mfma_f32_16x16x32_bf16 v[126:129], v[146:149], v[162:165], v[126:129]
	v_mfma_f32_16x16x32_bf16 v[122:125], v[154:157], v[162:165], v[122:125]
	v_mfma_f32_16x16x32_bf16 v[110:113], v[146:149], v[170:173], v[110:113]
	v_mfma_f32_16x16x32_bf16 v[106:109], v[154:157], v[170:173], v[106:109]
	v_mfma_f32_16x16x32_bf16 v[94:97], v[146:149], v[178:181], v[94:97]
	v_mfma_f32_16x16x32_bf16 v[90:93], v[154:157], v[178:181], v[90:93]
	v_mfma_f32_16x16x32_bf16 v[78:81], v[146:149], v[186:189], v[78:81]
	v_mfma_f32_16x16x32_bf16 v[74:77], v[154:157], v[186:189], v[74:77]
	s_barrier
	s_add_i32 s2, 0, 0x1c000
	s_add_i32 s0, s43, s11
	v_add_u32_e32 v208, s2, v143
	v_lshl_add_u64 v[140:141], v[140:141], 0, s[16:17]
	s_mov_b32 m0, s0
	ds_read_b128 v[190:193], v208
	ds_read_b128 v[194:197], v208 offset:1024
	ds_read_b128 v[220:223], v208 offset:2048
	ds_read_b128 v[224:227], v208 offset:3072
	global_load_lds_dwordx4 v[140:141], off
	v_lshl_add_u64 v[140:141], v[198:199], 0, s[16:17]
	s_add_i32 m0, s0, 0x2000
	s_nop 0
	global_load_lds_dwordx4 v[140:141], off
	s_waitcnt lgkmcnt(0)
	s_barrier
	v_mfma_f32_16x16x32_bf16 v[118:121], v[190:193], v[158:161], v[118:121]
	v_mfma_f32_16x16x32_bf16 v[114:117], v[220:223], v[158:161], v[114:117]
	v_mfma_f32_16x16x32_bf16 v[102:105], v[190:193], v[166:169], v[102:105]
	v_mfma_f32_16x16x32_bf16 v[98:101], v[220:223], v[166:169], v[98:101]
	v_mfma_f32_16x16x32_bf16 v[86:89], v[190:193], v[174:177], v[86:89]
	v_mfma_f32_16x16x32_bf16 v[82:85], v[220:223], v[174:177], v[82:85]
	v_mfma_f32_16x16x32_bf16 v[70:73], v[190:193], v[182:185], v[70:73]
	v_mfma_f32_16x16x32_bf16 v[66:69], v[220:223], v[182:185], v[66:69]
	v_mfma_f32_16x16x32_bf16 v[118:121], v[194:197], v[162:165], v[118:121]
	v_mfma_f32_16x16x32_bf16 v[114:117], v[224:227], v[162:165], v[114:117]
	v_mfma_f32_16x16x32_bf16 v[102:105], v[194:197], v[170:173], v[102:105]
	v_mfma_f32_16x16x32_bf16 v[98:101], v[224:227], v[170:173], v[98:101]
	v_mfma_f32_16x16x32_bf16 v[86:89], v[194:197], v[178:181], v[86:89]
	v_mfma_f32_16x16x32_bf16 v[82:85], v[224:227], v[178:181], v[82:85]
	v_mfma_f32_16x16x32_bf16 v[70:73], v[194:197], v[186:189], v[70:73]
	v_mfma_f32_16x16x32_bf16 v[66:69], v[224:227], v[186:189], v[66:69]
	s_mov_b32 m0, s24
	v_lshl_add_u64 v[140:141], v[228:229], 0, s[16:17]
	s_barrier
; #define PG8_STAGE(bufoff, gbase, voff) do { _Pragma("unroll") for (int _i = 0; _i < 2; ++_i) \
;         __builtin_amdgcn_global_load_lds((const unsigned*)((const char*)(gbase) + (voff)[_i]), (LAS unsigned*)(lds + (bufoff) + ldsw + _i * 8192), 16, 0, 0); } while (0)
; #define PG8_LDA(dst, b, h) do { _Pragma("unroll") for (int m = 0; m < 4; ++m) _Pragma("unroll") for (int k = 0; k < 2; ++k) dst[m][k] = *(const LAS bf16x8*)(lds + PG8_SA(b, h) + aoff + m * 2048 + k * 1024); } while (0)
; #define PG8_MMA(ai, bj, At, Bt) do { __builtin_amdgcn_s_setprio(1); _Pragma("unroll") for (int m = 0; m < 4; ++m) _Pragma("unroll") for (int n = 0; n < 2; ++n) _Pragma("unroll") for (int k = 0; k < 2; ++k) \
;         acc[ai][bj][m][n] = __builtin_amdgcn_mfma_f32_16x16x32_bf16(Bt[n][k], At[m][k], acc[ai][bj][m][n], 0, 0, 0); __builtin_amdgcn_s_setprio(0); } while (0)
; #define PG8_WAIT_V(n) asm volatile("s_waitcnt vmcnt(" #n ")" ::: "memory")
; #define PG8_WAIT_L(n) asm volatile("s_waitcnt lgkmcnt(" #n ")" ::: "memory")
; #define PG8_BAR __builtin_amdgcn_s_barrier()
; #define PG8_SCHED __builtin_amdgcn_sched_barrier(0)
; __device__ __forceinline__ f32x4 gelu4(const f32x4 x) {
;     const f32x4 t = x * x, a = x * (t * -0.10294324f + -2.3022082f);
;     f32x4 e; e[0] = __builtin_amdgcn_exp2f(a[0]); e[1] = __builtin_amdgcn_exp2f(a[1]); e[2] = __builtin_amdgcn_exp2f(a[2]); e[3] = __builtin_amdgcn_exp2f(a[3]);
;     const f32x4 d = e + 1.0f;
;     f32x4 r; r[0] = __builtin_amdgcn_rcpf(d[0]); r[1] = __builtin_amdgcn_rcpf(d[1]); r[2] = __builtin_amdgcn_rcpf(d[2]); r[3] = __builtin_amdgcn_rcpf(d[3]);
;     return x * r;
; }
;     ...
;             PG8_LDA(At, 1, 1); PG8_STAGE(PG8_SA(1, 0), a3, voffA);
;             PG8_BAR; PG8_WAIT_L(0); PG8_MMA(1, 0, At, B0); PG8_BAR; PG8_SCHED;
;             PG8_STAGE(PG8_SB(1, 1), b3 + hstep, voffB);
;             PG8_WAIT_V(6); PG8_BAR; PG8_MMA(1, 1, At, B1); PG8_BAR;
;         }
	ds_read_b128 v[158:161], v145 offset:49152
	ds_read_b128 v[162:165], v145 offset:50176
	ds_read_b128 v[166:169], v145 offset:51200
	ds_read_b128 v[170:173], v145 offset:52224
	ds_read_b128 v[174:177], v145 offset:53248
	ds_read_b128 v[178:181], v145 offset:54272
	ds_read_b128 v[182:185], v145 offset:55296
	ds_read_b128 v[186:189], v145 offset:56320
	global_load_lds_dwordx4 v[140:141], off
	v_lshl_add_u64 v[140:141], v[230:231], 0, s[16:17]
	s_mov_b32 m0, s25
	s_nop 0
	global_load_lds_dwordx4 v[140:141], off
	s_waitcnt lgkmcnt(0)
	s_barrier
	v_mfma_f32_16x16x32_bf16 v[60:63], v[136:139], v[158:161], v[60:63]
	v_mfma_f32_16x16x32_bf16 v[56:59], v[150:153], v[158:161], v[56:59]
	v_mfma_f32_16x16x32_bf16 v[44:47], v[136:139], v[166:169], v[44:47]
	v_mfma_f32_16x16x32_bf16 v[40:43], v[150:153], v[166:169], v[40:43]
	v_mfma_f32_16x16x32_bf16 v[28:31], v[136:139], v[174:177], v[28:31]
	v_mfma_f32_16x16x32_bf16 v[24:27], v[150:153], v[174:177], v[24:27]
	v_mfma_f32_16x16x32_bf16 v[12:15], v[136:139], v[182:185], v[12:15]
	v_mfma_f32_16x16x32_bf16 v[8:11], v[150:153], v[182:185], v[8:11]
	v_mfma_f32_16x16x32_bf16 v[60:63], v[146:149], v[162:165], v[60:63]
	v_mfma_f32_16x16x32_bf16 v[56:59], v[154:157], v[162:165], v[56:59]
	v_mfma_f32_16x16x32_bf16 v[44:47], v[146:149], v[170:173], v[44:47]
	v_mfma_f32_16x16x32_bf16 v[40:43], v[154:157], v[170:173], v[40:43]
	v_mfma_f32_16x16x32_bf16 v[28:31], v[146:149], v[178:181], v[28:31]
	v_mfma_f32_16x16x32_bf16 v[24:27], v[154:157], v[178:181], v[24:27]
	v_mfma_f32_16x16x32_bf16 v[12:15], v[146:149], v[186:189], v[12:15]
	v_mfma_f32_16x16x32_bf16 v[8:11], v[154:157], v[186:189], v[8:11]
	s_barrier
	s_add_u32 s0, s8, 0x84080
	s_addc_u32 s1, s9, 0
	s_add_i32 s2, s2, s11
	v_lshl_add_u64 v[136:137], s[0:1], 0, v[64:65]
	s_mov_b32 m0, s2
	s_nop 0
	global_load_lds_dwordx4 v[136:137], off
	v_lshl_add_u64 v[136:137], s[0:1], 0, v[130:131]
	s_add_i32 m0, s2, 0x2000
	s_nop 0
	global_load_lds_dwordx4 v[136:137], off
	s_waitcnt vmcnt(6)
	s_barrier
	v_mfma_f32_16x16x32_bf16 v[52:55], v[190:193], v[158:161], v[52:55]
	v_mfma_f32_16x16x32_bf16 v[48:51], v[220:223], v[158:161], v[48:51]
	v_mfma_f32_16x16x32_bf16 v[36:39], v[190:193], v[166:169], v[36:39]
	v_mfma_f32_16x16x32_bf16 v[32:35], v[220:223], v[166:169], v[32:35]
	v_mfma_f32_16x16x32_bf16 v[20:23], v[190:193], v[174:177], v[20:23]
	v_mfma_f32_16x16x32_bf16 v[16:19], v[220:223], v[174:177], v[16:19]
	v_mfma_f32_16x16x32_bf16 v[4:7], v[190:193], v[182:185], v[4:7]
	v_mfma_f32_16x16x32_bf16 v[0:3], v[220:223], v[182:185], v[0:3]
	v_mfma_f32_16x16x32_bf16 v[52:55], v[194:197], v[162:165], v[52:55]
	v_mfma_f32_16x16x32_bf16 v[48:51], v[224:227], v[162:165], v[48:51]
	v_mfma_f32_16x16x32_bf16 v[36:39], v[194:197], v[170:173], v[36:39]
	v_mfma_f32_16x16x32_bf16 v[32:35], v[224:227], v[170:173], v[32:35]
	v_mfma_f32_16x16x32_bf16 v[20:23], v[194:197], v[178:181], v[20:23]
	v_mfma_f32_16x16x32_bf16 v[16:19], v[224:227], v[178:181], v[16:19]
	v_mfma_f32_16x16x32_bf16 v[4:7], v[194:197], v[186:189], v[4:7]
	v_mfma_f32_16x16x32_bf16 v[0:3], v[224:227], v[186:189], v[0:3]
	s_add_i32 s42, s42, 2
	s_add_u32 s40, s40, 0x100
	s_addc_u32 s41, s41, 0
	s_cmp_gt_u32 s42, 29
	s_mov_b64 s[0:1], s[4:5]
	s_barrier
	s_cbranch_scc0 .LBB0_1441
	s_add_i32 s0, s38, -2
	s_cmp_lt_u32 s0, 8
	s_cselect_b64 s[2:3], -1, 0
	s_cmp_gt_u32 s0, 7
	s_cbranch_scc1 .LBB0_1444
	s_mov_b32 s40, 0xc0135761
	v_pk_mul_f32 v[136:137], v[128:129], v[128:129]
	v_pk_mul_f32 v[138:139], v[126:127], v[126:127]
	v_mov_b64_e32 v[140:141], s[40:41]
	s_mov_b32 s0, 0xbdd2d3e8
	v_pk_fma_f32 v[136:137], v[136:137], s[0:1], v[140:141] op_sel_hi:[1,0,0]
	v_pk_fma_f32 v[138:139], v[138:139], s[0:1], v[140:141] op_sel_hi:[1,0,0]
	v_pk_mul_f32 v[136:137], v[128:129], v[136:137]
	v_pk_mul_f32 v[138:139], v[126:127], v[138:139]
	v_exp_f32_e32 v136, v136
	v_exp_f32_e32 v138, v138
	v_exp_f32_e32 v137, v137
	v_exp_f32_e32 v139, v139
	v_pk_add_f32 v[136:137], v[136:137], 1.0 op_sel_hi:[1,0]
	v_pk_add_f32 v[138:139], v[138:139], 1.0 op_sel_hi:[1,0]
	v_rcp_f32_e32 v136, v136
	v_rcp_f32_e32 v138, v138
	v_rcp_f32_e32 v137, v137
	v_rcp_f32_e32 v139, v139
	v_pk_mul_f32 v[128:129], v[128:129], v[136:137]
	v_pk_mul_f32 v[126:127], v[126:127], v[138:139]
	s_branch .LBB0_1445
